# flat TOPGEN polling for all blocks + E1 gelu epilogue with packed f32 VALU (v_pk_fma/mul/add_f32, constants duplicated in both halves, no op_sel)
# speedup vs baseline: 1.0390x; 1.0105x over previous
; template <int MT, class Epi>
; DI void gemm_tile(const u16* __restrict__ X, long ldx, const u16* __restrict__ W, long ldw, int K, char* smem,
;                   int m0, int n0, const Epi& epi, bool pre = false, const u16* Xn = nullptr, const u16* Wn = nullptr) {
;     ...
;   do {
;     asm volatile("s_waitcnt vmcnt(0)" ::: "memory");
;     __syncthreads();
;     if (kt + 1 < nk) GT_DMA((unsigned)((kt + 1) & 1) * 32768u)
;     else if (Xn != nullptr) { xe = Xn + oxe; xo = Xn + oxo; we = Wn + owe; wo = Wn + owo; GT_DMA(0u) }
;     const char* cur = smem + (kt & 1) * 32768;
; #pragma unroll
;     for (int ks = 0; ks < 2; ++ks) {
;       bf16x8 xf[MT], wf[4];
;       const int ch = ((ks * 4 + g) ^ rsw) << 4;
; #pragma unroll
;       for (int i = 0; i < MT; ++i) xf[i] = *(const bf16x8*)(cur + (wm * 16 * MT + i * 16 + lr) * 128 + ch);
; #pragma unroll
;       for (int i = 0; i < 4; ++i) wf[i] = *(const bf16x8*)(cur + 16384 + (wn * 64 + i * 16 + lr) * 128 + ch);
; #pragma unroll
;       for (int nt = 0; nt < 4; ++nt)
; #pragma unroll
;         for (int mt = 0; mt < MT; ++mt)
;           acc[nt][mt] = __builtin_amdgcn_mfma_f32_16x16x32_bf16(wf[nt], xf[mt], acc[nt][mt], 0, 0, 0);
;     }
;   } while (++kt < nk);
.LBB0_422:
	s_add_i32 s7, s8, 0x8000
	v_lshl_add_u64 v[124:125], v[76:77], 0, s[40:41]
	s_and_b32 s9, s7, 0x8000
	v_lshl_add_u64 v[122:123], v[74:75], 0, s[40:41]
	v_lshl_add_u64 v[126:127], v[124:125], 0, s[74:75]
	s_waitcnt vmcnt(0)
	s_barrier
	s_and_b32 s8, s8, 0x8000
	v_or_b32_e32 v162, s8, v85
	v_add3_u32 v163, v162, v81, v82
	v_add3_u32 v164, v162, v84, v82
	v_or_b32_e32 v165, s8, v83
	v_add3_u32 v166, v165, v81, v82
	v_add3_u32 v167, v165, v84, v82
	ds_read_b128 v[86:89], v163
	ds_read_b128 v[90:93], v163 offset:2048
	ds_read_b128 v[94:97], v163 offset:4096
	ds_read_b128 v[98:101], v163 offset:6144
	ds_read_b128 v[102:105], v164 offset:16384
	ds_read_b128 v[106:109], v164 offset:18432
	ds_read_b128 v[110:113], v164 offset:20480
	ds_read_b128 v[114:117], v164 offset:22528
	ds_read_b128 v[130:133], v166
	ds_read_b128 v[134:137], v166 offset:2048
	ds_read_b128 v[138:141], v166 offset:4096
	ds_read_b128 v[142:145], v166 offset:6144
	ds_read_b128 v[146:149], v167 offset:16384
	ds_read_b128 v[150:153], v167 offset:18432
	ds_read_b128 v[154:157], v167 offset:20480
	ds_read_b128 v[158:161], v167 offset:22528
	s_add_i32 s10, s9, s5
	s_mov_b32 m0, s10
	s_nop 0
	global_load_lds_dwordx4 v[126:127], off
	v_lshl_add_u64 v[126:127], v[122:123], 0, s[94:95]
	s_add_i32 s11, s10, 0x400
	s_mov_b32 m0, s11
	s_nop 0
	global_load_lds_dwordx4 v[126:127], off
	v_lshl_add_u64 v[124:125], v[124:125], 0, s[76:77]
	s_add_i32 s11, s10, 0x800
	s_mov_b32 m0, s11
	s_nop 0
	global_load_lds_dwordx4 v[124:125], off
	v_lshl_add_u64 v[120:121], v[72:73], 0, s[40:41]
	v_lshl_add_u64 v[122:123], v[122:123], 0, s[54:55]
	s_addk_i32 s10, 0xc00
	s_mov_b32 m0, s10
	s_nop 0
	global_load_lds_dwordx4 v[122:123], off
	v_lshl_add_u64 v[118:119], v[70:71], 0, s[40:41]
	v_lshl_add_u64 v[128:129], v[120:121], 0, s[28:29]
	s_add_i32 s9, s9, s6
	s_mov_b32 m0, s9
	s_nop 0
	global_load_lds_dwordx4 v[128:129], off
	v_lshl_add_u64 v[122:123], v[118:119], 0, s[94:95]
	s_add_i32 s10, s9, 0x400
	s_mov_b32 m0, s10
	s_nop 0
	global_load_lds_dwordx4 v[122:123], off
	v_lshl_add_u64 v[120:121], v[120:121], 0, s[78:79]
	s_add_i32 s10, s9, 0x800
	s_mov_b32 m0, s10
	s_nop 0
	global_load_lds_dwordx4 v[120:121], off
	v_lshl_add_u64 v[118:119], v[118:119], 0, s[54:55]
	s_addk_i32 s9, 0xc00
	s_mov_b32 m0, s9
	s_nop 0
	global_load_lds_dwordx4 v[118:119], off
	s_mov_b32 s8, s7
	s_add_u32 s40, s40, 0x80
	s_addc_u32 s41, s41, 0
	s_cmpk_lg_i32 s40, 0x780
	s_waitcnt lgkmcnt(11)
	v_mfma_f32_16x16x32_bf16 v[62:65], v[102:105], v[86:89], v[62:65]
	v_mfma_f32_16x16x32_bf16 v[58:61], v[102:105], v[90:93], v[58:61]
	v_mfma_f32_16x16x32_bf16 v[54:57], v[102:105], v[94:97], v[54:57]
	v_mfma_f32_16x16x32_bf16 v[50:53], v[102:105], v[98:101], v[50:53]
	s_waitcnt lgkmcnt(10)
	v_mfma_f32_16x16x32_bf16 v[34:37], v[106:109], v[98:101], v[34:37]
	s_waitcnt lgkmcnt(9)
	v_mfma_f32_16x16x32_bf16 v[18:21], v[110:113], v[98:101], v[18:21]
	s_waitcnt lgkmcnt(8)
	v_mfma_f32_16x16x32_bf16 v[14:17], v[114:117], v[86:89], v[14:17]
	v_mfma_f32_16x16x32_bf16 v[10:13], v[114:117], v[90:93], v[10:13]
	v_mfma_f32_16x16x32_bf16 v[6:9], v[114:117], v[94:97], v[6:9]
	v_mfma_f32_16x16x32_bf16 v[2:5], v[114:117], v[98:101], v[2:5]
	v_mfma_f32_16x16x32_bf16 v[46:49], v[106:109], v[86:89], v[46:49]
	v_mfma_f32_16x16x32_bf16 v[42:45], v[106:109], v[90:93], v[42:45]
	v_mfma_f32_16x16x32_bf16 v[38:41], v[106:109], v[94:97], v[38:41]
	v_mfma_f32_16x16x32_bf16 v[30:33], v[110:113], v[86:89], v[30:33]
	v_mfma_f32_16x16x32_bf16 v[26:29], v[110:113], v[90:93], v[26:29]
	v_mfma_f32_16x16x32_bf16 v[22:25], v[110:113], v[94:97], v[22:25]
	s_waitcnt lgkmcnt(3)
	v_mfma_f32_16x16x32_bf16 v[62:65], v[146:149], v[130:133], v[62:65]
	v_mfma_f32_16x16x32_bf16 v[58:61], v[146:149], v[134:137], v[58:61]
	v_mfma_f32_16x16x32_bf16 v[54:57], v[146:149], v[138:141], v[54:57]
	v_mfma_f32_16x16x32_bf16 v[50:53], v[146:149], v[142:145], v[50:53]
	s_waitcnt lgkmcnt(2)
	v_mfma_f32_16x16x32_bf16 v[46:49], v[150:153], v[130:133], v[46:49]
	v_mfma_f32_16x16x32_bf16 v[42:45], v[150:153], v[134:137], v[42:45]
	v_mfma_f32_16x16x32_bf16 v[38:41], v[150:153], v[138:141], v[38:41]
	v_mfma_f32_16x16x32_bf16 v[34:37], v[150:153], v[142:145], v[34:37]
	s_waitcnt lgkmcnt(1)
	v_mfma_f32_16x16x32_bf16 v[30:33], v[154:157], v[130:133], v[30:33]
	v_mfma_f32_16x16x32_bf16 v[26:29], v[154:157], v[134:137], v[26:29]
	v_mfma_f32_16x16x32_bf16 v[22:25], v[154:157], v[138:141], v[22:25]
	v_mfma_f32_16x16x32_bf16 v[18:21], v[154:157], v[142:145], v[18:21]
	s_waitcnt lgkmcnt(0)
	v_mfma_f32_16x16x32_bf16 v[14:17], v[158:161], v[130:133], v[14:17]
	v_mfma_f32_16x16x32_bf16 v[10:13], v[158:161], v[134:137], v[10:13]
	v_mfma_f32_16x16x32_bf16 v[6:9], v[158:161], v[138:141], v[6:9]
	v_mfma_f32_16x16x32_bf16 v[2:5], v[158:161], v[142:145], v[2:5]
	s_cbranch_scc1 .LBB0_422
; DI int get_bid() { int b = blockIdx.x; asm volatile("" : "+s"(b)); return b; }
; template <int MT, class Epi>
; DI void gemm_tile(const u16* __restrict__ X, long ldx, const u16* __restrict__ W, long ldw, int K, char* smem,
;                   int m0, int n0, const Epi& epi, bool pre = false, const u16* Xn = nullptr, const u16* Wn = nullptr) {
;     ...
;   if (!pre) {
;     __syncthreads();
;     GT_DMA(0u)
;   } else {
;     xe += 64; xo += 64; we += 64; wo += 64;
;   }
;   const int nk = K >> 6;
;   int kt = 0;
;   do {
;     asm volatile("s_waitcnt vmcnt(0)" ::: "memory");
;     __syncthreads();
;     if (kt + 1 < nk) GT_DMA((unsigned)((kt + 1) & 1) * 32768u)
;     else if (Xn != nullptr) { xe = Xn + oxe; xo = Xn + oxo; we = Wn + owe; wo = Wn + owo; GT_DMA(0u) }
; DI void phase_even(const Params& p, int e, int sub, char* smem) {
;     ...
;     for (int t = get_bid(); t < 132 * 40; t += gridDim.x) {
;       const int tm = t / 40, tn = t % 40;
;       const int t2 = t + gridDim.x, tm2 = t2 / 40, tn2 = t2 % 40;
;       const bool nx = t2 < 132 * 40;
;       gemm_tile<4>(hbuf + (size_t)tm * 128 * 1024, 1024, W + WE_IN + (size_t)tn * 128 * 1024, 1024, 1024, smem, tm * 128, tn * 128, epi, pre,
;                    nx ? hbuf + (size_t)tm2 * 128 * 1024 : nullptr, W + WE_IN + (size_t)tn2 * 128 * 1024);
;       pre = nx;
	v_mov_b32_e32 v170, 0x3f3504f3
	v_mov_b32_e32 v171, 0x3f3504f3
	v_mov_b32_e32 v172, 0xbfb8aa3b
	v_mov_b32_e32 v173, 0xbfb8aa3b
	v_mov_b32_e32 v174, 0x378e98ab
	v_mov_b32_e32 v175, 0x378e98ab
	v_mov_b32_e32 v176, 0xb9c68948
	v_mov_b32_e32 v177, 0xb9c68948
	v_mov_b32_e32 v178, 0x3b7cd369
	v_mov_b32_e32 v179, 0x3b7cd369
	v_mov_b32_e32 v180, 0xbcc618b2
	v_mov_b32_e32 v181, 0xbcc618b2
	v_mov_b32_e32 v186, 0x3dda74e4
	v_mov_b32_e32 v187, 0x3dda74e4
	v_mov_b32_e32 v188, 0x3f228afd
	v_mov_b32_e32 v189, 0x3f228afd
	v_mov_b32_e32 v190, 0x3e03c728
	v_mov_b32_e32 v191, 0x3e03c728
	v_mov_b32_e32 v192, 0xba1345e1
	v_mov_b32_e32 v193, 0xba1345e1
	v_mov_b32_e32 v194, 0x3ba10414
	v_mov_b32_e32 v195, 0x3ba10414
	v_mov_b32_e32 v196, 0xbcdac9b8
	v_mov_b32_e32 v197, 0xbcdac9b8
	v_mov_b32_e32 v224, 0x3de703be
	v_mov_b32_e32 v225, 0x3de703be
	v_mov_b32_e32 v226, 0xbec09330
	v_mov_b32_e32 v227, 0xbec09330
	v_mov_b32_e32 v228, 0x3e0375d0
	v_mov_b32_e32 v229, 0x3e0375d0
	v_mov_b32_e32 v230, 1.0
	v_mov_b32_e32 v231, 1.0
	v_mov_b32_e32 v232, 0.5
	v_mov_b32_e32 v233, 0.5
	v_mov_b32_e32 v234, -1.0
	v_mov_b32_e32 v235, -1.0
	v_readlane_b32 s8, v255, 5
	v_readlane_b32 s14, v255, 11
	s_add_i32 s4, s4, s14
	s_mul_hi_i32 s7, s4, 0x66666667
	s_lshr_b32 s8, s7, 31
	s_ashr_i32 s7, s7, 4
	s_add_i32 s46, s7, s8
	s_cmpk_gt_i32 s4, 0x149f
	v_readlane_b32 s9, v255, 6
	s_cselect_b64 s[44:45], -1, 0
	s_ashr_i32 s47, s46, 31
	s_lshl_b64 s[8:9], s[46:47], 18
	s_add_u32 s7, s0, s8
	s_addc_u32 s8, s1, s9
	s_cmpk_lt_i32 s4, 0x14a0
	s_waitcnt vmcnt(0)
	s_cselect_b32 s41, s8, 0
	s_cselect_b32 s40, s7, 0
	v_readlane_b32 s12, v255, 9
	v_readlane_b32 s13, v255, 10
	s_cmp_eq_u64 s[40:41], 0
	v_readlane_b32 s10, v255, 7
	v_readlane_b32 s11, v255, 8
	v_readlane_b32 s15, v255, 12
	s_barrier
	s_cbranch_scc1 .LBB0_425
	s_mul_i32 s7, s46, 40
	s_sub_i32 s8, s4, s7
	s_ashr_i32 s9, s8, 31
	s_lshl_b64 s[8:9], s[8:9], 18
	s_add_u32 s8, s12, s8
	s_addc_u32 s9, s13, s9
	v_lshl_add_u64 v[70:71], s[40:41], 0, v[68:69]
	v_lshl_add_u64 v[72:73], s[8:9], 0, v[66:67]
	v_lshl_add_u64 v[66:67], s[40:41], 0, v[66:67]
	s_mov_b32 m0, s5
	s_nop 0
	global_load_lds_dwordx4 v[70:71], off
	s_mov_b64 s[10:11], 0x4000
	v_lshl_add_u64 v[68:69], s[8:9], 0, v[68:69]
	v_lshl_add_u64 v[74:75], v[66:67], 0, s[10:11]
	s_add_i32 s7, s5, 0x400
	s_mov_b32 m0, s7
	s_nop 0
	global_load_lds_dwordx4 v[74:75], off
	s_mov_b64 s[12:13], 0x8000
	v_lshl_add_u64 v[70:71], v[70:71], 0, s[12:13]
	s_add_i32 s7, s5, 0x800
	s_mov_b32 m0, s7
	s_nop 0
	global_load_lds_dwordx4 v[70:71], off
	s_mov_b64 s[14:15], 0xc000
	v_lshl_add_u64 v[66:67], v[66:67], 0, s[14:15]
	s_add_i32 s7, s5, 0xc00
	s_mov_b32 m0, s7
	s_nop 0
	global_load_lds_dwordx4 v[66:67], off
	s_mov_b32 m0, s6
	s_nop 0
	global_load_lds_dwordx4 v[68:69], off
	v_lshl_add_u64 v[66:67], v[72:73], 0, s[10:11]
	s_add_i32 s6, s5, 0x4400
	s_mov_b32 m0, s6
	s_nop 0
	global_load_lds_dwordx4 v[66:67], off
	v_lshl_add_u64 v[66:67], v[68:69], 0, s[12:13]
	s_add_i32 s6, s5, 0x4800
	s_mov_b32 m0, s6
	s_nop 0
	global_load_lds_dwordx4 v[66:67], off
	v_lshl_add_u64 v[66:67], v[72:73], 0, s[14:15]
	s_addk_i32 s5, 0x4c00
	s_mov_b32 m0, s5
	s_nop 0
	global_load_lds_dwordx4 v[66:67], off

; DI float silu_f(float x) { return x * __builtin_amdgcn_rcpf(1.f + __expf(-x)); }
; DI void st_bf4(u16* p, float a, float b, float c, float d) { *(uint2*)p = make_uint2(pk2(a, b), pk2(c, d)); }
; DI float gelu_f(float x) { return 0.5f * x * (1.f + erff(x * 0.70710678118654752f)); }
;   template <int NT, int MT> DI void run(f32x4 (&acc)[NT][MT], int mb, int nb) const {
;     ...
;         if (n < 1024) {
;           st_bf4(abuf + (size_t)m * 1024 + n, v[0], v[1], v[2], v[3]);
;           float* dst = nullptr;
;           if (m < M_PROMPT) { int t = m & 8191; if (t >= 8177) dst = spp + ((size_t)((m >> 13) * 15 + (t - 8177))) * 1024 + n; }
;           else { int r = m - M_PROMPT; int s = r & 31; if (s >= 17) dst = sps + ((size_t)((r >> 5) * 15 + (s - 17))) * 1024 + n; }
;           if (dst) *(float4*)dst = make_float4(v[0], v[1], v[2], v[3]);
;         } else if (n < 3072) {
;           st_bf4(uvbuf + (size_t)m * 2048 + (n - 1024), gelu_f(v[0]), gelu_f(v[1]), gelu_f(v[2]), gelu_f(v[3]));
;         } else {
;           st_bf4(gatebuf + (size_t)m * 2048 + (n - 3072), silu_f(v[0]), silu_f(v[1]), silu_f(v[2]), silu_f(v[3]));
.LBB0_428:
	s_andn2_saveexec_b64 s[48:49], s[48:49]
	s_cbranch_execz .LBB0_446
	v_pk_mul_f32 v[130:131], v[62:63], v[170:171]
	v_pk_mul_f32 v[142:143], v[64:65], v[170:171]
	v_and_b32_e32 v132, 0x7fffffff, v130
	v_and_b32_e32 v144, 0x7fffffff, v142
	v_and_b32_e32 v133, 0x7fffffff, v131
	v_and_b32_e32 v145, 0x7fffffff, v143
	v_pk_fma_f32 v[134:135], v[132:133], v[174:175], v[176:177]
	v_pk_fma_f32 v[146:147], v[144:145], v[174:175], v[176:177]
	v_pk_fma_f32 v[134:135], v[132:133], v[134:135], v[178:179]
	v_pk_fma_f32 v[146:147], v[144:145], v[146:147], v[178:179]
	v_pk_fma_f32 v[134:135], v[132:133], v[134:135], v[180:181]
	v_pk_fma_f32 v[146:147], v[144:145], v[146:147], v[180:181]
	v_pk_fma_f32 v[134:135], v[132:133], v[134:135], v[186:187]
	v_pk_fma_f32 v[146:147], v[144:145], v[146:147], v[186:187]
	v_pk_fma_f32 v[134:135], v[132:133], v[134:135], v[188:189]
	v_pk_fma_f32 v[146:147], v[144:145], v[146:147], v[188:189]
	v_pk_fma_f32 v[134:135], v[132:133], v[134:135], v[190:191]
	v_pk_fma_f32 v[146:147], v[144:145], v[146:147], v[190:191]
	v_pk_fma_f32 v[134:135], v[132:133], v[134:135], v[132:133]
	v_pk_fma_f32 v[146:147], v[144:145], v[146:147], v[144:145]
	v_pk_mul_f32 v[134:135], v[134:135], v[172:173]
	v_pk_mul_f32 v[146:147], v[146:147], v[172:173]
	v_pk_mul_f32 v[136:137], v[130:131], v[130:131]
	v_pk_mul_f32 v[148:149], v[142:143], v[142:143]
	v_exp_f32_e32 v134, v134
	v_exp_f32_e32 v146, v146
	v_exp_f32_e32 v135, v135
	v_exp_f32_e32 v147, v147
	v_pk_fma_f32 v[138:139], v[136:137], v[192:193], v[194:195]
	v_pk_fma_f32 v[150:151], v[148:149], v[192:193], v[194:195]
	v_pk_fma_f32 v[138:139], v[136:137], v[138:139], v[196:197]
	v_pk_fma_f32 v[150:151], v[148:149], v[150:151], v[196:197]
	v_pk_fma_f32 v[138:139], v[136:137], v[138:139], v[224:225]
	v_pk_fma_f32 v[150:151], v[148:149], v[150:151], v[224:225]
	v_pk_fma_f32 v[138:139], v[136:137], v[138:139], v[226:227]
	v_pk_fma_f32 v[150:151], v[148:149], v[150:151], v[226:227]
	v_pk_fma_f32 v[138:139], v[136:137], v[138:139], v[228:229]
	v_pk_fma_f32 v[150:151], v[148:149], v[150:151], v[228:229]
	v_pk_fma_f32 v[134:135], v[134:135], v[234:235], v[230:231]
	v_pk_fma_f32 v[146:147], v[146:147], v[234:235], v[230:231]
	v_pk_fma_f32 v[138:139], v[132:133], v[138:139], v[132:133]
	v_pk_fma_f32 v[150:151], v[144:145], v[150:151], v[144:145]
	v_pk_mul_f32 v[140:141], v[62:63], v[232:233]
	v_pk_mul_f32 v[152:153], v[64:65], v[232:233]
	v_cmp_ngt_f32_e32 vcc, 1.0, v132
	v_cmp_ngt_f32_e64 s[8:9], 1.0, v133
	v_readlane_b32 s6, v252, 33
	v_readlane_b32 s7, v252, 34
	v_cndmask_b32_e32 v138, v138, v134, vcc
	v_cndmask_b32_e64 v139, v139, v135, s[8:9]
	v_cmp_ngt_f32_e32 vcc, 1.0, v144
	v_cmp_ngt_f32_e64 s[8:9], 1.0, v145
	v_bfi_b32 v138, s37, v138, v130
	v_bfi_b32 v139, s37, v139, v131
	v_cndmask_b32_e32 v150, v150, v146, vcc
	v_cndmask_b32_e64 v151, v151, v147, s[8:9]
	v_pk_add_f32 v[138:139], v[138:139], v[230:231]
	v_bfi_b32 v150, s37, v150, v142
	v_bfi_b32 v151, s37, v151, v143
	v_pk_add_f32 v[150:151], v[150:151], v[230:231]
	v_pk_mul_f32 v[138:139], v[140:141], v[138:139]
	v_lshl_add_u64 v[62:63], s[6:7], 0, v[68:69]
	v_pk_mul_f32 v[150:151], v[152:153], v[150:151]
	v_lshl_add_u64 v[62:63], v[182:183], 1, v[62:63]
	v_cvt_pk_bf16_f32 v64, v138, v139
	v_cvt_pk_bf16_f32 v65, v150, v151
	global_store_dwordx2 v[62:63], v[64:65], off offset:-2048

; DI float silu_f(float x) { return x * __builtin_amdgcn_rcpf(1.f + __expf(-x)); }
; DI void st_bf4(u16* p, float a, float b, float c, float d) { *(uint2*)p = make_uint2(pk2(a, b), pk2(c, d)); }
; DI float gelu_f(float x) { return 0.5f * x * (1.f + erff(x * 0.70710678118654752f)); }
;   template <int NT, int MT> DI void run(f32x4 (&acc)[NT][MT], int mb, int nb) const {
;     ...
;         if (n < 1024) {
;           st_bf4(abuf + (size_t)m * 1024 + n, v[0], v[1], v[2], v[3]);
;           float* dst = nullptr;
;           if (m < M_PROMPT) { int t = m & 8191; if (t >= 8177) dst = spp + ((size_t)((m >> 13) * 15 + (t - 8177))) * 1024 + n; }
;           else { int r = m - M_PROMPT; int s = r & 31; if (s >= 17) dst = sps + ((size_t)((r >> 5) * 15 + (s - 17))) * 1024 + n; }
;           if (dst) *(float4*)dst = make_float4(v[0], v[1], v[2], v[3]);
;         } else if (n < 3072) {
;           st_bf4(uvbuf + (size_t)m * 2048 + (n - 1024), gelu_f(v[0]), gelu_f(v[1]), gelu_f(v[2]), gelu_f(v[3]));
;         } else {
;           st_bf4(gatebuf + (size_t)m * 2048 + (n - 3072), silu_f(v[0]), silu_f(v[1]), silu_f(v[2]), silu_f(v[3]));
.LBB0_452:
	s_andn2_saveexec_b64 s[48:49], s[48:49]
	s_cbranch_execz .LBB0_470
	v_pk_mul_f32 v[130:131], v[58:59], v[170:171]
	v_pk_mul_f32 v[142:143], v[60:61], v[170:171]
	v_and_b32_e32 v132, 0x7fffffff, v130
	v_and_b32_e32 v144, 0x7fffffff, v142
	v_and_b32_e32 v133, 0x7fffffff, v131
	v_and_b32_e32 v145, 0x7fffffff, v143
	v_pk_fma_f32 v[134:135], v[132:133], v[174:175], v[176:177]
	v_pk_fma_f32 v[146:147], v[144:145], v[174:175], v[176:177]
	v_pk_fma_f32 v[134:135], v[132:133], v[134:135], v[178:179]
	v_pk_fma_f32 v[146:147], v[144:145], v[146:147], v[178:179]
	v_pk_fma_f32 v[134:135], v[132:133], v[134:135], v[180:181]
	v_pk_fma_f32 v[146:147], v[144:145], v[146:147], v[180:181]
	v_pk_fma_f32 v[134:135], v[132:133], v[134:135], v[186:187]
	v_pk_fma_f32 v[146:147], v[144:145], v[146:147], v[186:187]
	v_pk_fma_f32 v[134:135], v[132:133], v[134:135], v[188:189]
	v_pk_fma_f32 v[146:147], v[144:145], v[146:147], v[188:189]
	v_pk_fma_f32 v[134:135], v[132:133], v[134:135], v[190:191]
	v_pk_fma_f32 v[146:147], v[144:145], v[146:147], v[190:191]
	v_pk_fma_f32 v[134:135], v[132:133], v[134:135], v[132:133]
	v_pk_fma_f32 v[146:147], v[144:145], v[146:147], v[144:145]
	v_pk_mul_f32 v[134:135], v[134:135], v[172:173]
	v_pk_mul_f32 v[146:147], v[146:147], v[172:173]
	v_pk_mul_f32 v[136:137], v[130:131], v[130:131]
	v_pk_mul_f32 v[148:149], v[142:143], v[142:143]
	v_exp_f32_e32 v134, v134
	v_exp_f32_e32 v146, v146
	v_exp_f32_e32 v135, v135
	v_exp_f32_e32 v147, v147
	v_pk_fma_f32 v[138:139], v[136:137], v[192:193], v[194:195]
	v_pk_fma_f32 v[150:151], v[148:149], v[192:193], v[194:195]
	v_pk_fma_f32 v[138:139], v[136:137], v[138:139], v[196:197]
	v_pk_fma_f32 v[150:151], v[148:149], v[150:151], v[196:197]
	v_pk_fma_f32 v[138:139], v[136:137], v[138:139], v[224:225]
	v_pk_fma_f32 v[150:151], v[148:149], v[150:151], v[224:225]
	v_pk_fma_f32 v[138:139], v[136:137], v[138:139], v[226:227]
	v_pk_fma_f32 v[150:151], v[148:149], v[150:151], v[226:227]
	v_pk_fma_f32 v[138:139], v[136:137], v[138:139], v[228:229]
	v_pk_fma_f32 v[150:151], v[148:149], v[150:151], v[228:229]
	v_pk_fma_f32 v[134:135], v[134:135], v[234:235], v[230:231]
	v_pk_fma_f32 v[146:147], v[146:147], v[234:235], v[230:231]
	v_pk_fma_f32 v[138:139], v[132:133], v[138:139], v[132:133]
	v_pk_fma_f32 v[150:151], v[144:145], v[150:151], v[144:145]
	v_pk_mul_f32 v[140:141], v[58:59], v[232:233]
	v_pk_mul_f32 v[152:153], v[60:61], v[232:233]
	v_cmp_ngt_f32_e32 vcc, 1.0, v132
	v_cmp_ngt_f32_e64 s[8:9], 1.0, v133
	v_readlane_b32 s6, v252, 33
	v_readlane_b32 s7, v252, 34
	v_cndmask_b32_e32 v138, v138, v134, vcc
	v_cndmask_b32_e64 v139, v139, v135, s[8:9]
	v_cmp_ngt_f32_e32 vcc, 1.0, v144
	v_cmp_ngt_f32_e64 s[8:9], 1.0, v145
	v_bfi_b32 v138, s37, v138, v130
	v_bfi_b32 v139, s37, v139, v131
	v_cndmask_b32_e32 v150, v150, v146, vcc
	v_cndmask_b32_e64 v151, v151, v147, s[8:9]
	v_pk_add_f32 v[138:139], v[138:139], v[230:231]
	v_bfi_b32 v150, s37, v150, v142
	v_bfi_b32 v151, s37, v151, v143
	v_pk_add_f32 v[150:151], v[150:151], v[230:231]
	v_pk_mul_f32 v[138:139], v[140:141], v[138:139]
	v_lshl_add_u64 v[58:59], s[6:7], 0, v[64:65]
	v_pk_mul_f32 v[150:151], v[152:153], v[150:151]
	v_lshl_add_u64 v[58:59], v[182:183], 1, v[58:59]
	v_cvt_pk_bf16_f32 v60, v138, v139
	v_cvt_pk_bf16_f32 v61, v150, v151
	global_store_dwordx2 v[58:59], v[60:61], off offset:-2048

; DI float silu_f(float x) { return x * __builtin_amdgcn_rcpf(1.f + __expf(-x)); }
; DI void st_bf4(u16* p, float a, float b, float c, float d) { *(uint2*)p = make_uint2(pk2(a, b), pk2(c, d)); }
; DI float gelu_f(float x) { return 0.5f * x * (1.f + erff(x * 0.70710678118654752f)); }
;   template <int NT, int MT> DI void run(f32x4 (&acc)[NT][MT], int mb, int nb) const {
;     ...
;         if (n < 1024) {
;           st_bf4(abuf + (size_t)m * 1024 + n, v[0], v[1], v[2], v[3]);
;           float* dst = nullptr;
;           if (m < M_PROMPT) { int t = m & 8191; if (t >= 8177) dst = spp + ((size_t)((m >> 13) * 15 + (t - 8177))) * 1024 + n; }
;           else { int r = m - M_PROMPT; int s = r & 31; if (s >= 17) dst = sps + ((size_t)((r >> 5) * 15 + (s - 17))) * 1024 + n; }
;           if (dst) *(float4*)dst = make_float4(v[0], v[1], v[2], v[3]);
;         } else if (n < 3072) {
;           st_bf4(uvbuf + (size_t)m * 2048 + (n - 1024), gelu_f(v[0]), gelu_f(v[1]), gelu_f(v[2]), gelu_f(v[3]));
;         } else {
;           st_bf4(gatebuf + (size_t)m * 2048 + (n - 3072), silu_f(v[0]), silu_f(v[1]), silu_f(v[2]), silu_f(v[3]));
.LBB0_482:
	s_andn2_saveexec_b64 s[48:49], s[48:49]
	s_cbranch_execz .LBB0_500
	v_pk_mul_f32 v[130:131], v[54:55], v[170:171]
	v_pk_mul_f32 v[142:143], v[56:57], v[170:171]
	v_and_b32_e32 v132, 0x7fffffff, v130
	v_and_b32_e32 v144, 0x7fffffff, v142
	v_and_b32_e32 v133, 0x7fffffff, v131
	v_and_b32_e32 v145, 0x7fffffff, v143
	v_pk_fma_f32 v[134:135], v[132:133], v[174:175], v[176:177]
	v_pk_fma_f32 v[146:147], v[144:145], v[174:175], v[176:177]
	v_pk_fma_f32 v[134:135], v[132:133], v[134:135], v[178:179]
	v_pk_fma_f32 v[146:147], v[144:145], v[146:147], v[178:179]
	v_pk_fma_f32 v[134:135], v[132:133], v[134:135], v[180:181]
	v_pk_fma_f32 v[146:147], v[144:145], v[146:147], v[180:181]
	v_pk_fma_f32 v[134:135], v[132:133], v[134:135], v[186:187]
	v_pk_fma_f32 v[146:147], v[144:145], v[146:147], v[186:187]
	v_pk_fma_f32 v[134:135], v[132:133], v[134:135], v[188:189]
	v_pk_fma_f32 v[146:147], v[144:145], v[146:147], v[188:189]
	v_pk_fma_f32 v[134:135], v[132:133], v[134:135], v[190:191]
	v_pk_fma_f32 v[146:147], v[144:145], v[146:147], v[190:191]
	v_pk_fma_f32 v[134:135], v[132:133], v[134:135], v[132:133]
	v_pk_fma_f32 v[146:147], v[144:145], v[146:147], v[144:145]
	v_pk_mul_f32 v[134:135], v[134:135], v[172:173]
	v_pk_mul_f32 v[146:147], v[146:147], v[172:173]
	v_pk_mul_f32 v[136:137], v[130:131], v[130:131]
	v_pk_mul_f32 v[148:149], v[142:143], v[142:143]
	v_exp_f32_e32 v134, v134
	v_exp_f32_e32 v146, v146
	v_exp_f32_e32 v135, v135
	v_exp_f32_e32 v147, v147
	v_pk_fma_f32 v[138:139], v[136:137], v[192:193], v[194:195]
	v_pk_fma_f32 v[150:151], v[148:149], v[192:193], v[194:195]
	v_pk_fma_f32 v[138:139], v[136:137], v[138:139], v[196:197]
	v_pk_fma_f32 v[150:151], v[148:149], v[150:151], v[196:197]
	v_pk_fma_f32 v[138:139], v[136:137], v[138:139], v[224:225]
	v_pk_fma_f32 v[150:151], v[148:149], v[150:151], v[224:225]
	v_pk_fma_f32 v[138:139], v[136:137], v[138:139], v[226:227]
	v_pk_fma_f32 v[150:151], v[148:149], v[150:151], v[226:227]
	v_pk_fma_f32 v[138:139], v[136:137], v[138:139], v[228:229]
	v_pk_fma_f32 v[150:151], v[148:149], v[150:151], v[228:229]
	v_pk_fma_f32 v[134:135], v[134:135], v[234:235], v[230:231]
	v_pk_fma_f32 v[146:147], v[146:147], v[234:235], v[230:231]
	v_pk_fma_f32 v[138:139], v[132:133], v[138:139], v[132:133]
	v_pk_fma_f32 v[150:151], v[144:145], v[150:151], v[144:145]
	v_pk_mul_f32 v[140:141], v[54:55], v[232:233]
	v_pk_mul_f32 v[152:153], v[56:57], v[232:233]
	v_cmp_ngt_f32_e32 vcc, 1.0, v132
	v_cmp_ngt_f32_e64 s[8:9], 1.0, v133
	v_readlane_b32 s6, v252, 33
	v_readlane_b32 s7, v252, 34
	v_cndmask_b32_e32 v138, v138, v134, vcc
	v_cndmask_b32_e64 v139, v139, v135, s[8:9]
	v_cmp_ngt_f32_e32 vcc, 1.0, v144
	v_cmp_ngt_f32_e64 s[8:9], 1.0, v145
	v_bfi_b32 v138, s37, v138, v130
	v_bfi_b32 v139, s37, v139, v131
	v_cndmask_b32_e32 v150, v150, v146, vcc
	v_cndmask_b32_e64 v151, v151, v147, s[8:9]
	v_pk_add_f32 v[138:139], v[138:139], v[230:231]
	v_bfi_b32 v150, s37, v150, v142
	v_bfi_b32 v151, s37, v151, v143
	v_pk_add_f32 v[150:151], v[150:151], v[230:231]
	v_pk_mul_f32 v[138:139], v[140:141], v[138:139]
	v_lshl_add_u64 v[54:55], s[6:7], 0, v[60:61]
	v_pk_mul_f32 v[150:151], v[152:153], v[150:151]
	v_lshl_add_u64 v[54:55], v[182:183], 1, v[54:55]
	v_cvt_pk_bf16_f32 v56, v138, v139
	v_cvt_pk_bf16_f32 v57, v150, v151
	global_store_dwordx2 v[54:55], v[56:57], off offset:-2048

; DI float silu_f(float x) { return x * __builtin_amdgcn_rcpf(1.f + __expf(-x)); }
; DI void st_bf4(u16* p, float a, float b, float c, float d) { *(uint2*)p = make_uint2(pk2(a, b), pk2(c, d)); }
; DI float gelu_f(float x) { return 0.5f * x * (1.f + erff(x * 0.70710678118654752f)); }
;   template <int NT, int MT> DI void run(f32x4 (&acc)[NT][MT], int mb, int nb) const {
;     ...
;         if (n < 1024) {
;           st_bf4(abuf + (size_t)m * 1024 + n, v[0], v[1], v[2], v[3]);
;           float* dst = nullptr;
;           if (m < M_PROMPT) { int t = m & 8191; if (t >= 8177) dst = spp + ((size_t)((m >> 13) * 15 + (t - 8177))) * 1024 + n; }
;           else { int r = m - M_PROMPT; int s = r & 31; if (s >= 17) dst = sps + ((size_t)((r >> 5) * 15 + (s - 17))) * 1024 + n; }
;           if (dst) *(float4*)dst = make_float4(v[0], v[1], v[2], v[3]);
;         } else if (n < 3072) {
;           st_bf4(uvbuf + (size_t)m * 2048 + (n - 1024), gelu_f(v[0]), gelu_f(v[1]), gelu_f(v[2]), gelu_f(v[3]));
;         } else {
;           st_bf4(gatebuf + (size_t)m * 2048 + (n - 3072), silu_f(v[0]), silu_f(v[1]), silu_f(v[2]), silu_f(v[3]));
.LBB0_506:
	s_andn2_saveexec_b64 s[46:47], s[46:47]
	s_cbranch_execz .LBB0_524
	v_pk_mul_f32 v[130:131], v[50:51], v[170:171]
	v_pk_mul_f32 v[142:143], v[52:53], v[170:171]
	v_and_b32_e32 v132, 0x7fffffff, v130
	v_and_b32_e32 v144, 0x7fffffff, v142
	v_and_b32_e32 v133, 0x7fffffff, v131
	v_and_b32_e32 v145, 0x7fffffff, v143
	v_pk_fma_f32 v[134:135], v[132:133], v[174:175], v[176:177]
	v_pk_fma_f32 v[146:147], v[144:145], v[174:175], v[176:177]
	v_pk_fma_f32 v[134:135], v[132:133], v[134:135], v[178:179]
	v_pk_fma_f32 v[146:147], v[144:145], v[146:147], v[178:179]
	v_pk_fma_f32 v[134:135], v[132:133], v[134:135], v[180:181]
	v_pk_fma_f32 v[146:147], v[144:145], v[146:147], v[180:181]
	v_pk_fma_f32 v[134:135], v[132:133], v[134:135], v[186:187]
	v_pk_fma_f32 v[146:147], v[144:145], v[146:147], v[186:187]
	v_pk_fma_f32 v[134:135], v[132:133], v[134:135], v[188:189]
	v_pk_fma_f32 v[146:147], v[144:145], v[146:147], v[188:189]
	v_pk_fma_f32 v[134:135], v[132:133], v[134:135], v[190:191]
	v_pk_fma_f32 v[146:147], v[144:145], v[146:147], v[190:191]
	v_pk_fma_f32 v[134:135], v[132:133], v[134:135], v[132:133]
	v_pk_fma_f32 v[146:147], v[144:145], v[146:147], v[144:145]
	v_pk_mul_f32 v[134:135], v[134:135], v[172:173]
	v_pk_mul_f32 v[146:147], v[146:147], v[172:173]
	v_pk_mul_f32 v[136:137], v[130:131], v[130:131]
	v_pk_mul_f32 v[148:149], v[142:143], v[142:143]
	v_exp_f32_e32 v134, v134
	v_exp_f32_e32 v146, v146
	v_exp_f32_e32 v135, v135
	v_exp_f32_e32 v147, v147
	v_pk_fma_f32 v[138:139], v[136:137], v[192:193], v[194:195]
	v_pk_fma_f32 v[150:151], v[148:149], v[192:193], v[194:195]
	v_pk_fma_f32 v[138:139], v[136:137], v[138:139], v[196:197]
	v_pk_fma_f32 v[150:151], v[148:149], v[150:151], v[196:197]
	v_pk_fma_f32 v[138:139], v[136:137], v[138:139], v[224:225]
	v_pk_fma_f32 v[150:151], v[148:149], v[150:151], v[224:225]
	v_pk_fma_f32 v[138:139], v[136:137], v[138:139], v[226:227]
	v_pk_fma_f32 v[150:151], v[148:149], v[150:151], v[226:227]
	v_pk_fma_f32 v[138:139], v[136:137], v[138:139], v[228:229]
	v_pk_fma_f32 v[150:151], v[148:149], v[150:151], v[228:229]
	v_pk_fma_f32 v[134:135], v[134:135], v[234:235], v[230:231]
	v_pk_fma_f32 v[146:147], v[146:147], v[234:235], v[230:231]
	v_pk_fma_f32 v[138:139], v[132:133], v[138:139], v[132:133]
	v_pk_fma_f32 v[150:151], v[144:145], v[150:151], v[144:145]
	v_pk_mul_f32 v[140:141], v[50:51], v[232:233]
	v_pk_mul_f32 v[152:153], v[52:53], v[232:233]
	v_cmp_ngt_f32_e32 vcc, 1.0, v132
	v_cmp_ngt_f32_e64 s[8:9], 1.0, v133
	v_readlane_b32 s6, v252, 33
	v_readlane_b32 s7, v252, 34
	v_cndmask_b32_e32 v138, v138, v134, vcc
	v_cndmask_b32_e64 v139, v139, v135, s[8:9]
	v_cmp_ngt_f32_e32 vcc, 1.0, v144
	v_cmp_ngt_f32_e64 s[8:9], 1.0, v145
	v_bfi_b32 v138, s37, v138, v130
	v_bfi_b32 v139, s37, v139, v131
	v_cndmask_b32_e32 v150, v150, v146, vcc
	v_cndmask_b32_e64 v151, v151, v147, s[8:9]
	v_pk_add_f32 v[138:139], v[138:139], v[230:231]
	v_bfi_b32 v150, s37, v150, v142
	v_bfi_b32 v151, s37, v151, v143
	v_pk_add_f32 v[150:151], v[150:151], v[230:231]
	v_pk_mul_f32 v[138:139], v[140:141], v[138:139]
	v_lshl_add_u64 v[50:51], s[6:7], 0, v[56:57]
	v_pk_mul_f32 v[150:151], v[152:153], v[150:151]
	v_lshl_add_u64 v[50:51], v[182:183], 1, v[50:51]
	v_cvt_pk_bf16_f32 v52, v138, v139
	v_cvt_pk_bf16_f32 v53, v150, v151
	global_store_dwordx2 v[50:51], v[52:53], off offset:-2048

; DI float silu_f(float x) { return x * __builtin_amdgcn_rcpf(1.f + __expf(-x)); }
; DI void st_bf4(u16* p, float a, float b, float c, float d) { *(uint2*)p = make_uint2(pk2(a, b), pk2(c, d)); }
; DI float gelu_f(float x) { return 0.5f * x * (1.f + erff(x * 0.70710678118654752f)); }
;   template <int NT, int MT> DI void run(f32x4 (&acc)[NT][MT], int mb, int nb) const {
;     ...
;         if (n < 1024) {
;           st_bf4(abuf + (size_t)m * 1024 + n, v[0], v[1], v[2], v[3]);
;           float* dst = nullptr;
;           if (m < M_PROMPT) { int t = m & 8191; if (t >= 8177) dst = spp + ((size_t)((m >> 13) * 15 + (t - 8177))) * 1024 + n; }
;           else { int r = m - M_PROMPT; int s = r & 31; if (s >= 17) dst = sps + ((size_t)((r >> 5) * 15 + (s - 17))) * 1024 + n; }
;           if (dst) *(float4*)dst = make_float4(v[0], v[1], v[2], v[3]);
;         } else if (n < 3072) {
;           st_bf4(uvbuf + (size_t)m * 2048 + (n - 1024), gelu_f(v[0]), gelu_f(v[1]), gelu_f(v[2]), gelu_f(v[3]));
;         } else {
;           st_bf4(gatebuf + (size_t)m * 2048 + (n - 3072), silu_f(v[0]), silu_f(v[1]), silu_f(v[2]), silu_f(v[3]));
.LBB0_536:
	s_andn2_saveexec_b64 s[48:49], s[48:49]
	s_cbranch_execz .LBB0_554
	v_pk_mul_f32 v[130:131], v[46:47], v[170:171]
	v_pk_mul_f32 v[142:143], v[48:49], v[170:171]
	v_and_b32_e32 v132, 0x7fffffff, v130
	v_and_b32_e32 v144, 0x7fffffff, v142
	v_and_b32_e32 v133, 0x7fffffff, v131
	v_and_b32_e32 v145, 0x7fffffff, v143
	v_pk_fma_f32 v[134:135], v[132:133], v[174:175], v[176:177]
	v_pk_fma_f32 v[146:147], v[144:145], v[174:175], v[176:177]
	v_pk_fma_f32 v[134:135], v[132:133], v[134:135], v[178:179]
	v_pk_fma_f32 v[146:147], v[144:145], v[146:147], v[178:179]
	v_pk_fma_f32 v[134:135], v[132:133], v[134:135], v[180:181]
	v_pk_fma_f32 v[146:147], v[144:145], v[146:147], v[180:181]
	v_pk_fma_f32 v[134:135], v[132:133], v[134:135], v[186:187]
	v_pk_fma_f32 v[146:147], v[144:145], v[146:147], v[186:187]
	v_pk_fma_f32 v[134:135], v[132:133], v[134:135], v[188:189]
	v_pk_fma_f32 v[146:147], v[144:145], v[146:147], v[188:189]
	v_pk_fma_f32 v[134:135], v[132:133], v[134:135], v[190:191]
	v_pk_fma_f32 v[146:147], v[144:145], v[146:147], v[190:191]
	v_pk_fma_f32 v[134:135], v[132:133], v[134:135], v[132:133]
	v_pk_fma_f32 v[146:147], v[144:145], v[146:147], v[144:145]
	v_pk_mul_f32 v[134:135], v[134:135], v[172:173]
	v_pk_mul_f32 v[146:147], v[146:147], v[172:173]
	v_pk_mul_f32 v[136:137], v[130:131], v[130:131]
	v_pk_mul_f32 v[148:149], v[142:143], v[142:143]
	v_exp_f32_e32 v134, v134
	v_exp_f32_e32 v146, v146
	v_exp_f32_e32 v135, v135
	v_exp_f32_e32 v147, v147
	v_pk_fma_f32 v[138:139], v[136:137], v[192:193], v[194:195]
	v_pk_fma_f32 v[150:151], v[148:149], v[192:193], v[194:195]
	v_pk_fma_f32 v[138:139], v[136:137], v[138:139], v[196:197]
	v_pk_fma_f32 v[150:151], v[148:149], v[150:151], v[196:197]
	v_pk_fma_f32 v[138:139], v[136:137], v[138:139], v[224:225]
	v_pk_fma_f32 v[150:151], v[148:149], v[150:151], v[224:225]
	v_pk_fma_f32 v[138:139], v[136:137], v[138:139], v[226:227]
	v_pk_fma_f32 v[150:151], v[148:149], v[150:151], v[226:227]
	v_pk_fma_f32 v[138:139], v[136:137], v[138:139], v[228:229]
	v_pk_fma_f32 v[150:151], v[148:149], v[150:151], v[228:229]
	v_pk_fma_f32 v[134:135], v[134:135], v[234:235], v[230:231]
	v_pk_fma_f32 v[146:147], v[146:147], v[234:235], v[230:231]
	v_pk_fma_f32 v[138:139], v[132:133], v[138:139], v[132:133]
	v_pk_fma_f32 v[150:151], v[144:145], v[150:151], v[144:145]
	v_pk_mul_f32 v[140:141], v[46:47], v[232:233]
	v_pk_mul_f32 v[152:153], v[48:49], v[232:233]
	v_cmp_ngt_f32_e32 vcc, 1.0, v132
	v_cmp_ngt_f32_e64 s[8:9], 1.0, v133
	v_readlane_b32 s6, v252, 33
	v_readlane_b32 s7, v252, 34
	v_cndmask_b32_e32 v138, v138, v134, vcc
	v_cndmask_b32_e64 v139, v139, v135, s[8:9]
	v_cmp_ngt_f32_e32 vcc, 1.0, v144
	v_cmp_ngt_f32_e64 s[8:9], 1.0, v145
	v_bfi_b32 v138, s37, v138, v130
	v_bfi_b32 v139, s37, v139, v131
	v_cndmask_b32_e32 v150, v150, v146, vcc
	v_cndmask_b32_e64 v151, v151, v147, s[8:9]
	v_pk_add_f32 v[138:139], v[138:139], v[230:231]
	v_bfi_b32 v150, s37, v150, v142
	v_bfi_b32 v151, s37, v151, v143
	v_pk_add_f32 v[150:151], v[150:151], v[230:231]
	v_pk_mul_f32 v[138:139], v[140:141], v[138:139]
	v_lshl_add_u64 v[46:47], s[6:7], 0, v[50:51]
	v_pk_mul_f32 v[150:151], v[152:153], v[150:151]
	v_lshl_add_u64 v[46:47], v[182:183], 1, v[46:47]
	v_cvt_pk_bf16_f32 v48, v138, v139
	v_cvt_pk_bf16_f32 v49, v150, v151
	global_store_dwordx2 v[46:47], v[48:49], off offset:-2016

; DI float silu_f(float x) { return x * __builtin_amdgcn_rcpf(1.f + __expf(-x)); }
; DI void st_bf4(u16* p, float a, float b, float c, float d) { *(uint2*)p = make_uint2(pk2(a, b), pk2(c, d)); }
; DI float gelu_f(float x) { return 0.5f * x * (1.f + erff(x * 0.70710678118654752f)); }
;   template <int NT, int MT> DI void run(f32x4 (&acc)[NT][MT], int mb, int nb) const {
;     ...
;         if (n < 1024) {
;           st_bf4(abuf + (size_t)m * 1024 + n, v[0], v[1], v[2], v[3]);
;           float* dst = nullptr;
;           if (m < M_PROMPT) { int t = m & 8191; if (t >= 8177) dst = spp + ((size_t)((m >> 13) * 15 + (t - 8177))) * 1024 + n; }
;           else { int r = m - M_PROMPT; int s = r & 31; if (s >= 17) dst = sps + ((size_t)((r >> 5) * 15 + (s - 17))) * 1024 + n; }
;           if (dst) *(float4*)dst = make_float4(v[0], v[1], v[2], v[3]);
;         } else if (n < 3072) {
;           st_bf4(uvbuf + (size_t)m * 2048 + (n - 1024), gelu_f(v[0]), gelu_f(v[1]), gelu_f(v[2]), gelu_f(v[3]));
;         } else {
;           st_bf4(gatebuf + (size_t)m * 2048 + (n - 3072), silu_f(v[0]), silu_f(v[1]), silu_f(v[2]), silu_f(v[3]));
.LBB0_560:
	s_andn2_saveexec_b64 s[48:49], s[48:49]
	s_cbranch_execz .LBB0_578
	v_pk_mul_f32 v[130:131], v[42:43], v[170:171]
	v_pk_mul_f32 v[142:143], v[44:45], v[170:171]
	v_and_b32_e32 v132, 0x7fffffff, v130
	v_and_b32_e32 v144, 0x7fffffff, v142
	v_and_b32_e32 v133, 0x7fffffff, v131
	v_and_b32_e32 v145, 0x7fffffff, v143
	v_pk_fma_f32 v[134:135], v[132:133], v[174:175], v[176:177]
	v_pk_fma_f32 v[146:147], v[144:145], v[174:175], v[176:177]
	v_pk_fma_f32 v[134:135], v[132:133], v[134:135], v[178:179]
	v_pk_fma_f32 v[146:147], v[144:145], v[146:147], v[178:179]
	v_pk_fma_f32 v[134:135], v[132:133], v[134:135], v[180:181]
	v_pk_fma_f32 v[146:147], v[144:145], v[146:147], v[180:181]
	v_pk_fma_f32 v[134:135], v[132:133], v[134:135], v[186:187]
	v_pk_fma_f32 v[146:147], v[144:145], v[146:147], v[186:187]
	v_pk_fma_f32 v[134:135], v[132:133], v[134:135], v[188:189]
	v_pk_fma_f32 v[146:147], v[144:145], v[146:147], v[188:189]
	v_pk_fma_f32 v[134:135], v[132:133], v[134:135], v[190:191]
	v_pk_fma_f32 v[146:147], v[144:145], v[146:147], v[190:191]
	v_pk_fma_f32 v[134:135], v[132:133], v[134:135], v[132:133]
	v_pk_fma_f32 v[146:147], v[144:145], v[146:147], v[144:145]
	v_pk_mul_f32 v[134:135], v[134:135], v[172:173]
	v_pk_mul_f32 v[146:147], v[146:147], v[172:173]
	v_pk_mul_f32 v[136:137], v[130:131], v[130:131]
	v_pk_mul_f32 v[148:149], v[142:143], v[142:143]
	v_exp_f32_e32 v134, v134
	v_exp_f32_e32 v146, v146
	v_exp_f32_e32 v135, v135
	v_exp_f32_e32 v147, v147
	v_pk_fma_f32 v[138:139], v[136:137], v[192:193], v[194:195]
	v_pk_fma_f32 v[150:151], v[148:149], v[192:193], v[194:195]
	v_pk_fma_f32 v[138:139], v[136:137], v[138:139], v[196:197]
	v_pk_fma_f32 v[150:151], v[148:149], v[150:151], v[196:197]
	v_pk_fma_f32 v[138:139], v[136:137], v[138:139], v[224:225]
	v_pk_fma_f32 v[150:151], v[148:149], v[150:151], v[224:225]
	v_pk_fma_f32 v[138:139], v[136:137], v[138:139], v[226:227]
	v_pk_fma_f32 v[150:151], v[148:149], v[150:151], v[226:227]
	v_pk_fma_f32 v[138:139], v[136:137], v[138:139], v[228:229]
	v_pk_fma_f32 v[150:151], v[148:149], v[150:151], v[228:229]
	v_pk_fma_f32 v[134:135], v[134:135], v[234:235], v[230:231]
	v_pk_fma_f32 v[146:147], v[146:147], v[234:235], v[230:231]
	v_pk_fma_f32 v[138:139], v[132:133], v[138:139], v[132:133]
	v_pk_fma_f32 v[150:151], v[144:145], v[150:151], v[144:145]
	v_pk_mul_f32 v[140:141], v[42:43], v[232:233]
	v_pk_mul_f32 v[152:153], v[44:45], v[232:233]
	v_cmp_ngt_f32_e32 vcc, 1.0, v132
	v_cmp_ngt_f32_e64 s[8:9], 1.0, v133
	v_readlane_b32 s6, v252, 33
	v_readlane_b32 s7, v252, 34
	v_cndmask_b32_e32 v138, v138, v134, vcc
	v_cndmask_b32_e64 v139, v139, v135, s[8:9]
	v_cmp_ngt_f32_e32 vcc, 1.0, v144
	v_cmp_ngt_f32_e64 s[8:9], 1.0, v145
	v_bfi_b32 v138, s37, v138, v130
	v_bfi_b32 v139, s37, v139, v131
	v_cndmask_b32_e32 v150, v150, v146, vcc
	v_cndmask_b32_e64 v151, v151, v147, s[8:9]
	v_pk_add_f32 v[138:139], v[138:139], v[230:231]
	v_bfi_b32 v150, s37, v150, v142
	v_bfi_b32 v151, s37, v151, v143
	v_pk_add_f32 v[150:151], v[150:151], v[230:231]
	v_pk_mul_f32 v[138:139], v[140:141], v[138:139]
	v_lshl_add_u64 v[42:43], s[6:7], 0, v[46:47]
	v_pk_mul_f32 v[150:151], v[152:153], v[150:151]
	v_lshl_add_u64 v[42:43], v[182:183], 1, v[42:43]
	v_cvt_pk_bf16_f32 v44, v138, v139
	v_cvt_pk_bf16_f32 v45, v150, v151
	global_store_dwordx2 v[42:43], v[44:45], off offset:-2016

; DI float silu_f(float x) { return x * __builtin_amdgcn_rcpf(1.f + __expf(-x)); }
; DI void st_bf4(u16* p, float a, float b, float c, float d) { *(uint2*)p = make_uint2(pk2(a, b), pk2(c, d)); }
; DI float gelu_f(float x) { return 0.5f * x * (1.f + erff(x * 0.70710678118654752f)); }
;   template <int NT, int MT> DI void run(f32x4 (&acc)[NT][MT], int mb, int nb) const {
;     ...
;         if (n < 1024) {
;           st_bf4(abuf + (size_t)m * 1024 + n, v[0], v[1], v[2], v[3]);
;           float* dst = nullptr;
;           if (m < M_PROMPT) { int t = m & 8191; if (t >= 8177) dst = spp + ((size_t)((m >> 13) * 15 + (t - 8177))) * 1024 + n; }
;           else { int r = m - M_PROMPT; int s = r & 31; if (s >= 17) dst = sps + ((size_t)((r >> 5) * 15 + (s - 17))) * 1024 + n; }
;           if (dst) *(float4*)dst = make_float4(v[0], v[1], v[2], v[3]);
;         } else if (n < 3072) {
;           st_bf4(uvbuf + (size_t)m * 2048 + (n - 1024), gelu_f(v[0]), gelu_f(v[1]), gelu_f(v[2]), gelu_f(v[3]));
;         } else {
;           st_bf4(gatebuf + (size_t)m * 2048 + (n - 3072), silu_f(v[0]), silu_f(v[1]), silu_f(v[2]), silu_f(v[3]));
.LBB0_590:
	s_andn2_saveexec_b64 s[48:49], s[48:49]
	s_cbranch_execz .LBB0_608
	v_pk_mul_f32 v[130:131], v[38:39], v[170:171]
	v_pk_mul_f32 v[142:143], v[40:41], v[170:171]
	v_and_b32_e32 v132, 0x7fffffff, v130
	v_and_b32_e32 v144, 0x7fffffff, v142
	v_and_b32_e32 v133, 0x7fffffff, v131
	v_and_b32_e32 v145, 0x7fffffff, v143
	v_pk_fma_f32 v[134:135], v[132:133], v[174:175], v[176:177]
	v_pk_fma_f32 v[146:147], v[144:145], v[174:175], v[176:177]
	v_pk_fma_f32 v[134:135], v[132:133], v[134:135], v[178:179]
	v_pk_fma_f32 v[146:147], v[144:145], v[146:147], v[178:179]
	v_pk_fma_f32 v[134:135], v[132:133], v[134:135], v[180:181]
	v_pk_fma_f32 v[146:147], v[144:145], v[146:147], v[180:181]
	v_pk_fma_f32 v[134:135], v[132:133], v[134:135], v[186:187]
	v_pk_fma_f32 v[146:147], v[144:145], v[146:147], v[186:187]
	v_pk_fma_f32 v[134:135], v[132:133], v[134:135], v[188:189]
	v_pk_fma_f32 v[146:147], v[144:145], v[146:147], v[188:189]
	v_pk_fma_f32 v[134:135], v[132:133], v[134:135], v[190:191]
	v_pk_fma_f32 v[146:147], v[144:145], v[146:147], v[190:191]
	v_pk_fma_f32 v[134:135], v[132:133], v[134:135], v[132:133]
	v_pk_fma_f32 v[146:147], v[144:145], v[146:147], v[144:145]
	v_pk_mul_f32 v[134:135], v[134:135], v[172:173]
	v_pk_mul_f32 v[146:147], v[146:147], v[172:173]
	v_pk_mul_f32 v[136:137], v[130:131], v[130:131]
	v_pk_mul_f32 v[148:149], v[142:143], v[142:143]
	v_exp_f32_e32 v134, v134
	v_exp_f32_e32 v146, v146
	v_exp_f32_e32 v135, v135
	v_exp_f32_e32 v147, v147
	v_pk_fma_f32 v[138:139], v[136:137], v[192:193], v[194:195]
	v_pk_fma_f32 v[150:151], v[148:149], v[192:193], v[194:195]
	v_pk_fma_f32 v[138:139], v[136:137], v[138:139], v[196:197]
	v_pk_fma_f32 v[150:151], v[148:149], v[150:151], v[196:197]
	v_pk_fma_f32 v[138:139], v[136:137], v[138:139], v[224:225]
	v_pk_fma_f32 v[150:151], v[148:149], v[150:151], v[224:225]
	v_pk_fma_f32 v[138:139], v[136:137], v[138:139], v[226:227]
	v_pk_fma_f32 v[150:151], v[148:149], v[150:151], v[226:227]
	v_pk_fma_f32 v[138:139], v[136:137], v[138:139], v[228:229]
	v_pk_fma_f32 v[150:151], v[148:149], v[150:151], v[228:229]
	v_pk_fma_f32 v[134:135], v[134:135], v[234:235], v[230:231]
	v_pk_fma_f32 v[146:147], v[146:147], v[234:235], v[230:231]
	v_pk_fma_f32 v[138:139], v[132:133], v[138:139], v[132:133]
	v_pk_fma_f32 v[150:151], v[144:145], v[150:151], v[144:145]
	v_pk_mul_f32 v[140:141], v[38:39], v[232:233]
	v_pk_mul_f32 v[152:153], v[40:41], v[232:233]
	v_cmp_ngt_f32_e32 vcc, 1.0, v132
	v_cmp_ngt_f32_e64 s[8:9], 1.0, v133
	v_readlane_b32 s6, v252, 33
	v_readlane_b32 s7, v252, 34
	v_cndmask_b32_e32 v138, v138, v134, vcc
	v_cndmask_b32_e64 v139, v139, v135, s[8:9]
	v_cmp_ngt_f32_e32 vcc, 1.0, v144
	v_cmp_ngt_f32_e64 s[8:9], 1.0, v145
	v_bfi_b32 v138, s37, v138, v130
	v_bfi_b32 v139, s37, v139, v131
	v_cndmask_b32_e32 v150, v150, v146, vcc
	v_cndmask_b32_e64 v151, v151, v147, s[8:9]
	v_pk_add_f32 v[138:139], v[138:139], v[230:231]
	v_bfi_b32 v150, s37, v150, v142
	v_bfi_b32 v151, s37, v151, v143
	v_pk_add_f32 v[150:151], v[150:151], v[230:231]
	v_pk_mul_f32 v[138:139], v[140:141], v[138:139]
	v_lshl_add_u64 v[38:39], s[6:7], 0, v[42:43]
	v_pk_mul_f32 v[150:151], v[152:153], v[150:151]
	v_lshl_add_u64 v[38:39], v[182:183], 1, v[38:39]
	v_cvt_pk_bf16_f32 v40, v138, v139
	v_cvt_pk_bf16_f32 v41, v150, v151
	global_store_dwordx2 v[38:39], v[40:41], off offset:-2016

; DI float silu_f(float x) { return x * __builtin_amdgcn_rcpf(1.f + __expf(-x)); }
; DI void st_bf4(u16* p, float a, float b, float c, float d) { *(uint2*)p = make_uint2(pk2(a, b), pk2(c, d)); }
; DI float gelu_f(float x) { return 0.5f * x * (1.f + erff(x * 0.70710678118654752f)); }
;   template <int NT, int MT> DI void run(f32x4 (&acc)[NT][MT], int mb, int nb) const {
;     ...
;         if (n < 1024) {
;           st_bf4(abuf + (size_t)m * 1024 + n, v[0], v[1], v[2], v[3]);
;           float* dst = nullptr;
;           if (m < M_PROMPT) { int t = m & 8191; if (t >= 8177) dst = spp + ((size_t)((m >> 13) * 15 + (t - 8177))) * 1024 + n; }
;           else { int r = m - M_PROMPT; int s = r & 31; if (s >= 17) dst = sps + ((size_t)((r >> 5) * 15 + (s - 17))) * 1024 + n; }
;           if (dst) *(float4*)dst = make_float4(v[0], v[1], v[2], v[3]);
;         } else if (n < 3072) {
;           st_bf4(uvbuf + (size_t)m * 2048 + (n - 1024), gelu_f(v[0]), gelu_f(v[1]), gelu_f(v[2]), gelu_f(v[3]));
;         } else {
;           st_bf4(gatebuf + (size_t)m * 2048 + (n - 3072), silu_f(v[0]), silu_f(v[1]), silu_f(v[2]), silu_f(v[3]));
.LBB0_614:
	s_andn2_saveexec_b64 s[46:47], s[46:47]
	s_cbranch_execz .LBB0_632
	v_pk_mul_f32 v[130:131], v[34:35], v[170:171]
	v_pk_mul_f32 v[142:143], v[36:37], v[170:171]
	v_and_b32_e32 v132, 0x7fffffff, v130
	v_and_b32_e32 v144, 0x7fffffff, v142
	v_and_b32_e32 v133, 0x7fffffff, v131
	v_and_b32_e32 v145, 0x7fffffff, v143
	v_pk_fma_f32 v[134:135], v[132:133], v[174:175], v[176:177]
	v_pk_fma_f32 v[146:147], v[144:145], v[174:175], v[176:177]
	v_pk_fma_f32 v[134:135], v[132:133], v[134:135], v[178:179]
	v_pk_fma_f32 v[146:147], v[144:145], v[146:147], v[178:179]
	v_pk_fma_f32 v[134:135], v[132:133], v[134:135], v[180:181]
	v_pk_fma_f32 v[146:147], v[144:145], v[146:147], v[180:181]
	v_pk_fma_f32 v[134:135], v[132:133], v[134:135], v[186:187]
	v_pk_fma_f32 v[146:147], v[144:145], v[146:147], v[186:187]
	v_pk_fma_f32 v[134:135], v[132:133], v[134:135], v[188:189]
	v_pk_fma_f32 v[146:147], v[144:145], v[146:147], v[188:189]
	v_pk_fma_f32 v[134:135], v[132:133], v[134:135], v[190:191]
	v_pk_fma_f32 v[146:147], v[144:145], v[146:147], v[190:191]
	v_pk_fma_f32 v[134:135], v[132:133], v[134:135], v[132:133]
	v_pk_fma_f32 v[146:147], v[144:145], v[146:147], v[144:145]
	v_pk_mul_f32 v[134:135], v[134:135], v[172:173]
	v_pk_mul_f32 v[146:147], v[146:147], v[172:173]
	v_pk_mul_f32 v[136:137], v[130:131], v[130:131]
	v_pk_mul_f32 v[148:149], v[142:143], v[142:143]
	v_exp_f32_e32 v134, v134
	v_exp_f32_e32 v146, v146
	v_exp_f32_e32 v135, v135
	v_exp_f32_e32 v147, v147
	v_pk_fma_f32 v[138:139], v[136:137], v[192:193], v[194:195]
	v_pk_fma_f32 v[150:151], v[148:149], v[192:193], v[194:195]
	v_pk_fma_f32 v[138:139], v[136:137], v[138:139], v[196:197]
	v_pk_fma_f32 v[150:151], v[148:149], v[150:151], v[196:197]
	v_pk_fma_f32 v[138:139], v[136:137], v[138:139], v[224:225]
	v_pk_fma_f32 v[150:151], v[148:149], v[150:151], v[224:225]
	v_pk_fma_f32 v[138:139], v[136:137], v[138:139], v[226:227]
	v_pk_fma_f32 v[150:151], v[148:149], v[150:151], v[226:227]
	v_pk_fma_f32 v[138:139], v[136:137], v[138:139], v[228:229]
	v_pk_fma_f32 v[150:151], v[148:149], v[150:151], v[228:229]
	v_pk_fma_f32 v[134:135], v[134:135], v[234:235], v[230:231]
	v_pk_fma_f32 v[146:147], v[146:147], v[234:235], v[230:231]
	v_pk_fma_f32 v[138:139], v[132:133], v[138:139], v[132:133]
	v_pk_fma_f32 v[150:151], v[144:145], v[150:151], v[144:145]
	v_pk_mul_f32 v[140:141], v[34:35], v[232:233]
	v_pk_mul_f32 v[152:153], v[36:37], v[232:233]
	v_cmp_ngt_f32_e32 vcc, 1.0, v132
	v_cmp_ngt_f32_e64 s[8:9], 1.0, v133
	v_readlane_b32 s6, v252, 33
	v_readlane_b32 s7, v252, 34
	v_cndmask_b32_e32 v138, v138, v134, vcc
	v_cndmask_b32_e64 v139, v139, v135, s[8:9]
	v_cmp_ngt_f32_e32 vcc, 1.0, v144
	v_cmp_ngt_f32_e64 s[8:9], 1.0, v145
	v_bfi_b32 v138, s37, v138, v130
	v_bfi_b32 v139, s37, v139, v131
	v_cndmask_b32_e32 v150, v150, v146, vcc
	v_cndmask_b32_e64 v151, v151, v147, s[8:9]
	v_pk_add_f32 v[138:139], v[138:139], v[230:231]
	v_bfi_b32 v150, s37, v150, v142
	v_bfi_b32 v151, s37, v151, v143
	v_pk_add_f32 v[150:151], v[150:151], v[230:231]
	v_pk_mul_f32 v[138:139], v[140:141], v[138:139]
	v_lshl_add_u64 v[34:35], s[6:7], 0, v[38:39]
	v_pk_mul_f32 v[150:151], v[152:153], v[150:151]
	v_lshl_add_u64 v[34:35], v[182:183], 1, v[34:35]
	v_cvt_pk_bf16_f32 v36, v138, v139
	v_cvt_pk_bf16_f32 v37, v150, v151
	global_store_dwordx2 v[34:35], v[36:37], off offset:-2016

; DI float silu_f(float x) { return x * __builtin_amdgcn_rcpf(1.f + __expf(-x)); }
; DI void st_bf4(u16* p, float a, float b, float c, float d) { *(uint2*)p = make_uint2(pk2(a, b), pk2(c, d)); }
; DI float gelu_f(float x) { return 0.5f * x * (1.f + erff(x * 0.70710678118654752f)); }
;   template <int NT, int MT> DI void run(f32x4 (&acc)[NT][MT], int mb, int nb) const {
;     ...
;         if (n < 1024) {
;           st_bf4(abuf + (size_t)m * 1024 + n, v[0], v[1], v[2], v[3]);
;           float* dst = nullptr;
;           if (m < M_PROMPT) { int t = m & 8191; if (t >= 8177) dst = spp + ((size_t)((m >> 13) * 15 + (t - 8177))) * 1024 + n; }
;           else { int r = m - M_PROMPT; int s = r & 31; if (s >= 17) dst = sps + ((size_t)((r >> 5) * 15 + (s - 17))) * 1024 + n; }
;           if (dst) *(float4*)dst = make_float4(v[0], v[1], v[2], v[3]);
;         } else if (n < 3072) {
;           st_bf4(uvbuf + (size_t)m * 2048 + (n - 1024), gelu_f(v[0]), gelu_f(v[1]), gelu_f(v[2]), gelu_f(v[3]));
;         } else {
;           st_bf4(gatebuf + (size_t)m * 2048 + (n - 3072), silu_f(v[0]), silu_f(v[1]), silu_f(v[2]), silu_f(v[3]));
.LBB0_644:
	s_andn2_saveexec_b64 s[48:49], s[48:49]
	s_cbranch_execz .LBB0_662
	v_pk_mul_f32 v[130:131], v[30:31], v[170:171]
	v_pk_mul_f32 v[142:143], v[32:33], v[170:171]
	v_and_b32_e32 v132, 0x7fffffff, v130
	v_and_b32_e32 v144, 0x7fffffff, v142
	v_and_b32_e32 v133, 0x7fffffff, v131
	v_and_b32_e32 v145, 0x7fffffff, v143
	v_pk_fma_f32 v[134:135], v[132:133], v[174:175], v[176:177]
	v_pk_fma_f32 v[146:147], v[144:145], v[174:175], v[176:177]
	v_pk_fma_f32 v[134:135], v[132:133], v[134:135], v[178:179]
	v_pk_fma_f32 v[146:147], v[144:145], v[146:147], v[178:179]
	v_pk_fma_f32 v[134:135], v[132:133], v[134:135], v[180:181]
	v_pk_fma_f32 v[146:147], v[144:145], v[146:147], v[180:181]
	v_pk_fma_f32 v[134:135], v[132:133], v[134:135], v[186:187]
	v_pk_fma_f32 v[146:147], v[144:145], v[146:147], v[186:187]
	v_pk_fma_f32 v[134:135], v[132:133], v[134:135], v[188:189]
	v_pk_fma_f32 v[146:147], v[144:145], v[146:147], v[188:189]
	v_pk_fma_f32 v[134:135], v[132:133], v[134:135], v[190:191]
	v_pk_fma_f32 v[146:147], v[144:145], v[146:147], v[190:191]
	v_pk_fma_f32 v[134:135], v[132:133], v[134:135], v[132:133]
	v_pk_fma_f32 v[146:147], v[144:145], v[146:147], v[144:145]
	v_pk_mul_f32 v[134:135], v[134:135], v[172:173]
	v_pk_mul_f32 v[146:147], v[146:147], v[172:173]
	v_pk_mul_f32 v[136:137], v[130:131], v[130:131]
	v_pk_mul_f32 v[148:149], v[142:143], v[142:143]
	v_exp_f32_e32 v134, v134
	v_exp_f32_e32 v146, v146
	v_exp_f32_e32 v135, v135
	v_exp_f32_e32 v147, v147
	v_pk_fma_f32 v[138:139], v[136:137], v[192:193], v[194:195]
	v_pk_fma_f32 v[150:151], v[148:149], v[192:193], v[194:195]
	v_pk_fma_f32 v[138:139], v[136:137], v[138:139], v[196:197]
	v_pk_fma_f32 v[150:151], v[148:149], v[150:151], v[196:197]
	v_pk_fma_f32 v[138:139], v[136:137], v[138:139], v[224:225]
	v_pk_fma_f32 v[150:151], v[148:149], v[150:151], v[224:225]
	v_pk_fma_f32 v[138:139], v[136:137], v[138:139], v[226:227]
	v_pk_fma_f32 v[150:151], v[148:149], v[150:151], v[226:227]
	v_pk_fma_f32 v[138:139], v[136:137], v[138:139], v[228:229]
	v_pk_fma_f32 v[150:151], v[148:149], v[150:151], v[228:229]
	v_pk_fma_f32 v[134:135], v[134:135], v[234:235], v[230:231]
	v_pk_fma_f32 v[146:147], v[146:147], v[234:235], v[230:231]
	v_pk_fma_f32 v[138:139], v[132:133], v[138:139], v[132:133]
	v_pk_fma_f32 v[150:151], v[144:145], v[150:151], v[144:145]
	v_pk_mul_f32 v[140:141], v[30:31], v[232:233]
	v_pk_mul_f32 v[152:153], v[32:33], v[232:233]
	v_cmp_ngt_f32_e32 vcc, 1.0, v132
	v_cmp_ngt_f32_e64 s[8:9], 1.0, v133
	v_readlane_b32 s6, v252, 33
	v_readlane_b32 s7, v252, 34
	v_cndmask_b32_e32 v138, v138, v134, vcc
	v_cndmask_b32_e64 v139, v139, v135, s[8:9]
	v_cmp_ngt_f32_e32 vcc, 1.0, v144
	v_cmp_ngt_f32_e64 s[8:9], 1.0, v145
	v_bfi_b32 v138, s37, v138, v130
	v_bfi_b32 v139, s37, v139, v131
	v_cndmask_b32_e32 v150, v150, v146, vcc
	v_cndmask_b32_e64 v151, v151, v147, s[8:9]
	v_pk_add_f32 v[138:139], v[138:139], v[230:231]
	v_bfi_b32 v150, s37, v150, v142
	v_bfi_b32 v151, s37, v151, v143
	v_pk_add_f32 v[150:151], v[150:151], v[230:231]
	v_pk_mul_f32 v[138:139], v[140:141], v[138:139]
	v_lshl_add_u64 v[30:31], s[6:7], 0, v[34:35]
	v_pk_mul_f32 v[150:151], v[152:153], v[150:151]
	v_lshl_add_u64 v[30:31], v[182:183], 1, v[30:31]
	v_cvt_pk_bf16_f32 v32, v138, v139
	v_cvt_pk_bf16_f32 v33, v150, v151
	global_store_dwordx2 v[30:31], v[32:33], off offset:-1984

; DI float silu_f(float x) { return x * __builtin_amdgcn_rcpf(1.f + __expf(-x)); }
; DI void st_bf4(u16* p, float a, float b, float c, float d) { *(uint2*)p = make_uint2(pk2(a, b), pk2(c, d)); }
; DI float gelu_f(float x) { return 0.5f * x * (1.f + erff(x * 0.70710678118654752f)); }
;   template <int NT, int MT> DI void run(f32x4 (&acc)[NT][MT], int mb, int nb) const {
;     ...
;         if (n < 1024) {
;           st_bf4(abuf + (size_t)m * 1024 + n, v[0], v[1], v[2], v[3]);
;           float* dst = nullptr;
;           if (m < M_PROMPT) { int t = m & 8191; if (t >= 8177) dst = spp + ((size_t)((m >> 13) * 15 + (t - 8177))) * 1024 + n; }
;           else { int r = m - M_PROMPT; int s = r & 31; if (s >= 17) dst = sps + ((size_t)((r >> 5) * 15 + (s - 17))) * 1024 + n; }
;           if (dst) *(float4*)dst = make_float4(v[0], v[1], v[2], v[3]);
;         } else if (n < 3072) {
;           st_bf4(uvbuf + (size_t)m * 2048 + (n - 1024), gelu_f(v[0]), gelu_f(v[1]), gelu_f(v[2]), gelu_f(v[3]));
;         } else {
;           st_bf4(gatebuf + (size_t)m * 2048 + (n - 3072), silu_f(v[0]), silu_f(v[1]), silu_f(v[2]), silu_f(v[3]));
.LBB0_668:
	s_andn2_saveexec_b64 s[48:49], s[48:49]
	s_cbranch_execz .LBB0_686
	v_pk_mul_f32 v[130:131], v[26:27], v[170:171]
	v_pk_mul_f32 v[142:143], v[28:29], v[170:171]
	v_and_b32_e32 v132, 0x7fffffff, v130
	v_and_b32_e32 v144, 0x7fffffff, v142
	v_and_b32_e32 v133, 0x7fffffff, v131
	v_and_b32_e32 v145, 0x7fffffff, v143
	v_pk_fma_f32 v[134:135], v[132:133], v[174:175], v[176:177]
	v_pk_fma_f32 v[146:147], v[144:145], v[174:175], v[176:177]
	v_pk_fma_f32 v[134:135], v[132:133], v[134:135], v[178:179]
	v_pk_fma_f32 v[146:147], v[144:145], v[146:147], v[178:179]
	v_pk_fma_f32 v[134:135], v[132:133], v[134:135], v[180:181]
	v_pk_fma_f32 v[146:147], v[144:145], v[146:147], v[180:181]
	v_pk_fma_f32 v[134:135], v[132:133], v[134:135], v[186:187]
	v_pk_fma_f32 v[146:147], v[144:145], v[146:147], v[186:187]
	v_pk_fma_f32 v[134:135], v[132:133], v[134:135], v[188:189]
	v_pk_fma_f32 v[146:147], v[144:145], v[146:147], v[188:189]
	v_pk_fma_f32 v[134:135], v[132:133], v[134:135], v[190:191]
	v_pk_fma_f32 v[146:147], v[144:145], v[146:147], v[190:191]
	v_pk_fma_f32 v[134:135], v[132:133], v[134:135], v[132:133]
	v_pk_fma_f32 v[146:147], v[144:145], v[146:147], v[144:145]
	v_pk_mul_f32 v[134:135], v[134:135], v[172:173]
	v_pk_mul_f32 v[146:147], v[146:147], v[172:173]
	v_pk_mul_f32 v[136:137], v[130:131], v[130:131]
	v_pk_mul_f32 v[148:149], v[142:143], v[142:143]
	v_exp_f32_e32 v134, v134
	v_exp_f32_e32 v146, v146
	v_exp_f32_e32 v135, v135
	v_exp_f32_e32 v147, v147
	v_pk_fma_f32 v[138:139], v[136:137], v[192:193], v[194:195]
	v_pk_fma_f32 v[150:151], v[148:149], v[192:193], v[194:195]
	v_pk_fma_f32 v[138:139], v[136:137], v[138:139], v[196:197]
	v_pk_fma_f32 v[150:151], v[148:149], v[150:151], v[196:197]
	v_pk_fma_f32 v[138:139], v[136:137], v[138:139], v[224:225]
	v_pk_fma_f32 v[150:151], v[148:149], v[150:151], v[224:225]
	v_pk_fma_f32 v[138:139], v[136:137], v[138:139], v[226:227]
	v_pk_fma_f32 v[150:151], v[148:149], v[150:151], v[226:227]
	v_pk_fma_f32 v[138:139], v[136:137], v[138:139], v[228:229]
	v_pk_fma_f32 v[150:151], v[148:149], v[150:151], v[228:229]
	v_pk_fma_f32 v[134:135], v[134:135], v[234:235], v[230:231]
	v_pk_fma_f32 v[146:147], v[146:147], v[234:235], v[230:231]
	v_pk_fma_f32 v[138:139], v[132:133], v[138:139], v[132:133]
	v_pk_fma_f32 v[150:151], v[144:145], v[150:151], v[144:145]
	v_pk_mul_f32 v[140:141], v[26:27], v[232:233]
	v_pk_mul_f32 v[152:153], v[28:29], v[232:233]
	v_cmp_ngt_f32_e32 vcc, 1.0, v132
	v_cmp_ngt_f32_e64 s[8:9], 1.0, v133
	v_readlane_b32 s6, v252, 33
	v_readlane_b32 s7, v252, 34
	v_cndmask_b32_e32 v138, v138, v134, vcc
	v_cndmask_b32_e64 v139, v139, v135, s[8:9]
	v_cmp_ngt_f32_e32 vcc, 1.0, v144
	v_cmp_ngt_f32_e64 s[8:9], 1.0, v145
	v_bfi_b32 v138, s37, v138, v130
	v_bfi_b32 v139, s37, v139, v131
	v_cndmask_b32_e32 v150, v150, v146, vcc
	v_cndmask_b32_e64 v151, v151, v147, s[8:9]
	v_pk_add_f32 v[138:139], v[138:139], v[230:231]
	v_bfi_b32 v150, s37, v150, v142
	v_bfi_b32 v151, s37, v151, v143
	v_pk_add_f32 v[150:151], v[150:151], v[230:231]
	v_pk_mul_f32 v[138:139], v[140:141], v[138:139]
	v_lshl_add_u64 v[26:27], s[6:7], 0, v[30:31]
	v_pk_mul_f32 v[150:151], v[152:153], v[150:151]
	v_lshl_add_u64 v[26:27], v[182:183], 1, v[26:27]
	v_cvt_pk_bf16_f32 v28, v138, v139
	v_cvt_pk_bf16_f32 v29, v150, v151
	global_store_dwordx2 v[26:27], v[28:29], off offset:-1984

; DI void st_bf4(u16* p, float a, float b, float c, float d) { *(uint2*)p = make_uint2(pk2(a, b), pk2(c, d)); }
; DI float gelu_f(float x) { return 0.5f * x * (1.f + erff(x * 0.70710678118654752f)); }
;   template <int NT, int MT> DI void run(f32x4 (&acc)[NT][MT], int mb, int nb) const {
;     ...
;         } else if (n < 3072) {
;           st_bf4(uvbuf + (size_t)m * 2048 + (n - 1024), gelu_f(v[0]), gelu_f(v[1]), gelu_f(v[2]), gelu_f(v[3]));
.LBB0_698:
	s_andn2_saveexec_b64 s[48:49], s[48:49]
	s_cbranch_execz .LBB0_716
	v_pk_mul_f32 v[130:131], v[22:23], v[170:171]
	v_pk_mul_f32 v[142:143], v[24:25], v[170:171]
	v_and_b32_e32 v132, 0x7fffffff, v130
	v_and_b32_e32 v144, 0x7fffffff, v142
	v_and_b32_e32 v133, 0x7fffffff, v131
	v_and_b32_e32 v145, 0x7fffffff, v143
	v_pk_fma_f32 v[134:135], v[132:133], v[174:175], v[176:177]
	v_pk_fma_f32 v[146:147], v[144:145], v[174:175], v[176:177]
	v_pk_fma_f32 v[134:135], v[132:133], v[134:135], v[178:179]
	v_pk_fma_f32 v[146:147], v[144:145], v[146:147], v[178:179]
	v_pk_fma_f32 v[134:135], v[132:133], v[134:135], v[180:181]
	v_pk_fma_f32 v[146:147], v[144:145], v[146:147], v[180:181]
	v_pk_fma_f32 v[134:135], v[132:133], v[134:135], v[186:187]
	v_pk_fma_f32 v[146:147], v[144:145], v[146:147], v[186:187]
	v_pk_fma_f32 v[134:135], v[132:133], v[134:135], v[188:189]
	v_pk_fma_f32 v[146:147], v[144:145], v[146:147], v[188:189]
	v_pk_fma_f32 v[134:135], v[132:133], v[134:135], v[190:191]
	v_pk_fma_f32 v[146:147], v[144:145], v[146:147], v[190:191]
	v_pk_fma_f32 v[134:135], v[132:133], v[134:135], v[132:133]
	v_pk_fma_f32 v[146:147], v[144:145], v[146:147], v[144:145]
	v_pk_mul_f32 v[134:135], v[134:135], v[172:173]
	v_pk_mul_f32 v[146:147], v[146:147], v[172:173]
	v_pk_mul_f32 v[136:137], v[130:131], v[130:131]
	v_pk_mul_f32 v[148:149], v[142:143], v[142:143]
	v_exp_f32_e32 v134, v134
	v_exp_f32_e32 v146, v146
	v_exp_f32_e32 v135, v135
	v_exp_f32_e32 v147, v147
	v_pk_fma_f32 v[138:139], v[136:137], v[192:193], v[194:195]
	v_pk_fma_f32 v[150:151], v[148:149], v[192:193], v[194:195]
	v_pk_fma_f32 v[138:139], v[136:137], v[138:139], v[196:197]
	v_pk_fma_f32 v[150:151], v[148:149], v[150:151], v[196:197]
	v_pk_fma_f32 v[138:139], v[136:137], v[138:139], v[224:225]
	v_pk_fma_f32 v[150:151], v[148:149], v[150:151], v[224:225]
	v_pk_fma_f32 v[138:139], v[136:137], v[138:139], v[226:227]
	v_pk_fma_f32 v[150:151], v[148:149], v[150:151], v[226:227]
	v_pk_fma_f32 v[138:139], v[136:137], v[138:139], v[228:229]
	v_pk_fma_f32 v[150:151], v[148:149], v[150:151], v[228:229]
	v_pk_fma_f32 v[134:135], v[134:135], v[234:235], v[230:231]
	v_pk_fma_f32 v[146:147], v[146:147], v[234:235], v[230:231]
	v_pk_fma_f32 v[138:139], v[132:133], v[138:139], v[132:133]
	v_pk_fma_f32 v[150:151], v[144:145], v[150:151], v[144:145]
	v_pk_mul_f32 v[140:141], v[22:23], v[232:233]
	v_pk_mul_f32 v[152:153], v[24:25], v[232:233]
	v_cmp_ngt_f32_e32 vcc, 1.0, v132
	v_cmp_ngt_f32_e64 s[8:9], 1.0, v133
	v_readlane_b32 s6, v252, 33
	v_readlane_b32 s7, v252, 34
	v_cndmask_b32_e32 v138, v138, v134, vcc
	v_cndmask_b32_e64 v139, v139, v135, s[8:9]
	v_cmp_ngt_f32_e32 vcc, 1.0, v144
	v_cmp_ngt_f32_e64 s[8:9], 1.0, v145
	v_bfi_b32 v138, s37, v138, v130
	v_bfi_b32 v139, s37, v139, v131
	v_cndmask_b32_e32 v150, v150, v146, vcc
	v_cndmask_b32_e64 v151, v151, v147, s[8:9]
	v_pk_add_f32 v[138:139], v[138:139], v[230:231]
	v_bfi_b32 v150, s37, v150, v142
	v_bfi_b32 v151, s37, v151, v143
	v_pk_add_f32 v[150:151], v[150:151], v[230:231]
	v_pk_mul_f32 v[138:139], v[140:141], v[138:139]
	v_lshl_add_u64 v[22:23], s[6:7], 0, v[26:27]
	v_pk_mul_f32 v[150:151], v[152:153], v[150:151]
	v_lshl_add_u64 v[22:23], v[182:183], 1, v[22:23]
	v_cvt_pk_bf16_f32 v24, v138, v139
	v_cvt_pk_bf16_f32 v25, v150, v151
	global_store_dwordx2 v[22:23], v[24:25], off offset:-1984

; DI void st_bf4(u16* p, float a, float b, float c, float d) { *(uint2*)p = make_uint2(pk2(a, b), pk2(c, d)); }
; DI float gelu_f(float x) { return 0.5f * x * (1.f + erff(x * 0.70710678118654752f)); }
;   template <int NT, int MT> DI void run(f32x4 (&acc)[NT][MT], int mb, int nb) const {
;     ...
;         } else if (n < 3072) {
;           st_bf4(uvbuf + (size_t)m * 2048 + (n - 1024), gelu_f(v[0]), gelu_f(v[1]), gelu_f(v[2]), gelu_f(v[3]));
.LBB0_722:
	s_andn2_saveexec_b64 s[46:47], s[46:47]
	s_cbranch_execz .LBB0_740
	v_pk_mul_f32 v[130:131], v[18:19], v[170:171]
	v_pk_mul_f32 v[142:143], v[20:21], v[170:171]
	v_and_b32_e32 v132, 0x7fffffff, v130
	v_and_b32_e32 v144, 0x7fffffff, v142
	v_and_b32_e32 v133, 0x7fffffff, v131
	v_and_b32_e32 v145, 0x7fffffff, v143
	v_pk_fma_f32 v[134:135], v[132:133], v[174:175], v[176:177]
	v_pk_fma_f32 v[146:147], v[144:145], v[174:175], v[176:177]
	v_pk_fma_f32 v[134:135], v[132:133], v[134:135], v[178:179]
	v_pk_fma_f32 v[146:147], v[144:145], v[146:147], v[178:179]
	v_pk_fma_f32 v[134:135], v[132:133], v[134:135], v[180:181]
	v_pk_fma_f32 v[146:147], v[144:145], v[146:147], v[180:181]
	v_pk_fma_f32 v[134:135], v[132:133], v[134:135], v[186:187]
	v_pk_fma_f32 v[146:147], v[144:145], v[146:147], v[186:187]
	v_pk_fma_f32 v[134:135], v[132:133], v[134:135], v[188:189]
	v_pk_fma_f32 v[146:147], v[144:145], v[146:147], v[188:189]
	v_pk_fma_f32 v[134:135], v[132:133], v[134:135], v[190:191]
	v_pk_fma_f32 v[146:147], v[144:145], v[146:147], v[190:191]
	v_pk_fma_f32 v[134:135], v[132:133], v[134:135], v[132:133]
	v_pk_fma_f32 v[146:147], v[144:145], v[146:147], v[144:145]
	v_pk_mul_f32 v[134:135], v[134:135], v[172:173]
	v_pk_mul_f32 v[146:147], v[146:147], v[172:173]
	v_pk_mul_f32 v[136:137], v[130:131], v[130:131]
	v_pk_mul_f32 v[148:149], v[142:143], v[142:143]
	v_exp_f32_e32 v134, v134
	v_exp_f32_e32 v146, v146
	v_exp_f32_e32 v135, v135
	v_exp_f32_e32 v147, v147
	v_pk_fma_f32 v[138:139], v[136:137], v[192:193], v[194:195]
	v_pk_fma_f32 v[150:151], v[148:149], v[192:193], v[194:195]
	v_pk_fma_f32 v[138:139], v[136:137], v[138:139], v[196:197]
	v_pk_fma_f32 v[150:151], v[148:149], v[150:151], v[196:197]
	v_pk_fma_f32 v[138:139], v[136:137], v[138:139], v[224:225]
	v_pk_fma_f32 v[150:151], v[148:149], v[150:151], v[224:225]
	v_pk_fma_f32 v[138:139], v[136:137], v[138:139], v[226:227]
	v_pk_fma_f32 v[150:151], v[148:149], v[150:151], v[226:227]
	v_pk_fma_f32 v[138:139], v[136:137], v[138:139], v[228:229]
	v_pk_fma_f32 v[150:151], v[148:149], v[150:151], v[228:229]
	v_pk_fma_f32 v[134:135], v[134:135], v[234:235], v[230:231]
	v_pk_fma_f32 v[146:147], v[146:147], v[234:235], v[230:231]
	v_pk_fma_f32 v[138:139], v[132:133], v[138:139], v[132:133]
	v_pk_fma_f32 v[150:151], v[144:145], v[150:151], v[144:145]
	v_pk_mul_f32 v[140:141], v[18:19], v[232:233]
	v_pk_mul_f32 v[152:153], v[20:21], v[232:233]
	v_cmp_ngt_f32_e32 vcc, 1.0, v132
	v_cmp_ngt_f32_e64 s[8:9], 1.0, v133
	v_readlane_b32 s6, v252, 33
	v_readlane_b32 s7, v252, 34
	v_cndmask_b32_e32 v138, v138, v134, vcc
	v_cndmask_b32_e64 v139, v139, v135, s[8:9]
	v_cmp_ngt_f32_e32 vcc, 1.0, v144
	v_cmp_ngt_f32_e64 s[8:9], 1.0, v145
	v_bfi_b32 v138, s37, v138, v130
	v_bfi_b32 v139, s37, v139, v131
	v_cndmask_b32_e32 v150, v150, v146, vcc
	v_cndmask_b32_e64 v151, v151, v147, s[8:9]
	v_pk_add_f32 v[138:139], v[138:139], v[230:231]
	v_bfi_b32 v150, s37, v150, v142
	v_bfi_b32 v151, s37, v151, v143
	v_pk_add_f32 v[150:151], v[150:151], v[230:231]
	v_pk_mul_f32 v[138:139], v[140:141], v[138:139]
	v_lshl_add_u64 v[18:19], s[6:7], 0, v[22:23]
	v_pk_mul_f32 v[150:151], v[152:153], v[150:151]
	v_lshl_add_u64 v[18:19], v[182:183], 1, v[18:19]
	v_cvt_pk_bf16_f32 v20, v138, v139
	v_cvt_pk_bf16_f32 v21, v150, v151
	global_store_dwordx2 v[18:19], v[20:21], off offset:-1984

; DI void st_bf4(u16* p, float a, float b, float c, float d) { *(uint2*)p = make_uint2(pk2(a, b), pk2(c, d)); }
; DI float gelu_f(float x) { return 0.5f * x * (1.f + erff(x * 0.70710678118654752f)); }
;   template <int NT, int MT> DI void run(f32x4 (&acc)[NT][MT], int mb, int nb) const {
;     ...
;         } else if (n < 3072) {
;           st_bf4(uvbuf + (size_t)m * 2048 + (n - 1024), gelu_f(v[0]), gelu_f(v[1]), gelu_f(v[2]), gelu_f(v[3]));
.LBB0_752:
	s_andn2_saveexec_b64 s[48:49], s[48:49]
	s_cbranch_execz .LBB0_770
	v_pk_mul_f32 v[130:131], v[14:15], v[170:171]
	v_pk_mul_f32 v[142:143], v[16:17], v[170:171]
	v_and_b32_e32 v132, 0x7fffffff, v130
	v_and_b32_e32 v144, 0x7fffffff, v142
	v_and_b32_e32 v133, 0x7fffffff, v131
	v_and_b32_e32 v145, 0x7fffffff, v143
	v_pk_fma_f32 v[134:135], v[132:133], v[174:175], v[176:177]
	v_pk_fma_f32 v[146:147], v[144:145], v[174:175], v[176:177]
	v_pk_fma_f32 v[134:135], v[132:133], v[134:135], v[178:179]
	v_pk_fma_f32 v[146:147], v[144:145], v[146:147], v[178:179]
	v_pk_fma_f32 v[134:135], v[132:133], v[134:135], v[180:181]
	v_pk_fma_f32 v[146:147], v[144:145], v[146:147], v[180:181]
	v_pk_fma_f32 v[134:135], v[132:133], v[134:135], v[186:187]
	v_pk_fma_f32 v[146:147], v[144:145], v[146:147], v[186:187]
	v_pk_fma_f32 v[134:135], v[132:133], v[134:135], v[188:189]
	v_pk_fma_f32 v[146:147], v[144:145], v[146:147], v[188:189]
	v_pk_fma_f32 v[134:135], v[132:133], v[134:135], v[190:191]
	v_pk_fma_f32 v[146:147], v[144:145], v[146:147], v[190:191]
	v_pk_fma_f32 v[134:135], v[132:133], v[134:135], v[132:133]
	v_pk_fma_f32 v[146:147], v[144:145], v[146:147], v[144:145]
	v_pk_mul_f32 v[134:135], v[134:135], v[172:173]
	v_pk_mul_f32 v[146:147], v[146:147], v[172:173]
	v_pk_mul_f32 v[136:137], v[130:131], v[130:131]
	v_pk_mul_f32 v[148:149], v[142:143], v[142:143]
	v_exp_f32_e32 v134, v134
	v_exp_f32_e32 v146, v146
	v_exp_f32_e32 v135, v135
	v_exp_f32_e32 v147, v147
	v_pk_fma_f32 v[138:139], v[136:137], v[192:193], v[194:195]
	v_pk_fma_f32 v[150:151], v[148:149], v[192:193], v[194:195]
	v_pk_fma_f32 v[138:139], v[136:137], v[138:139], v[196:197]
	v_pk_fma_f32 v[150:151], v[148:149], v[150:151], v[196:197]
	v_pk_fma_f32 v[138:139], v[136:137], v[138:139], v[224:225]
	v_pk_fma_f32 v[150:151], v[148:149], v[150:151], v[224:225]
	v_pk_fma_f32 v[138:139], v[136:137], v[138:139], v[226:227]
	v_pk_fma_f32 v[150:151], v[148:149], v[150:151], v[226:227]
	v_pk_fma_f32 v[138:139], v[136:137], v[138:139], v[228:229]
	v_pk_fma_f32 v[150:151], v[148:149], v[150:151], v[228:229]
	v_pk_fma_f32 v[134:135], v[134:135], v[234:235], v[230:231]
	v_pk_fma_f32 v[146:147], v[146:147], v[234:235], v[230:231]
	v_pk_fma_f32 v[138:139], v[132:133], v[138:139], v[132:133]
	v_pk_fma_f32 v[150:151], v[144:145], v[150:151], v[144:145]
	v_pk_mul_f32 v[140:141], v[14:15], v[232:233]
	v_pk_mul_f32 v[152:153], v[16:17], v[232:233]
	v_cmp_ngt_f32_e32 vcc, 1.0, v132
	v_cmp_ngt_f32_e64 s[8:9], 1.0, v133
	v_readlane_b32 s6, v252, 33
	v_readlane_b32 s7, v252, 34
	v_cndmask_b32_e32 v138, v138, v134, vcc
	v_cndmask_b32_e64 v139, v139, v135, s[8:9]
	v_cmp_ngt_f32_e32 vcc, 1.0, v144
	v_cmp_ngt_f32_e64 s[8:9], 1.0, v145
	v_bfi_b32 v138, s37, v138, v130
	v_bfi_b32 v139, s37, v139, v131
	v_cndmask_b32_e32 v150, v150, v146, vcc
	v_cndmask_b32_e64 v151, v151, v147, s[8:9]
	v_pk_add_f32 v[138:139], v[138:139], v[230:231]
	v_bfi_b32 v150, s37, v150, v142
	v_bfi_b32 v151, s37, v151, v143
	v_pk_add_f32 v[150:151], v[150:151], v[230:231]
	v_pk_mul_f32 v[138:139], v[140:141], v[138:139]
	v_lshl_add_u64 v[14:15], s[6:7], 0, v[18:19]
	v_pk_mul_f32 v[150:151], v[152:153], v[150:151]
	v_lshl_add_u64 v[14:15], v[182:183], 1, v[14:15]
	v_cvt_pk_bf16_f32 v16, v138, v139
	v_cvt_pk_bf16_f32 v17, v150, v151
	global_store_dwordx2 v[14:15], v[16:17], off offset:-1952

; DI void st_bf4(u16* p, float a, float b, float c, float d) { *(uint2*)p = make_uint2(pk2(a, b), pk2(c, d)); }
; DI float gelu_f(float x) { return 0.5f * x * (1.f + erff(x * 0.70710678118654752f)); }
;   template <int NT, int MT> DI void run(f32x4 (&acc)[NT][MT], int mb, int nb) const {
;     ...
;         } else if (n < 3072) {
;           st_bf4(uvbuf + (size_t)m * 2048 + (n - 1024), gelu_f(v[0]), gelu_f(v[1]), gelu_f(v[2]), gelu_f(v[3]));
.LBB0_776:
	s_andn2_saveexec_b64 s[48:49], s[48:49]
	s_cbranch_execz .LBB0_794
	v_pk_mul_f32 v[130:131], v[10:11], v[170:171]
	v_pk_mul_f32 v[142:143], v[12:13], v[170:171]
	v_and_b32_e32 v132, 0x7fffffff, v130
	v_and_b32_e32 v144, 0x7fffffff, v142
	v_and_b32_e32 v133, 0x7fffffff, v131
	v_and_b32_e32 v145, 0x7fffffff, v143
	v_pk_fma_f32 v[134:135], v[132:133], v[174:175], v[176:177]
	v_pk_fma_f32 v[146:147], v[144:145], v[174:175], v[176:177]
	v_pk_fma_f32 v[134:135], v[132:133], v[134:135], v[178:179]
	v_pk_fma_f32 v[146:147], v[144:145], v[146:147], v[178:179]
	v_pk_fma_f32 v[134:135], v[132:133], v[134:135], v[180:181]
	v_pk_fma_f32 v[146:147], v[144:145], v[146:147], v[180:181]
	v_pk_fma_f32 v[134:135], v[132:133], v[134:135], v[186:187]
	v_pk_fma_f32 v[146:147], v[144:145], v[146:147], v[186:187]
	v_pk_fma_f32 v[134:135], v[132:133], v[134:135], v[188:189]
	v_pk_fma_f32 v[146:147], v[144:145], v[146:147], v[188:189]
	v_pk_fma_f32 v[134:135], v[132:133], v[134:135], v[190:191]
	v_pk_fma_f32 v[146:147], v[144:145], v[146:147], v[190:191]
	v_pk_fma_f32 v[134:135], v[132:133], v[134:135], v[132:133]
	v_pk_fma_f32 v[146:147], v[144:145], v[146:147], v[144:145]
	v_pk_mul_f32 v[134:135], v[134:135], v[172:173]
	v_pk_mul_f32 v[146:147], v[146:147], v[172:173]
	v_pk_mul_f32 v[136:137], v[130:131], v[130:131]
	v_pk_mul_f32 v[148:149], v[142:143], v[142:143]
	v_exp_f32_e32 v134, v134
	v_exp_f32_e32 v146, v146
	v_exp_f32_e32 v135, v135
	v_exp_f32_e32 v147, v147
	v_pk_fma_f32 v[138:139], v[136:137], v[192:193], v[194:195]
	v_pk_fma_f32 v[150:151], v[148:149], v[192:193], v[194:195]
	v_pk_fma_f32 v[138:139], v[136:137], v[138:139], v[196:197]
	v_pk_fma_f32 v[150:151], v[148:149], v[150:151], v[196:197]
	v_pk_fma_f32 v[138:139], v[136:137], v[138:139], v[224:225]
	v_pk_fma_f32 v[150:151], v[148:149], v[150:151], v[224:225]
	v_pk_fma_f32 v[138:139], v[136:137], v[138:139], v[226:227]
	v_pk_fma_f32 v[150:151], v[148:149], v[150:151], v[226:227]
	v_pk_fma_f32 v[138:139], v[136:137], v[138:139], v[228:229]
	v_pk_fma_f32 v[150:151], v[148:149], v[150:151], v[228:229]
	v_pk_fma_f32 v[134:135], v[134:135], v[234:235], v[230:231]
	v_pk_fma_f32 v[146:147], v[146:147], v[234:235], v[230:231]
	v_pk_fma_f32 v[138:139], v[132:133], v[138:139], v[132:133]
	v_pk_fma_f32 v[150:151], v[144:145], v[150:151], v[144:145]
	v_pk_mul_f32 v[140:141], v[10:11], v[232:233]
	v_pk_mul_f32 v[152:153], v[12:13], v[232:233]
	v_cmp_ngt_f32_e32 vcc, 1.0, v132
	v_cmp_ngt_f32_e64 s[8:9], 1.0, v133
	v_readlane_b32 s6, v252, 33
	v_readlane_b32 s7, v252, 34
	v_cndmask_b32_e32 v138, v138, v134, vcc
	v_cndmask_b32_e64 v139, v139, v135, s[8:9]
	v_cmp_ngt_f32_e32 vcc, 1.0, v144
	v_cmp_ngt_f32_e64 s[8:9], 1.0, v145
	v_bfi_b32 v138, s37, v138, v130
	v_bfi_b32 v139, s37, v139, v131
	v_cndmask_b32_e32 v150, v150, v146, vcc
	v_cndmask_b32_e64 v151, v151, v147, s[8:9]
	v_pk_add_f32 v[138:139], v[138:139], v[230:231]
	v_bfi_b32 v150, s37, v150, v142
	v_bfi_b32 v151, s37, v151, v143
	v_pk_add_f32 v[150:151], v[150:151], v[230:231]
	v_pk_mul_f32 v[138:139], v[140:141], v[138:139]
	v_lshl_add_u64 v[10:11], s[6:7], 0, v[14:15]
	v_pk_mul_f32 v[150:151], v[152:153], v[150:151]
	v_lshl_add_u64 v[10:11], v[182:183], 1, v[10:11]
	v_cvt_pk_bf16_f32 v12, v138, v139
	v_cvt_pk_bf16_f32 v13, v150, v151
	global_store_dwordx2 v[10:11], v[12:13], off offset:-1952

; DI void st_bf4(u16* p, float a, float b, float c, float d) { *(uint2*)p = make_uint2(pk2(a, b), pk2(c, d)); }
; DI float gelu_f(float x) { return 0.5f * x * (1.f + erff(x * 0.70710678118654752f)); }
;   template <int NT, int MT> DI void run(f32x4 (&acc)[NT][MT], int mb, int nb) const {
;     ...
;         } else if (n < 3072) {
;           st_bf4(uvbuf + (size_t)m * 2048 + (n - 1024), gelu_f(v[0]), gelu_f(v[1]), gelu_f(v[2]), gelu_f(v[3]));
.LBB0_806:
	s_andn2_saveexec_b64 s[48:49], s[48:49]
	s_cbranch_execz .LBB0_824
	v_pk_mul_f32 v[130:131], v[6:7], v[170:171]
	v_pk_mul_f32 v[142:143], v[8:9], v[170:171]
	v_and_b32_e32 v132, 0x7fffffff, v130
	v_and_b32_e32 v144, 0x7fffffff, v142
	v_and_b32_e32 v133, 0x7fffffff, v131
	v_and_b32_e32 v145, 0x7fffffff, v143
	v_pk_fma_f32 v[134:135], v[132:133], v[174:175], v[176:177]
	v_pk_fma_f32 v[146:147], v[144:145], v[174:175], v[176:177]
	v_pk_fma_f32 v[134:135], v[132:133], v[134:135], v[178:179]
	v_pk_fma_f32 v[146:147], v[144:145], v[146:147], v[178:179]
	v_pk_fma_f32 v[134:135], v[132:133], v[134:135], v[180:181]
	v_pk_fma_f32 v[146:147], v[144:145], v[146:147], v[180:181]
	v_pk_fma_f32 v[134:135], v[132:133], v[134:135], v[186:187]
	v_pk_fma_f32 v[146:147], v[144:145], v[146:147], v[186:187]
	v_pk_fma_f32 v[134:135], v[132:133], v[134:135], v[188:189]
	v_pk_fma_f32 v[146:147], v[144:145], v[146:147], v[188:189]
	v_pk_fma_f32 v[134:135], v[132:133], v[134:135], v[190:191]
	v_pk_fma_f32 v[146:147], v[144:145], v[146:147], v[190:191]
	v_pk_fma_f32 v[134:135], v[132:133], v[134:135], v[132:133]
	v_pk_fma_f32 v[146:147], v[144:145], v[146:147], v[144:145]
	v_pk_mul_f32 v[134:135], v[134:135], v[172:173]
	v_pk_mul_f32 v[146:147], v[146:147], v[172:173]
	v_pk_mul_f32 v[136:137], v[130:131], v[130:131]
	v_pk_mul_f32 v[148:149], v[142:143], v[142:143]
	v_exp_f32_e32 v134, v134
	v_exp_f32_e32 v146, v146
	v_exp_f32_e32 v135, v135
	v_exp_f32_e32 v147, v147
	v_pk_fma_f32 v[138:139], v[136:137], v[192:193], v[194:195]
	v_pk_fma_f32 v[150:151], v[148:149], v[192:193], v[194:195]
	v_pk_fma_f32 v[138:139], v[136:137], v[138:139], v[196:197]
	v_pk_fma_f32 v[150:151], v[148:149], v[150:151], v[196:197]
	v_pk_fma_f32 v[138:139], v[136:137], v[138:139], v[224:225]
	v_pk_fma_f32 v[150:151], v[148:149], v[150:151], v[224:225]
	v_pk_fma_f32 v[138:139], v[136:137], v[138:139], v[226:227]
	v_pk_fma_f32 v[150:151], v[148:149], v[150:151], v[226:227]
	v_pk_fma_f32 v[138:139], v[136:137], v[138:139], v[228:229]
	v_pk_fma_f32 v[150:151], v[148:149], v[150:151], v[228:229]
	v_pk_fma_f32 v[134:135], v[134:135], v[234:235], v[230:231]
	v_pk_fma_f32 v[146:147], v[146:147], v[234:235], v[230:231]
	v_pk_fma_f32 v[138:139], v[132:133], v[138:139], v[132:133]
	v_pk_fma_f32 v[150:151], v[144:145], v[150:151], v[144:145]
	v_pk_mul_f32 v[140:141], v[6:7], v[232:233]
	v_pk_mul_f32 v[152:153], v[8:9], v[232:233]
	v_cmp_ngt_f32_e32 vcc, 1.0, v132
	v_cmp_ngt_f32_e64 s[8:9], 1.0, v133
	v_readlane_b32 s6, v252, 33
	v_readlane_b32 s7, v252, 34
	v_cndmask_b32_e32 v138, v138, v134, vcc
	v_cndmask_b32_e64 v139, v139, v135, s[8:9]
	v_cmp_ngt_f32_e32 vcc, 1.0, v144
	v_cmp_ngt_f32_e64 s[8:9], 1.0, v145
	v_bfi_b32 v138, s37, v138, v130
	v_bfi_b32 v139, s37, v139, v131
	v_cndmask_b32_e32 v150, v150, v146, vcc
	v_cndmask_b32_e64 v151, v151, v147, s[8:9]
	v_pk_add_f32 v[138:139], v[138:139], v[230:231]
	v_bfi_b32 v150, s37, v150, v142
	v_bfi_b32 v151, s37, v151, v143
	v_pk_add_f32 v[150:151], v[150:151], v[230:231]
	v_pk_mul_f32 v[138:139], v[140:141], v[138:139]
	v_lshl_add_u64 v[6:7], s[6:7], 0, v[10:11]
	v_pk_mul_f32 v[150:151], v[152:153], v[150:151]
	v_lshl_add_u64 v[6:7], v[182:183], 1, v[6:7]
	v_cvt_pk_bf16_f32 v8, v138, v139
	v_cvt_pk_bf16_f32 v9, v150, v151
	global_store_dwordx2 v[6:7], v[8:9], off offset:-1952

; DI void st_bf4(u16* p, float a, float b, float c, float d) { *(uint2*)p = make_uint2(pk2(a, b), pk2(c, d)); }
; DI float gelu_f(float x) { return 0.5f * x * (1.f + erff(x * 0.70710678118654752f)); }
;   template <int NT, int MT> DI void run(f32x4 (&acc)[NT][MT], int mb, int nb) const {
;     ...
;         } else if (n < 3072) {
;           st_bf4(uvbuf + (size_t)m * 2048 + (n - 1024), gelu_f(v[0]), gelu_f(v[1]), gelu_f(v[2]), gelu_f(v[3]));
.LBB0_830:
	s_andn2_saveexec_b64 s[38:39], s[38:39]
	s_cbranch_execz .LBB0_848
	v_pk_mul_f32 v[130:131], v[2:3], v[170:171]
	v_pk_mul_f32 v[142:143], v[4:5], v[170:171]
	v_and_b32_e32 v132, 0x7fffffff, v130
	v_and_b32_e32 v144, 0x7fffffff, v142
	v_and_b32_e32 v133, 0x7fffffff, v131
	v_and_b32_e32 v145, 0x7fffffff, v143
	v_pk_fma_f32 v[134:135], v[132:133], v[174:175], v[176:177]
	v_pk_fma_f32 v[146:147], v[144:145], v[174:175], v[176:177]
	v_pk_fma_f32 v[134:135], v[132:133], v[134:135], v[178:179]
	v_pk_fma_f32 v[146:147], v[144:145], v[146:147], v[178:179]
	v_pk_fma_f32 v[134:135], v[132:133], v[134:135], v[180:181]
	v_pk_fma_f32 v[146:147], v[144:145], v[146:147], v[180:181]
	v_pk_fma_f32 v[134:135], v[132:133], v[134:135], v[186:187]
	v_pk_fma_f32 v[146:147], v[144:145], v[146:147], v[186:187]
	v_pk_fma_f32 v[134:135], v[132:133], v[134:135], v[188:189]
	v_pk_fma_f32 v[146:147], v[144:145], v[146:147], v[188:189]
	v_pk_fma_f32 v[134:135], v[132:133], v[134:135], v[190:191]
	v_pk_fma_f32 v[146:147], v[144:145], v[146:147], v[190:191]
	v_pk_fma_f32 v[134:135], v[132:133], v[134:135], v[132:133]
	v_pk_fma_f32 v[146:147], v[144:145], v[146:147], v[144:145]
	v_pk_mul_f32 v[134:135], v[134:135], v[172:173]
	v_pk_mul_f32 v[146:147], v[146:147], v[172:173]
	v_pk_mul_f32 v[136:137], v[130:131], v[130:131]
	v_pk_mul_f32 v[148:149], v[142:143], v[142:143]
	v_exp_f32_e32 v134, v134
	v_exp_f32_e32 v146, v146
	v_exp_f32_e32 v135, v135
	v_exp_f32_e32 v147, v147
	v_pk_fma_f32 v[138:139], v[136:137], v[192:193], v[194:195]
	v_pk_fma_f32 v[150:151], v[148:149], v[192:193], v[194:195]
	v_pk_fma_f32 v[138:139], v[136:137], v[138:139], v[196:197]
	v_pk_fma_f32 v[150:151], v[148:149], v[150:151], v[196:197]
	v_pk_fma_f32 v[138:139], v[136:137], v[138:139], v[224:225]
	v_pk_fma_f32 v[150:151], v[148:149], v[150:151], v[224:225]
	v_pk_fma_f32 v[138:139], v[136:137], v[138:139], v[226:227]
	v_pk_fma_f32 v[150:151], v[148:149], v[150:151], v[226:227]
	v_pk_fma_f32 v[138:139], v[136:137], v[138:139], v[228:229]
	v_pk_fma_f32 v[150:151], v[148:149], v[150:151], v[228:229]
	v_pk_fma_f32 v[134:135], v[134:135], v[234:235], v[230:231]
	v_pk_fma_f32 v[146:147], v[146:147], v[234:235], v[230:231]
	v_pk_fma_f32 v[138:139], v[132:133], v[138:139], v[132:133]
	v_pk_fma_f32 v[150:151], v[144:145], v[150:151], v[144:145]
	v_pk_mul_f32 v[140:141], v[2:3], v[232:233]
	v_pk_mul_f32 v[152:153], v[4:5], v[232:233]
	v_cmp_ngt_f32_e32 vcc, 1.0, v132
	v_cmp_ngt_f32_e64 s[8:9], 1.0, v133
	v_readlane_b32 s6, v252, 33
	v_readlane_b32 s7, v252, 34
	v_cndmask_b32_e32 v138, v138, v134, vcc
	v_cndmask_b32_e64 v139, v139, v135, s[8:9]
	v_cmp_ngt_f32_e32 vcc, 1.0, v144
	v_cmp_ngt_f32_e64 s[8:9], 1.0, v145
	v_bfi_b32 v138, s37, v138, v130
	v_bfi_b32 v139, s37, v139, v131
	v_cndmask_b32_e32 v150, v150, v146, vcc
	v_cndmask_b32_e64 v151, v151, v147, s[8:9]
	v_pk_add_f32 v[138:139], v[138:139], v[230:231]
	v_bfi_b32 v150, s37, v150, v142
	v_bfi_b32 v151, s37, v151, v143
	v_pk_add_f32 v[150:151], v[150:151], v[230:231]
	v_pk_mul_f32 v[138:139], v[140:141], v[138:139]
	v_lshl_add_u64 v[2:3], s[6:7], 0, v[6:7]
	v_pk_mul_f32 v[150:151], v[152:153], v[150:151]
	v_lshl_add_u64 v[2:3], v[182:183], 1, v[2:3]
	v_cvt_pk_bf16_f32 v4, v138, v139
	v_cvt_pk_bf16_f32 v5, v150, v151
	global_store_dwordx2 v[2:3], v[4:5], off offset:-1952

; template <int MT, class Epi>
; DI void gemm_tile(const u16* __restrict__ X, long ldx, const u16* __restrict__ W, long ldw, int K, char* smem,
;                   int m0, int n0, const Epi& epi, bool pre = false, const u16* Xn = nullptr, const u16* Wn = nullptr) {
;     ...
;   do {
;     asm volatile("s_waitcnt vmcnt(0)" ::: "memory");
;     __syncthreads();
;     if (kt + 1 < nk) GT_DMA((unsigned)((kt + 1) & 1) * 32768u)
;     else if (Xn != nullptr) { xe = Xn + oxe; xo = Xn + oxo; we = Wn + owe; wo = Wn + owo; GT_DMA(0u) }
;     const char* cur = smem + (kt & 1) * 32768;
; #pragma unroll
;     for (int ks = 0; ks < 2; ++ks) {
;       bf16x8 xf[MT], wf[4];
;       const int ch = ((ks * 4 + g) ^ rsw) << 4;
; #pragma unroll
;       for (int i = 0; i < MT; ++i) xf[i] = *(const bf16x8*)(cur + (wm * 16 * MT + i * 16 + lr) * 128 + ch);
; #pragma unroll
;       for (int i = 0; i < 4; ++i) wf[i] = *(const bf16x8*)(cur + 16384 + (wn * 64 + i * 16 + lr) * 128 + ch);
; #pragma unroll
;       for (int nt = 0; nt < 4; ++nt)
; #pragma unroll
;         for (int mt = 0; mt < MT; ++mt)
;           acc[nt][mt] = __builtin_amdgcn_mfma_f32_16x16x32_bf16(wf[nt], xf[mt], acc[nt][mt], 0, 0, 0);
;     }
;   } while (++kt < nk);
.LBB0_1312:
	s_add_i32 s7, s8, 0x8000
	v_lshl_add_u64 v[124:125], v[74:75], 0, s[40:41]
	s_and_b32 s9, s7, 0x8000
	v_lshl_add_u64 v[122:123], v[72:73], 0, s[40:41]
	v_lshl_add_u64 v[126:127], v[124:125], 0, s[74:75]
	s_waitcnt vmcnt(0)
	s_waitcnt lgkmcnt(0)
	s_barrier
	s_and_b32 s8, s8, 0x8000
	v_or_b32_e32 v162, s8, v84
	v_add3_u32 v163, v162, v80, v81
	v_add3_u32 v164, v162, v83, v81
	v_or_b32_e32 v165, s8, v82
	v_add3_u32 v166, v165, v80, v81
	v_add3_u32 v167, v165, v83, v81
	ds_read_b128 v[86:89], v163
	ds_read_b128 v[90:93], v163 offset:2048
	ds_read_b128 v[94:97], v163 offset:4096
	ds_read_b128 v[98:101], v163 offset:6144
	ds_read_b128 v[102:105], v164 offset:16384
	ds_read_b128 v[106:109], v164 offset:18432
	ds_read_b128 v[110:113], v164 offset:20480
	ds_read_b128 v[114:117], v164 offset:22528
	ds_read_b128 v[130:133], v166
	ds_read_b128 v[134:137], v166 offset:2048
	ds_read_b128 v[138:141], v166 offset:4096
	ds_read_b128 v[142:145], v166 offset:6144
	ds_read_b128 v[146:149], v167 offset:16384
	ds_read_b128 v[150:153], v167 offset:18432
	ds_read_b128 v[154:157], v167 offset:20480
	ds_read_b128 v[158:161], v167 offset:22528
	s_add_i32 s10, s9, s5
	s_mov_b32 m0, s10
	s_nop 0
	global_load_lds_dwordx4 v[126:127], off
	v_lshl_add_u64 v[126:127], v[122:123], 0, s[94:95]
	s_add_i32 s11, s10, 0x400
	s_mov_b32 m0, s11
	s_nop 0
	global_load_lds_dwordx4 v[126:127], off
	v_lshl_add_u64 v[124:125], v[124:125], 0, s[76:77]
	s_add_i32 s11, s10, 0x800
	s_mov_b32 m0, s11
	s_nop 0
	global_load_lds_dwordx4 v[124:125], off
	v_lshl_add_u64 v[120:121], v[70:71], 0, s[40:41]
	v_lshl_add_u64 v[122:123], v[122:123], 0, s[54:55]
	s_addk_i32 s10, 0xc00
	s_mov_b32 m0, s10
	s_nop 0
	global_load_lds_dwordx4 v[122:123], off
	v_lshl_add_u64 v[118:119], v[68:69], 0, s[40:41]
	v_lshl_add_u64 v[128:129], v[120:121], 0, s[28:29]
	s_add_i32 s9, s9, s6
	s_mov_b32 m0, s9
	s_nop 0
	global_load_lds_dwordx4 v[128:129], off
	v_lshl_add_u64 v[122:123], v[118:119], 0, s[94:95]
	s_add_i32 s10, s9, 0x400
	s_mov_b32 m0, s10
	s_nop 0
	global_load_lds_dwordx4 v[122:123], off
	v_lshl_add_u64 v[120:121], v[120:121], 0, s[78:79]
	s_add_i32 s10, s9, 0x800
	s_mov_b32 m0, s10
	s_nop 0
	global_load_lds_dwordx4 v[120:121], off
	v_lshl_add_u64 v[118:119], v[118:119], 0, s[54:55]
	s_addk_i32 s9, 0xc00
	s_mov_b32 m0, s9
	s_nop 0
	global_load_lds_dwordx4 v[118:119], off
	s_mov_b32 s8, s7
	s_add_u32 s40, s40, 0x80
	s_addc_u32 s41, s41, 0
	s_cmpk_lg_i32 s40, 0x780
	s_waitcnt lgkmcnt(11)
	v_mfma_f32_16x16x32_bf16 v[48:51], v[102:105], v[98:101], v[48:51]
	s_waitcnt lgkmcnt(10)
	v_mfma_f32_16x16x32_bf16 v[32:35], v[106:109], v[98:101], v[32:35]
	s_waitcnt lgkmcnt(9)
	v_mfma_f32_16x16x32_bf16 v[16:19], v[110:113], v[98:101], v[16:19]
	s_waitcnt lgkmcnt(8)
	v_mfma_f32_16x16x32_bf16 v[0:3], v[114:117], v[98:101], v[0:3]
	v_mfma_f32_16x16x32_bf16 v[60:63], v[102:105], v[86:89], v[60:63]
	v_mfma_f32_16x16x32_bf16 v[56:59], v[102:105], v[90:93], v[56:59]
	v_mfma_f32_16x16x32_bf16 v[52:55], v[102:105], v[94:97], v[52:55]
	v_mfma_f32_16x16x32_bf16 v[44:47], v[106:109], v[86:89], v[44:47]
	v_mfma_f32_16x16x32_bf16 v[40:43], v[106:109], v[90:93], v[40:43]
	v_mfma_f32_16x16x32_bf16 v[36:39], v[106:109], v[94:97], v[36:39]
	v_mfma_f32_16x16x32_bf16 v[28:31], v[110:113], v[86:89], v[28:31]
	v_mfma_f32_16x16x32_bf16 v[24:27], v[110:113], v[90:93], v[24:27]
	v_mfma_f32_16x16x32_bf16 v[20:23], v[110:113], v[94:97], v[20:23]
	v_mfma_f32_16x16x32_bf16 v[12:15], v[114:117], v[86:89], v[12:15]
	v_mfma_f32_16x16x32_bf16 v[8:11], v[114:117], v[90:93], v[8:11]
	v_mfma_f32_16x16x32_bf16 v[4:7], v[114:117], v[94:97], v[4:7]
	s_waitcnt lgkmcnt(3)
	v_mfma_f32_16x16x32_bf16 v[60:63], v[146:149], v[130:133], v[60:63]
	v_mfma_f32_16x16x32_bf16 v[56:59], v[146:149], v[134:137], v[56:59]
	v_mfma_f32_16x16x32_bf16 v[52:55], v[146:149], v[138:141], v[52:55]
	v_mfma_f32_16x16x32_bf16 v[48:51], v[146:149], v[142:145], v[48:51]
	s_waitcnt lgkmcnt(2)
	v_mfma_f32_16x16x32_bf16 v[44:47], v[150:153], v[130:133], v[44:47]
	v_mfma_f32_16x16x32_bf16 v[40:43], v[150:153], v[134:137], v[40:43]
	v_mfma_f32_16x16x32_bf16 v[36:39], v[150:153], v[138:141], v[36:39]
	v_mfma_f32_16x16x32_bf16 v[32:35], v[150:153], v[142:145], v[32:35]
	s_waitcnt lgkmcnt(1)
	v_mfma_f32_16x16x32_bf16 v[28:31], v[154:157], v[130:133], v[28:31]
	v_mfma_f32_16x16x32_bf16 v[24:27], v[154:157], v[134:137], v[24:27]
	v_mfma_f32_16x16x32_bf16 v[20:23], v[154:157], v[138:141], v[20:23]
	v_mfma_f32_16x16x32_bf16 v[16:19], v[154:157], v[142:145], v[16:19]
	s_waitcnt lgkmcnt(0)
	v_mfma_f32_16x16x32_bf16 v[12:15], v[158:161], v[130:133], v[12:15]
	v_mfma_f32_16x16x32_bf16 v[8:11], v[158:161], v[134:137], v[8:11]
	v_mfma_f32_16x16x32_bf16 v[4:7], v[158:161], v[138:141], v[4:7]
	v_mfma_f32_16x16x32_bf16 v[0:3], v[158:161], v[142:145], v[0:3]
	s_cbranch_scc1 .LBB0_1312
; DI int get_bid() { int b = blockIdx.x; asm volatile("" : "+s"(b)); return b; }
; template <int MT, class Epi>
; DI void gemm_tile(const u16* __restrict__ X, long ldx, const u16* __restrict__ W, long ldw, int K, char* smem,
;                   int m0, int n0, const Epi& epi, bool pre = false, const u16* Xn = nullptr, const u16* Wn = nullptr) {
;     ...
;   do {
;     asm volatile("s_waitcnt vmcnt(0)" ::: "memory");
;     __syncthreads();
;     if (kt + 1 < nk) GT_DMA((unsigned)((kt + 1) & 1) * 32768u)
;     else if (Xn != nullptr) { xe = Xn + oxe; xo = Xn + oxo; we = Wn + owe; wo = Wn + owo; GT_DMA(0u) }
; DI void phase_even(const Params& p, int e, int sub, char* smem) {
;     ...
;     for (int t = get_bid(); t < 132 * 40; t += gridDim.x) {
;       const int tm = t / 40, tn = t % 40;
;       const int t2 = t + gridDim.x, tm2 = t2 / 40, tn2 = t2 % 40;
;       const bool nx = t2 < 132 * 40;
;       gemm_tile<4>(hbuf + (size_t)tm * 128 * 1024, 1024, W + WE_IN + (size_t)tn * 128 * 1024, 1024, 1024, smem, tm * 128, tn * 128, epi, pre,
;                    nx ? hbuf + (size_t)tm2 * 128 * 1024 : nullptr, W + WE_IN + (size_t)tn2 * 128 * 1024);
	v_mov_b32_e32 v170, 0x3f3504f3
	v_mov_b32_e32 v171, 0x3f3504f3
	v_mov_b32_e32 v172, 0xbfb8aa3b
	v_mov_b32_e32 v173, 0xbfb8aa3b
	v_mov_b32_e32 v174, 0x378e98ab
	v_mov_b32_e32 v175, 0x378e98ab
	v_mov_b32_e32 v176, 0xb9c68948
	v_mov_b32_e32 v177, 0xb9c68948
	v_mov_b32_e32 v178, 0x3b7cd369
	v_mov_b32_e32 v179, 0x3b7cd369
	v_mov_b32_e32 v180, 0xbcc618b2
	v_mov_b32_e32 v181, 0xbcc618b2
	v_mov_b32_e32 v186, 0x3dda74e4
	v_mov_b32_e32 v187, 0x3dda74e4
	v_mov_b32_e32 v188, 0x3f228afd
	v_mov_b32_e32 v189, 0x3f228afd
	v_mov_b32_e32 v190, 0x3e03c728
	v_mov_b32_e32 v191, 0x3e03c728
	v_mov_b32_e32 v192, 0xba1345e1
	v_mov_b32_e32 v193, 0xba1345e1
	v_mov_b32_e32 v194, 0x3ba10414
	v_mov_b32_e32 v195, 0x3ba10414
	v_mov_b32_e32 v196, 0xbcdac9b8
	v_mov_b32_e32 v197, 0xbcdac9b8
	v_mov_b32_e32 v224, 0x3de703be
	v_mov_b32_e32 v225, 0x3de703be
	v_mov_b32_e32 v226, 0xbec09330
	v_mov_b32_e32 v227, 0xbec09330
	v_mov_b32_e32 v228, 0x3e0375d0
	v_mov_b32_e32 v229, 0x3e0375d0
	v_mov_b32_e32 v230, 1.0
	v_mov_b32_e32 v231, 1.0
	v_mov_b32_e32 v232, 0.5
	v_mov_b32_e32 v233, 0.5
	v_mov_b32_e32 v234, -1.0
	v_mov_b32_e32 v235, -1.0
	v_readlane_b32 s8, v255, 5
	v_readlane_b32 s14, v255, 11
	s_add_i32 s4, s4, s14
	s_mul_hi_i32 s7, s4, 0x66666667
	s_lshr_b32 s8, s7, 31
	s_ashr_i32 s7, s7, 4
	s_add_i32 s46, s7, s8
	s_cmpk_gt_i32 s4, 0x149f
	v_readlane_b32 s9, v255, 6
	s_cselect_b64 s[44:45], -1, 0
	s_ashr_i32 s47, s46, 31
	s_lshl_b64 s[8:9], s[46:47], 18
	s_add_u32 s7, s0, s8
	s_addc_u32 s8, s1, s9
	s_cmpk_lt_i32 s4, 0x14a0
	s_waitcnt vmcnt(0)
	s_cselect_b32 s41, s8, 0
	s_cselect_b32 s40, s7, 0
	v_readlane_b32 s12, v255, 9
	v_readlane_b32 s13, v255, 10
	s_cmp_eq_u64 s[40:41], 0
	v_readlane_b32 s10, v255, 7
	v_readlane_b32 s11, v255, 8
	v_readlane_b32 s15, v255, 12
	s_barrier
	s_cbranch_scc1 .LBB0_1315
	s_mul_i32 s7, s46, 40
	s_sub_i32 s8, s4, s7
	s_ashr_i32 s9, s8, 31
	s_lshl_b64 s[8:9], s[8:9], 18
	s_add_u32 s8, s12, s8
	s_addc_u32 s9, s13, s9
	v_lshl_add_u64 v[68:69], s[40:41], 0, v[66:67]
	v_lshl_add_u64 v[70:71], s[8:9], 0, v[64:65]
	v_lshl_add_u64 v[64:65], s[40:41], 0, v[64:65]
	s_mov_b32 m0, s5
	s_nop 0
	global_load_lds_dwordx4 v[68:69], off
	s_mov_b64 s[10:11], 0x4000
	v_lshl_add_u64 v[66:67], s[8:9], 0, v[66:67]
	v_lshl_add_u64 v[72:73], v[64:65], 0, s[10:11]
	s_add_i32 s7, s5, 0x400
	s_mov_b32 m0, s7
	s_nop 0
	global_load_lds_dwordx4 v[72:73], off
	s_mov_b64 s[12:13], 0x8000
	v_lshl_add_u64 v[68:69], v[68:69], 0, s[12:13]
	s_add_i32 s7, s5, 0x800
	s_mov_b32 m0, s7
	s_nop 0
	global_load_lds_dwordx4 v[68:69], off
	s_mov_b64 s[14:15], 0xc000
	v_lshl_add_u64 v[64:65], v[64:65], 0, s[14:15]
	s_add_i32 s7, s5, 0xc00
	s_mov_b32 m0, s7
	s_nop 0
	global_load_lds_dwordx4 v[64:65], off
	s_mov_b32 m0, s6
	s_nop 0
	global_load_lds_dwordx4 v[66:67], off
	v_lshl_add_u64 v[64:65], v[70:71], 0, s[10:11]
	s_add_i32 s6, s5, 0x4400
	s_mov_b32 m0, s6
	s_nop 0
	global_load_lds_dwordx4 v[64:65], off
	v_lshl_add_u64 v[64:65], v[66:67], 0, s[12:13]
	s_add_i32 s6, s5, 0x4800
	s_mov_b32 m0, s6
	s_nop 0
	global_load_lds_dwordx4 v[64:65], off
	v_lshl_add_u64 v[64:65], v[70:71], 0, s[14:15]
	s_addk_i32 s5, 0x4c00
	s_mov_b32 m0, s5
	s_nop 0
	global_load_lds_dwordx4 v[64:65], off

; DI void st_bf4(u16* p, float a, float b, float c, float d) { *(uint2*)p = make_uint2(pk2(a, b), pk2(c, d)); }
; DI float gelu_f(float x) { return 0.5f * x * (1.f + erff(x * 0.70710678118654752f)); }
;   template <int NT, int MT> DI void run(f32x4 (&acc)[NT][MT], int mb, int nb) const {
;     ...
;         } else if (n < 3072) {
;           st_bf4(uvbuf + (size_t)m * 2048 + (n - 1024), gelu_f(v[0]), gelu_f(v[1]), gelu_f(v[2]), gelu_f(v[3]));
.LBB0_1318:
	s_andn2_saveexec_b64 s[48:49], s[48:49]
	s_cbranch_execz .LBB0_1336
	v_pk_mul_f32 v[130:131], v[60:61], v[170:171]
	v_pk_mul_f32 v[142:143], v[62:63], v[170:171]
	v_and_b32_e32 v132, 0x7fffffff, v130
	v_and_b32_e32 v144, 0x7fffffff, v142
	v_and_b32_e32 v133, 0x7fffffff, v131
	v_and_b32_e32 v145, 0x7fffffff, v143
	v_pk_fma_f32 v[134:135], v[132:133], v[174:175], v[176:177]
	v_pk_fma_f32 v[146:147], v[144:145], v[174:175], v[176:177]
	v_pk_fma_f32 v[134:135], v[132:133], v[134:135], v[178:179]
	v_pk_fma_f32 v[146:147], v[144:145], v[146:147], v[178:179]
	v_pk_fma_f32 v[134:135], v[132:133], v[134:135], v[180:181]
	v_pk_fma_f32 v[146:147], v[144:145], v[146:147], v[180:181]
	v_pk_fma_f32 v[134:135], v[132:133], v[134:135], v[186:187]
	v_pk_fma_f32 v[146:147], v[144:145], v[146:147], v[186:187]
	v_pk_fma_f32 v[134:135], v[132:133], v[134:135], v[188:189]
	v_pk_fma_f32 v[146:147], v[144:145], v[146:147], v[188:189]
	v_pk_fma_f32 v[134:135], v[132:133], v[134:135], v[190:191]
	v_pk_fma_f32 v[146:147], v[144:145], v[146:147], v[190:191]
	v_pk_fma_f32 v[134:135], v[132:133], v[134:135], v[132:133]
	v_pk_fma_f32 v[146:147], v[144:145], v[146:147], v[144:145]
	v_pk_mul_f32 v[134:135], v[134:135], v[172:173]
	v_pk_mul_f32 v[146:147], v[146:147], v[172:173]
	v_pk_mul_f32 v[136:137], v[130:131], v[130:131]
	v_pk_mul_f32 v[148:149], v[142:143], v[142:143]
	v_exp_f32_e32 v134, v134
	v_exp_f32_e32 v146, v146
	v_exp_f32_e32 v135, v135
	v_exp_f32_e32 v147, v147
	v_pk_fma_f32 v[138:139], v[136:137], v[192:193], v[194:195]
	v_pk_fma_f32 v[150:151], v[148:149], v[192:193], v[194:195]
	v_pk_fma_f32 v[138:139], v[136:137], v[138:139], v[196:197]
	v_pk_fma_f32 v[150:151], v[148:149], v[150:151], v[196:197]
	v_pk_fma_f32 v[138:139], v[136:137], v[138:139], v[224:225]
	v_pk_fma_f32 v[150:151], v[148:149], v[150:151], v[224:225]
	v_pk_fma_f32 v[138:139], v[136:137], v[138:139], v[226:227]
	v_pk_fma_f32 v[150:151], v[148:149], v[150:151], v[226:227]
	v_pk_fma_f32 v[138:139], v[136:137], v[138:139], v[228:229]
	v_pk_fma_f32 v[150:151], v[148:149], v[150:151], v[228:229]
	v_pk_fma_f32 v[134:135], v[134:135], v[234:235], v[230:231]
	v_pk_fma_f32 v[146:147], v[146:147], v[234:235], v[230:231]
	v_pk_fma_f32 v[138:139], v[132:133], v[138:139], v[132:133]
	v_pk_fma_f32 v[150:151], v[144:145], v[150:151], v[144:145]
	v_pk_mul_f32 v[140:141], v[60:61], v[232:233]
	v_pk_mul_f32 v[152:153], v[62:63], v[232:233]
	v_cmp_ngt_f32_e32 vcc, 1.0, v132
	v_cmp_ngt_f32_e64 s[8:9], 1.0, v133
	v_readlane_b32 s6, v252, 33
	v_readlane_b32 s7, v252, 34
	v_cndmask_b32_e32 v138, v138, v134, vcc
	v_cndmask_b32_e64 v139, v139, v135, s[8:9]
	v_cmp_ngt_f32_e32 vcc, 1.0, v144
	v_cmp_ngt_f32_e64 s[8:9], 1.0, v145
	v_bfi_b32 v138, s37, v138, v130
	v_bfi_b32 v139, s37, v139, v131
	v_cndmask_b32_e32 v150, v150, v146, vcc
	v_cndmask_b32_e64 v151, v151, v147, s[8:9]
	v_pk_add_f32 v[138:139], v[138:139], v[230:231]
	v_bfi_b32 v150, s37, v150, v142
	v_bfi_b32 v151, s37, v151, v143
	v_pk_add_f32 v[150:151], v[150:151], v[230:231]
	v_pk_mul_f32 v[138:139], v[140:141], v[138:139]
	v_lshl_add_u64 v[60:61], s[6:7], 0, v[66:67]
	v_pk_mul_f32 v[150:151], v[152:153], v[150:151]
	v_lshl_add_u64 v[60:61], v[182:183], 1, v[60:61]
	v_cvt_pk_bf16_f32 v62, v138, v139
	v_cvt_pk_bf16_f32 v63, v150, v151
	global_store_dwordx2 v[60:61], v[62:63], off offset:-2048

; DI void st_bf4(u16* p, float a, float b, float c, float d) { *(uint2*)p = make_uint2(pk2(a, b), pk2(c, d)); }
; DI float gelu_f(float x) { return 0.5f * x * (1.f + erff(x * 0.70710678118654752f)); }
;   template <int NT, int MT> DI void run(f32x4 (&acc)[NT][MT], int mb, int nb) const {
;     ...
;         } else if (n < 3072) {
;           st_bf4(uvbuf + (size_t)m * 2048 + (n - 1024), gelu_f(v[0]), gelu_f(v[1]), gelu_f(v[2]), gelu_f(v[3]));
.LBB0_1342:
	s_andn2_saveexec_b64 s[48:49], s[48:49]
	s_cbranch_execz .LBB0_1360
	v_pk_mul_f32 v[130:131], v[56:57], v[170:171]
	v_pk_mul_f32 v[142:143], v[58:59], v[170:171]
	v_and_b32_e32 v132, 0x7fffffff, v130
	v_and_b32_e32 v144, 0x7fffffff, v142
	v_and_b32_e32 v133, 0x7fffffff, v131
	v_and_b32_e32 v145, 0x7fffffff, v143
	v_pk_fma_f32 v[134:135], v[132:133], v[174:175], v[176:177]
	v_pk_fma_f32 v[146:147], v[144:145], v[174:175], v[176:177]
	v_pk_fma_f32 v[134:135], v[132:133], v[134:135], v[178:179]
	v_pk_fma_f32 v[146:147], v[144:145], v[146:147], v[178:179]
	v_pk_fma_f32 v[134:135], v[132:133], v[134:135], v[180:181]
	v_pk_fma_f32 v[146:147], v[144:145], v[146:147], v[180:181]
	v_pk_fma_f32 v[134:135], v[132:133], v[134:135], v[186:187]
	v_pk_fma_f32 v[146:147], v[144:145], v[146:147], v[186:187]
	v_pk_fma_f32 v[134:135], v[132:133], v[134:135], v[188:189]
	v_pk_fma_f32 v[146:147], v[144:145], v[146:147], v[188:189]
	v_pk_fma_f32 v[134:135], v[132:133], v[134:135], v[190:191]
	v_pk_fma_f32 v[146:147], v[144:145], v[146:147], v[190:191]
	v_pk_fma_f32 v[134:135], v[132:133], v[134:135], v[132:133]
	v_pk_fma_f32 v[146:147], v[144:145], v[146:147], v[144:145]
	v_pk_mul_f32 v[134:135], v[134:135], v[172:173]
	v_pk_mul_f32 v[146:147], v[146:147], v[172:173]
	v_pk_mul_f32 v[136:137], v[130:131], v[130:131]
	v_pk_mul_f32 v[148:149], v[142:143], v[142:143]
	v_exp_f32_e32 v134, v134
	v_exp_f32_e32 v146, v146
	v_exp_f32_e32 v135, v135
	v_exp_f32_e32 v147, v147
	v_pk_fma_f32 v[138:139], v[136:137], v[192:193], v[194:195]
	v_pk_fma_f32 v[150:151], v[148:149], v[192:193], v[194:195]
	v_pk_fma_f32 v[138:139], v[136:137], v[138:139], v[196:197]
	v_pk_fma_f32 v[150:151], v[148:149], v[150:151], v[196:197]
	v_pk_fma_f32 v[138:139], v[136:137], v[138:139], v[224:225]
	v_pk_fma_f32 v[150:151], v[148:149], v[150:151], v[224:225]
	v_pk_fma_f32 v[138:139], v[136:137], v[138:139], v[226:227]
	v_pk_fma_f32 v[150:151], v[148:149], v[150:151], v[226:227]
	v_pk_fma_f32 v[138:139], v[136:137], v[138:139], v[228:229]
	v_pk_fma_f32 v[150:151], v[148:149], v[150:151], v[228:229]
	v_pk_fma_f32 v[134:135], v[134:135], v[234:235], v[230:231]
	v_pk_fma_f32 v[146:147], v[146:147], v[234:235], v[230:231]
	v_pk_fma_f32 v[138:139], v[132:133], v[138:139], v[132:133]
	v_pk_fma_f32 v[150:151], v[144:145], v[150:151], v[144:145]
	v_pk_mul_f32 v[140:141], v[56:57], v[232:233]
	v_pk_mul_f32 v[152:153], v[58:59], v[232:233]
	v_cmp_ngt_f32_e32 vcc, 1.0, v132
	v_cmp_ngt_f32_e64 s[8:9], 1.0, v133
	v_readlane_b32 s6, v252, 33
	v_readlane_b32 s7, v252, 34
	v_cndmask_b32_e32 v138, v138, v134, vcc
	v_cndmask_b32_e64 v139, v139, v135, s[8:9]
	v_cmp_ngt_f32_e32 vcc, 1.0, v144
	v_cmp_ngt_f32_e64 s[8:9], 1.0, v145
	v_bfi_b32 v138, s37, v138, v130
	v_bfi_b32 v139, s37, v139, v131
	v_cndmask_b32_e32 v150, v150, v146, vcc
	v_cndmask_b32_e64 v151, v151, v147, s[8:9]
	v_pk_add_f32 v[138:139], v[138:139], v[230:231]
	v_bfi_b32 v150, s37, v150, v142
	v_bfi_b32 v151, s37, v151, v143
	v_pk_add_f32 v[150:151], v[150:151], v[230:231]
	v_pk_mul_f32 v[138:139], v[140:141], v[138:139]
	v_lshl_add_u64 v[56:57], s[6:7], 0, v[62:63]
	v_pk_mul_f32 v[150:151], v[152:153], v[150:151]
	v_lshl_add_u64 v[56:57], v[182:183], 1, v[56:57]
	v_cvt_pk_bf16_f32 v58, v138, v139
	v_cvt_pk_bf16_f32 v59, v150, v151
	global_store_dwordx2 v[56:57], v[58:59], off offset:-2048

; DI void st_bf4(u16* p, float a, float b, float c, float d) { *(uint2*)p = make_uint2(pk2(a, b), pk2(c, d)); }
; DI float gelu_f(float x) { return 0.5f * x * (1.f + erff(x * 0.70710678118654752f)); }
;   template <int NT, int MT> DI void run(f32x4 (&acc)[NT][MT], int mb, int nb) const {
;     ...
;         } else if (n < 3072) {
;           st_bf4(uvbuf + (size_t)m * 2048 + (n - 1024), gelu_f(v[0]), gelu_f(v[1]), gelu_f(v[2]), gelu_f(v[3]));
.LBB0_1372:
	s_andn2_saveexec_b64 s[48:49], s[48:49]
	s_cbranch_execz .LBB0_1390
	v_pk_mul_f32 v[130:131], v[52:53], v[170:171]
	v_pk_mul_f32 v[142:143], v[54:55], v[170:171]
	v_and_b32_e32 v132, 0x7fffffff, v130
	v_and_b32_e32 v144, 0x7fffffff, v142
	v_and_b32_e32 v133, 0x7fffffff, v131
	v_and_b32_e32 v145, 0x7fffffff, v143
	v_pk_fma_f32 v[134:135], v[132:133], v[174:175], v[176:177]
	v_pk_fma_f32 v[146:147], v[144:145], v[174:175], v[176:177]
	v_pk_fma_f32 v[134:135], v[132:133], v[134:135], v[178:179]
	v_pk_fma_f32 v[146:147], v[144:145], v[146:147], v[178:179]
	v_pk_fma_f32 v[134:135], v[132:133], v[134:135], v[180:181]
	v_pk_fma_f32 v[146:147], v[144:145], v[146:147], v[180:181]
	v_pk_fma_f32 v[134:135], v[132:133], v[134:135], v[186:187]
	v_pk_fma_f32 v[146:147], v[144:145], v[146:147], v[186:187]
	v_pk_fma_f32 v[134:135], v[132:133], v[134:135], v[188:189]
	v_pk_fma_f32 v[146:147], v[144:145], v[146:147], v[188:189]
	v_pk_fma_f32 v[134:135], v[132:133], v[134:135], v[190:191]
	v_pk_fma_f32 v[146:147], v[144:145], v[146:147], v[190:191]
	v_pk_fma_f32 v[134:135], v[132:133], v[134:135], v[132:133]
	v_pk_fma_f32 v[146:147], v[144:145], v[146:147], v[144:145]
	v_pk_mul_f32 v[134:135], v[134:135], v[172:173]
	v_pk_mul_f32 v[146:147], v[146:147], v[172:173]
	v_pk_mul_f32 v[136:137], v[130:131], v[130:131]
	v_pk_mul_f32 v[148:149], v[142:143], v[142:143]
	v_exp_f32_e32 v134, v134
	v_exp_f32_e32 v146, v146
	v_exp_f32_e32 v135, v135
	v_exp_f32_e32 v147, v147
	v_pk_fma_f32 v[138:139], v[136:137], v[192:193], v[194:195]
	v_pk_fma_f32 v[150:151], v[148:149], v[192:193], v[194:195]
	v_pk_fma_f32 v[138:139], v[136:137], v[138:139], v[196:197]
	v_pk_fma_f32 v[150:151], v[148:149], v[150:151], v[196:197]
	v_pk_fma_f32 v[138:139], v[136:137], v[138:139], v[224:225]
	v_pk_fma_f32 v[150:151], v[148:149], v[150:151], v[224:225]
	v_pk_fma_f32 v[138:139], v[136:137], v[138:139], v[226:227]
	v_pk_fma_f32 v[150:151], v[148:149], v[150:151], v[226:227]
	v_pk_fma_f32 v[138:139], v[136:137], v[138:139], v[228:229]
	v_pk_fma_f32 v[150:151], v[148:149], v[150:151], v[228:229]
	v_pk_fma_f32 v[134:135], v[134:135], v[234:235], v[230:231]
	v_pk_fma_f32 v[146:147], v[146:147], v[234:235], v[230:231]
	v_pk_fma_f32 v[138:139], v[132:133], v[138:139], v[132:133]
	v_pk_fma_f32 v[150:151], v[144:145], v[150:151], v[144:145]
	v_pk_mul_f32 v[140:141], v[52:53], v[232:233]
	v_pk_mul_f32 v[152:153], v[54:55], v[232:233]
	v_cmp_ngt_f32_e32 vcc, 1.0, v132
	v_cmp_ngt_f32_e64 s[8:9], 1.0, v133
	v_readlane_b32 s6, v252, 33
	v_readlane_b32 s7, v252, 34
	v_cndmask_b32_e32 v138, v138, v134, vcc
	v_cndmask_b32_e64 v139, v139, v135, s[8:9]
	v_cmp_ngt_f32_e32 vcc, 1.0, v144
	v_cmp_ngt_f32_e64 s[8:9], 1.0, v145
	v_bfi_b32 v138, s37, v138, v130
	v_bfi_b32 v139, s37, v139, v131
	v_cndmask_b32_e32 v150, v150, v146, vcc
	v_cndmask_b32_e64 v151, v151, v147, s[8:9]
	v_pk_add_f32 v[138:139], v[138:139], v[230:231]
	v_bfi_b32 v150, s37, v150, v142
	v_bfi_b32 v151, s37, v151, v143
	v_pk_add_f32 v[150:151], v[150:151], v[230:231]
	v_pk_mul_f32 v[138:139], v[140:141], v[138:139]
	v_lshl_add_u64 v[52:53], s[6:7], 0, v[58:59]
	v_pk_mul_f32 v[150:151], v[152:153], v[150:151]
	v_lshl_add_u64 v[52:53], v[182:183], 1, v[52:53]
	v_cvt_pk_bf16_f32 v54, v138, v139
	v_cvt_pk_bf16_f32 v55, v150, v151
	global_store_dwordx2 v[52:53], v[54:55], off offset:-2048

; DI void st_bf4(u16* p, float a, float b, float c, float d) { *(uint2*)p = make_uint2(pk2(a, b), pk2(c, d)); }
; DI float gelu_f(float x) { return 0.5f * x * (1.f + erff(x * 0.70710678118654752f)); }
;   template <int NT, int MT> DI void run(f32x4 (&acc)[NT][MT], int mb, int nb) const {
;     ...
;         } else if (n < 3072) {
;           st_bf4(uvbuf + (size_t)m * 2048 + (n - 1024), gelu_f(v[0]), gelu_f(v[1]), gelu_f(v[2]), gelu_f(v[3]));
.LBB0_1396:
	s_andn2_saveexec_b64 s[46:47], s[46:47]
	s_cbranch_execz .LBB0_1414
	v_pk_mul_f32 v[130:131], v[48:49], v[170:171]
	v_pk_mul_f32 v[142:143], v[50:51], v[170:171]
	v_and_b32_e32 v132, 0x7fffffff, v130
	v_and_b32_e32 v144, 0x7fffffff, v142
	v_and_b32_e32 v133, 0x7fffffff, v131
	v_and_b32_e32 v145, 0x7fffffff, v143
	v_pk_fma_f32 v[134:135], v[132:133], v[174:175], v[176:177]
	v_pk_fma_f32 v[146:147], v[144:145], v[174:175], v[176:177]
	v_pk_fma_f32 v[134:135], v[132:133], v[134:135], v[178:179]
	v_pk_fma_f32 v[146:147], v[144:145], v[146:147], v[178:179]
	v_pk_fma_f32 v[134:135], v[132:133], v[134:135], v[180:181]
	v_pk_fma_f32 v[146:147], v[144:145], v[146:147], v[180:181]
	v_pk_fma_f32 v[134:135], v[132:133], v[134:135], v[186:187]
	v_pk_fma_f32 v[146:147], v[144:145], v[146:147], v[186:187]
	v_pk_fma_f32 v[134:135], v[132:133], v[134:135], v[188:189]
	v_pk_fma_f32 v[146:147], v[144:145], v[146:147], v[188:189]
	v_pk_fma_f32 v[134:135], v[132:133], v[134:135], v[190:191]
	v_pk_fma_f32 v[146:147], v[144:145], v[146:147], v[190:191]
	v_pk_fma_f32 v[134:135], v[132:133], v[134:135], v[132:133]
	v_pk_fma_f32 v[146:147], v[144:145], v[146:147], v[144:145]
	v_pk_mul_f32 v[134:135], v[134:135], v[172:173]
	v_pk_mul_f32 v[146:147], v[146:147], v[172:173]
	v_pk_mul_f32 v[136:137], v[130:131], v[130:131]
	v_pk_mul_f32 v[148:149], v[142:143], v[142:143]
	v_exp_f32_e32 v134, v134
	v_exp_f32_e32 v146, v146
	v_exp_f32_e32 v135, v135
	v_exp_f32_e32 v147, v147
	v_pk_fma_f32 v[138:139], v[136:137], v[192:193], v[194:195]
	v_pk_fma_f32 v[150:151], v[148:149], v[192:193], v[194:195]
	v_pk_fma_f32 v[138:139], v[136:137], v[138:139], v[196:197]
	v_pk_fma_f32 v[150:151], v[148:149], v[150:151], v[196:197]
	v_pk_fma_f32 v[138:139], v[136:137], v[138:139], v[224:225]
	v_pk_fma_f32 v[150:151], v[148:149], v[150:151], v[224:225]
	v_pk_fma_f32 v[138:139], v[136:137], v[138:139], v[226:227]
	v_pk_fma_f32 v[150:151], v[148:149], v[150:151], v[226:227]
	v_pk_fma_f32 v[138:139], v[136:137], v[138:139], v[228:229]
	v_pk_fma_f32 v[150:151], v[148:149], v[150:151], v[228:229]
	v_pk_fma_f32 v[134:135], v[134:135], v[234:235], v[230:231]
	v_pk_fma_f32 v[146:147], v[146:147], v[234:235], v[230:231]
	v_pk_fma_f32 v[138:139], v[132:133], v[138:139], v[132:133]
	v_pk_fma_f32 v[150:151], v[144:145], v[150:151], v[144:145]
	v_pk_mul_f32 v[140:141], v[48:49], v[232:233]
	v_pk_mul_f32 v[152:153], v[50:51], v[232:233]
	v_cmp_ngt_f32_e32 vcc, 1.0, v132
	v_cmp_ngt_f32_e64 s[8:9], 1.0, v133
	v_readlane_b32 s6, v252, 33
	v_readlane_b32 s7, v252, 34
	v_cndmask_b32_e32 v138, v138, v134, vcc
	v_cndmask_b32_e64 v139, v139, v135, s[8:9]
	v_cmp_ngt_f32_e32 vcc, 1.0, v144
	v_cmp_ngt_f32_e64 s[8:9], 1.0, v145
	v_bfi_b32 v138, s37, v138, v130
	v_bfi_b32 v139, s37, v139, v131
	v_cndmask_b32_e32 v150, v150, v146, vcc
	v_cndmask_b32_e64 v151, v151, v147, s[8:9]
	v_pk_add_f32 v[138:139], v[138:139], v[230:231]
	v_bfi_b32 v150, s37, v150, v142
	v_bfi_b32 v151, s37, v151, v143
	v_pk_add_f32 v[150:151], v[150:151], v[230:231]
	v_pk_mul_f32 v[138:139], v[140:141], v[138:139]
	v_lshl_add_u64 v[48:49], s[6:7], 0, v[54:55]
	v_pk_mul_f32 v[150:151], v[152:153], v[150:151]
	v_lshl_add_u64 v[48:49], v[182:183], 1, v[48:49]
	v_cvt_pk_bf16_f32 v50, v138, v139
	v_cvt_pk_bf16_f32 v51, v150, v151
	global_store_dwordx2 v[48:49], v[50:51], off offset:-2048

; DI void st_bf4(u16* p, float a, float b, float c, float d) { *(uint2*)p = make_uint2(pk2(a, b), pk2(c, d)); }
; DI float gelu_f(float x) { return 0.5f * x * (1.f + erff(x * 0.70710678118654752f)); }
;   template <int NT, int MT> DI void run(f32x4 (&acc)[NT][MT], int mb, int nb) const {
;     ...
;         } else if (n < 3072) {
;           st_bf4(uvbuf + (size_t)m * 2048 + (n - 1024), gelu_f(v[0]), gelu_f(v[1]), gelu_f(v[2]), gelu_f(v[3]));
.LBB0_1426:
	s_andn2_saveexec_b64 s[48:49], s[48:49]
	s_cbranch_execz .LBB0_1444
	v_pk_mul_f32 v[130:131], v[44:45], v[170:171]
	v_pk_mul_f32 v[142:143], v[46:47], v[170:171]
	v_and_b32_e32 v132, 0x7fffffff, v130
	v_and_b32_e32 v144, 0x7fffffff, v142
	v_and_b32_e32 v133, 0x7fffffff, v131
	v_and_b32_e32 v145, 0x7fffffff, v143
	v_pk_fma_f32 v[134:135], v[132:133], v[174:175], v[176:177]
	v_pk_fma_f32 v[146:147], v[144:145], v[174:175], v[176:177]
	v_pk_fma_f32 v[134:135], v[132:133], v[134:135], v[178:179]
	v_pk_fma_f32 v[146:147], v[144:145], v[146:147], v[178:179]
	v_pk_fma_f32 v[134:135], v[132:133], v[134:135], v[180:181]
	v_pk_fma_f32 v[146:147], v[144:145], v[146:147], v[180:181]
	v_pk_fma_f32 v[134:135], v[132:133], v[134:135], v[186:187]
	v_pk_fma_f32 v[146:147], v[144:145], v[146:147], v[186:187]
	v_pk_fma_f32 v[134:135], v[132:133], v[134:135], v[188:189]
	v_pk_fma_f32 v[146:147], v[144:145], v[146:147], v[188:189]
	v_pk_fma_f32 v[134:135], v[132:133], v[134:135], v[190:191]
	v_pk_fma_f32 v[146:147], v[144:145], v[146:147], v[190:191]
	v_pk_fma_f32 v[134:135], v[132:133], v[134:135], v[132:133]
	v_pk_fma_f32 v[146:147], v[144:145], v[146:147], v[144:145]
	v_pk_mul_f32 v[134:135], v[134:135], v[172:173]
	v_pk_mul_f32 v[146:147], v[146:147], v[172:173]
	v_pk_mul_f32 v[136:137], v[130:131], v[130:131]
	v_pk_mul_f32 v[148:149], v[142:143], v[142:143]
	v_exp_f32_e32 v134, v134
	v_exp_f32_e32 v146, v146
	v_exp_f32_e32 v135, v135
	v_exp_f32_e32 v147, v147
	v_pk_fma_f32 v[138:139], v[136:137], v[192:193], v[194:195]
	v_pk_fma_f32 v[150:151], v[148:149], v[192:193], v[194:195]
	v_pk_fma_f32 v[138:139], v[136:137], v[138:139], v[196:197]
	v_pk_fma_f32 v[150:151], v[148:149], v[150:151], v[196:197]
	v_pk_fma_f32 v[138:139], v[136:137], v[138:139], v[224:225]
	v_pk_fma_f32 v[150:151], v[148:149], v[150:151], v[224:225]
	v_pk_fma_f32 v[138:139], v[136:137], v[138:139], v[226:227]
	v_pk_fma_f32 v[150:151], v[148:149], v[150:151], v[226:227]
	v_pk_fma_f32 v[138:139], v[136:137], v[138:139], v[228:229]
	v_pk_fma_f32 v[150:151], v[148:149], v[150:151], v[228:229]
	v_pk_fma_f32 v[134:135], v[134:135], v[234:235], v[230:231]
	v_pk_fma_f32 v[146:147], v[146:147], v[234:235], v[230:231]
	v_pk_fma_f32 v[138:139], v[132:133], v[138:139], v[132:133]
	v_pk_fma_f32 v[150:151], v[144:145], v[150:151], v[144:145]
	v_pk_mul_f32 v[140:141], v[44:45], v[232:233]
	v_pk_mul_f32 v[152:153], v[46:47], v[232:233]
	v_cmp_ngt_f32_e32 vcc, 1.0, v132
	v_cmp_ngt_f32_e64 s[8:9], 1.0, v133
	v_readlane_b32 s6, v252, 33
	v_readlane_b32 s7, v252, 34
	v_cndmask_b32_e32 v138, v138, v134, vcc
	v_cndmask_b32_e64 v139, v139, v135, s[8:9]
	v_cmp_ngt_f32_e32 vcc, 1.0, v144
	v_cmp_ngt_f32_e64 s[8:9], 1.0, v145
	v_bfi_b32 v138, s37, v138, v130
	v_bfi_b32 v139, s37, v139, v131
	v_cndmask_b32_e32 v150, v150, v146, vcc
	v_cndmask_b32_e64 v151, v151, v147, s[8:9]
	v_pk_add_f32 v[138:139], v[138:139], v[230:231]
	v_bfi_b32 v150, s37, v150, v142
	v_bfi_b32 v151, s37, v151, v143
	v_pk_add_f32 v[150:151], v[150:151], v[230:231]
	v_pk_mul_f32 v[138:139], v[140:141], v[138:139]
	v_lshl_add_u64 v[44:45], s[6:7], 0, v[48:49]
	v_pk_mul_f32 v[150:151], v[152:153], v[150:151]
	v_lshl_add_u64 v[44:45], v[182:183], 1, v[44:45]
	v_cvt_pk_bf16_f32 v46, v138, v139
	v_cvt_pk_bf16_f32 v47, v150, v151
	global_store_dwordx2 v[44:45], v[46:47], off offset:-2016

; DI void st_bf4(u16* p, float a, float b, float c, float d) { *(uint2*)p = make_uint2(pk2(a, b), pk2(c, d)); }
; DI float gelu_f(float x) { return 0.5f * x * (1.f + erff(x * 0.70710678118654752f)); }
;   template <int NT, int MT> DI void run(f32x4 (&acc)[NT][MT], int mb, int nb) const {
;     ...
;         } else if (n < 3072) {
;           st_bf4(uvbuf + (size_t)m * 2048 + (n - 1024), gelu_f(v[0]), gelu_f(v[1]), gelu_f(v[2]), gelu_f(v[3]));
.LBB0_1450:
	s_andn2_saveexec_b64 s[48:49], s[48:49]
	s_cbranch_execz .LBB0_1468
	v_pk_mul_f32 v[130:131], v[40:41], v[170:171]
	v_pk_mul_f32 v[142:143], v[42:43], v[170:171]
	v_and_b32_e32 v132, 0x7fffffff, v130
	v_and_b32_e32 v144, 0x7fffffff, v142
	v_and_b32_e32 v133, 0x7fffffff, v131
	v_and_b32_e32 v145, 0x7fffffff, v143
	v_pk_fma_f32 v[134:135], v[132:133], v[174:175], v[176:177]
	v_pk_fma_f32 v[146:147], v[144:145], v[174:175], v[176:177]
	v_pk_fma_f32 v[134:135], v[132:133], v[134:135], v[178:179]
	v_pk_fma_f32 v[146:147], v[144:145], v[146:147], v[178:179]
	v_pk_fma_f32 v[134:135], v[132:133], v[134:135], v[180:181]
	v_pk_fma_f32 v[146:147], v[144:145], v[146:147], v[180:181]
	v_pk_fma_f32 v[134:135], v[132:133], v[134:135], v[186:187]
	v_pk_fma_f32 v[146:147], v[144:145], v[146:147], v[186:187]
	v_pk_fma_f32 v[134:135], v[132:133], v[134:135], v[188:189]
	v_pk_fma_f32 v[146:147], v[144:145], v[146:147], v[188:189]
	v_pk_fma_f32 v[134:135], v[132:133], v[134:135], v[190:191]
	v_pk_fma_f32 v[146:147], v[144:145], v[146:147], v[190:191]
	v_pk_fma_f32 v[134:135], v[132:133], v[134:135], v[132:133]
	v_pk_fma_f32 v[146:147], v[144:145], v[146:147], v[144:145]
	v_pk_mul_f32 v[134:135], v[134:135], v[172:173]
	v_pk_mul_f32 v[146:147], v[146:147], v[172:173]
	v_pk_mul_f32 v[136:137], v[130:131], v[130:131]
	v_pk_mul_f32 v[148:149], v[142:143], v[142:143]
	v_exp_f32_e32 v134, v134
	v_exp_f32_e32 v146, v146
	v_exp_f32_e32 v135, v135
	v_exp_f32_e32 v147, v147
	v_pk_fma_f32 v[138:139], v[136:137], v[192:193], v[194:195]
	v_pk_fma_f32 v[150:151], v[148:149], v[192:193], v[194:195]
	v_pk_fma_f32 v[138:139], v[136:137], v[138:139], v[196:197]
	v_pk_fma_f32 v[150:151], v[148:149], v[150:151], v[196:197]
	v_pk_fma_f32 v[138:139], v[136:137], v[138:139], v[224:225]
	v_pk_fma_f32 v[150:151], v[148:149], v[150:151], v[224:225]
	v_pk_fma_f32 v[138:139], v[136:137], v[138:139], v[226:227]
	v_pk_fma_f32 v[150:151], v[148:149], v[150:151], v[226:227]
	v_pk_fma_f32 v[138:139], v[136:137], v[138:139], v[228:229]
	v_pk_fma_f32 v[150:151], v[148:149], v[150:151], v[228:229]
	v_pk_fma_f32 v[134:135], v[134:135], v[234:235], v[230:231]
	v_pk_fma_f32 v[146:147], v[146:147], v[234:235], v[230:231]
	v_pk_fma_f32 v[138:139], v[132:133], v[138:139], v[132:133]
	v_pk_fma_f32 v[150:151], v[144:145], v[150:151], v[144:145]
	v_pk_mul_f32 v[140:141], v[40:41], v[232:233]
	v_pk_mul_f32 v[152:153], v[42:43], v[232:233]
	v_cmp_ngt_f32_e32 vcc, 1.0, v132
	v_cmp_ngt_f32_e64 s[8:9], 1.0, v133
	v_readlane_b32 s6, v252, 33
	v_readlane_b32 s7, v252, 34
	v_cndmask_b32_e32 v138, v138, v134, vcc
	v_cndmask_b32_e64 v139, v139, v135, s[8:9]
	v_cmp_ngt_f32_e32 vcc, 1.0, v144
	v_cmp_ngt_f32_e64 s[8:9], 1.0, v145
	v_bfi_b32 v138, s37, v138, v130
	v_bfi_b32 v139, s37, v139, v131
	v_cndmask_b32_e32 v150, v150, v146, vcc
	v_cndmask_b32_e64 v151, v151, v147, s[8:9]
	v_pk_add_f32 v[138:139], v[138:139], v[230:231]
	v_bfi_b32 v150, s37, v150, v142
	v_bfi_b32 v151, s37, v151, v143
	v_pk_add_f32 v[150:151], v[150:151], v[230:231]
	v_pk_mul_f32 v[138:139], v[140:141], v[138:139]
	v_lshl_add_u64 v[40:41], s[6:7], 0, v[44:45]
	v_pk_mul_f32 v[150:151], v[152:153], v[150:151]
	v_lshl_add_u64 v[40:41], v[182:183], 1, v[40:41]
	v_cvt_pk_bf16_f32 v42, v138, v139
	v_cvt_pk_bf16_f32 v43, v150, v151
	global_store_dwordx2 v[40:41], v[42:43], off offset:-2016

; DI void st_bf4(u16* p, float a, float b, float c, float d) { *(uint2*)p = make_uint2(pk2(a, b), pk2(c, d)); }
; DI float gelu_f(float x) { return 0.5f * x * (1.f + erff(x * 0.70710678118654752f)); }
;   template <int NT, int MT> DI void run(f32x4 (&acc)[NT][MT], int mb, int nb) const {
;     ...
;         } else if (n < 3072) {
;           st_bf4(uvbuf + (size_t)m * 2048 + (n - 1024), gelu_f(v[0]), gelu_f(v[1]), gelu_f(v[2]), gelu_f(v[3]));
.LBB0_1480:
	s_andn2_saveexec_b64 s[48:49], s[48:49]
	s_cbranch_execz .LBB0_1498
	v_pk_mul_f32 v[130:131], v[36:37], v[170:171]
	v_pk_mul_f32 v[142:143], v[38:39], v[170:171]
	v_and_b32_e32 v132, 0x7fffffff, v130
	v_and_b32_e32 v144, 0x7fffffff, v142
	v_and_b32_e32 v133, 0x7fffffff, v131
	v_and_b32_e32 v145, 0x7fffffff, v143
	v_pk_fma_f32 v[134:135], v[132:133], v[174:175], v[176:177]
	v_pk_fma_f32 v[146:147], v[144:145], v[174:175], v[176:177]
	v_pk_fma_f32 v[134:135], v[132:133], v[134:135], v[178:179]
	v_pk_fma_f32 v[146:147], v[144:145], v[146:147], v[178:179]
	v_pk_fma_f32 v[134:135], v[132:133], v[134:135], v[180:181]
	v_pk_fma_f32 v[146:147], v[144:145], v[146:147], v[180:181]
	v_pk_fma_f32 v[134:135], v[132:133], v[134:135], v[186:187]
	v_pk_fma_f32 v[146:147], v[144:145], v[146:147], v[186:187]
	v_pk_fma_f32 v[134:135], v[132:133], v[134:135], v[188:189]
	v_pk_fma_f32 v[146:147], v[144:145], v[146:147], v[188:189]
	v_pk_fma_f32 v[134:135], v[132:133], v[134:135], v[190:191]
	v_pk_fma_f32 v[146:147], v[144:145], v[146:147], v[190:191]
	v_pk_fma_f32 v[134:135], v[132:133], v[134:135], v[132:133]
	v_pk_fma_f32 v[146:147], v[144:145], v[146:147], v[144:145]
	v_pk_mul_f32 v[134:135], v[134:135], v[172:173]
	v_pk_mul_f32 v[146:147], v[146:147], v[172:173]
	v_pk_mul_f32 v[136:137], v[130:131], v[130:131]
	v_pk_mul_f32 v[148:149], v[142:143], v[142:143]
	v_exp_f32_e32 v134, v134
	v_exp_f32_e32 v146, v146
	v_exp_f32_e32 v135, v135
	v_exp_f32_e32 v147, v147
	v_pk_fma_f32 v[138:139], v[136:137], v[192:193], v[194:195]
	v_pk_fma_f32 v[150:151], v[148:149], v[192:193], v[194:195]
	v_pk_fma_f32 v[138:139], v[136:137], v[138:139], v[196:197]
	v_pk_fma_f32 v[150:151], v[148:149], v[150:151], v[196:197]
	v_pk_fma_f32 v[138:139], v[136:137], v[138:139], v[224:225]
	v_pk_fma_f32 v[150:151], v[148:149], v[150:151], v[224:225]
	v_pk_fma_f32 v[138:139], v[136:137], v[138:139], v[226:227]
	v_pk_fma_f32 v[150:151], v[148:149], v[150:151], v[226:227]
	v_pk_fma_f32 v[138:139], v[136:137], v[138:139], v[228:229]
	v_pk_fma_f32 v[150:151], v[148:149], v[150:151], v[228:229]
	v_pk_fma_f32 v[134:135], v[134:135], v[234:235], v[230:231]
	v_pk_fma_f32 v[146:147], v[146:147], v[234:235], v[230:231]
	v_pk_fma_f32 v[138:139], v[132:133], v[138:139], v[132:133]
	v_pk_fma_f32 v[150:151], v[144:145], v[150:151], v[144:145]
	v_pk_mul_f32 v[140:141], v[36:37], v[232:233]
	v_pk_mul_f32 v[152:153], v[38:39], v[232:233]
	v_cmp_ngt_f32_e32 vcc, 1.0, v132
	v_cmp_ngt_f32_e64 s[8:9], 1.0, v133
	v_readlane_b32 s6, v252, 33
	v_readlane_b32 s7, v252, 34
	v_cndmask_b32_e32 v138, v138, v134, vcc
	v_cndmask_b32_e64 v139, v139, v135, s[8:9]
	v_cmp_ngt_f32_e32 vcc, 1.0, v144
	v_cmp_ngt_f32_e64 s[8:9], 1.0, v145
	v_bfi_b32 v138, s37, v138, v130
	v_bfi_b32 v139, s37, v139, v131
	v_cndmask_b32_e32 v150, v150, v146, vcc
	v_cndmask_b32_e64 v151, v151, v147, s[8:9]
	v_pk_add_f32 v[138:139], v[138:139], v[230:231]
	v_bfi_b32 v150, s37, v150, v142
	v_bfi_b32 v151, s37, v151, v143
	v_pk_add_f32 v[150:151], v[150:151], v[230:231]
	v_pk_mul_f32 v[138:139], v[140:141], v[138:139]
	v_lshl_add_u64 v[36:37], s[6:7], 0, v[40:41]
	v_pk_mul_f32 v[150:151], v[152:153], v[150:151]
	v_lshl_add_u64 v[36:37], v[182:183], 1, v[36:37]
	v_cvt_pk_bf16_f32 v38, v138, v139
	v_cvt_pk_bf16_f32 v39, v150, v151
	global_store_dwordx2 v[36:37], v[38:39], off offset:-2016

; DI void st_bf4(u16* p, float a, float b, float c, float d) { *(uint2*)p = make_uint2(pk2(a, b), pk2(c, d)); }
; DI float gelu_f(float x) { return 0.5f * x * (1.f + erff(x * 0.70710678118654752f)); }
;   template <int NT, int MT> DI void run(f32x4 (&acc)[NT][MT], int mb, int nb) const {
;     ...
;         } else if (n < 3072) {
;           st_bf4(uvbuf + (size_t)m * 2048 + (n - 1024), gelu_f(v[0]), gelu_f(v[1]), gelu_f(v[2]), gelu_f(v[3]));
.LBB0_1504:
	s_andn2_saveexec_b64 s[46:47], s[46:47]
	s_cbranch_execz .LBB0_1522
	v_pk_mul_f32 v[130:131], v[32:33], v[170:171]
	v_pk_mul_f32 v[142:143], v[34:35], v[170:171]
	v_and_b32_e32 v132, 0x7fffffff, v130
	v_and_b32_e32 v144, 0x7fffffff, v142
	v_and_b32_e32 v133, 0x7fffffff, v131
	v_and_b32_e32 v145, 0x7fffffff, v143
	v_pk_fma_f32 v[134:135], v[132:133], v[174:175], v[176:177]
	v_pk_fma_f32 v[146:147], v[144:145], v[174:175], v[176:177]
	v_pk_fma_f32 v[134:135], v[132:133], v[134:135], v[178:179]
	v_pk_fma_f32 v[146:147], v[144:145], v[146:147], v[178:179]
	v_pk_fma_f32 v[134:135], v[132:133], v[134:135], v[180:181]
	v_pk_fma_f32 v[146:147], v[144:145], v[146:147], v[180:181]
	v_pk_fma_f32 v[134:135], v[132:133], v[134:135], v[186:187]
	v_pk_fma_f32 v[146:147], v[144:145], v[146:147], v[186:187]
	v_pk_fma_f32 v[134:135], v[132:133], v[134:135], v[188:189]
	v_pk_fma_f32 v[146:147], v[144:145], v[146:147], v[188:189]
	v_pk_fma_f32 v[134:135], v[132:133], v[134:135], v[190:191]
	v_pk_fma_f32 v[146:147], v[144:145], v[146:147], v[190:191]
	v_pk_fma_f32 v[134:135], v[132:133], v[134:135], v[132:133]
	v_pk_fma_f32 v[146:147], v[144:145], v[146:147], v[144:145]
	v_pk_mul_f32 v[134:135], v[134:135], v[172:173]
	v_pk_mul_f32 v[146:147], v[146:147], v[172:173]
	v_pk_mul_f32 v[136:137], v[130:131], v[130:131]
	v_pk_mul_f32 v[148:149], v[142:143], v[142:143]
	v_exp_f32_e32 v134, v134
	v_exp_f32_e32 v146, v146
	v_exp_f32_e32 v135, v135
	v_exp_f32_e32 v147, v147
	v_pk_fma_f32 v[138:139], v[136:137], v[192:193], v[194:195]
	v_pk_fma_f32 v[150:151], v[148:149], v[192:193], v[194:195]
	v_pk_fma_f32 v[138:139], v[136:137], v[138:139], v[196:197]
	v_pk_fma_f32 v[150:151], v[148:149], v[150:151], v[196:197]
	v_pk_fma_f32 v[138:139], v[136:137], v[138:139], v[224:225]
	v_pk_fma_f32 v[150:151], v[148:149], v[150:151], v[224:225]
	v_pk_fma_f32 v[138:139], v[136:137], v[138:139], v[226:227]
	v_pk_fma_f32 v[150:151], v[148:149], v[150:151], v[226:227]
	v_pk_fma_f32 v[138:139], v[136:137], v[138:139], v[228:229]
	v_pk_fma_f32 v[150:151], v[148:149], v[150:151], v[228:229]
	v_pk_fma_f32 v[134:135], v[134:135], v[234:235], v[230:231]
	v_pk_fma_f32 v[146:147], v[146:147], v[234:235], v[230:231]
	v_pk_fma_f32 v[138:139], v[132:133], v[138:139], v[132:133]
	v_pk_fma_f32 v[150:151], v[144:145], v[150:151], v[144:145]
	v_pk_mul_f32 v[140:141], v[32:33], v[232:233]
	v_pk_mul_f32 v[152:153], v[34:35], v[232:233]
	v_cmp_ngt_f32_e32 vcc, 1.0, v132
	v_cmp_ngt_f32_e64 s[8:9], 1.0, v133
	v_readlane_b32 s6, v252, 33
	v_readlane_b32 s7, v252, 34
	v_cndmask_b32_e32 v138, v138, v134, vcc
	v_cndmask_b32_e64 v139, v139, v135, s[8:9]
	v_cmp_ngt_f32_e32 vcc, 1.0, v144
	v_cmp_ngt_f32_e64 s[8:9], 1.0, v145
	v_bfi_b32 v138, s37, v138, v130
	v_bfi_b32 v139, s37, v139, v131
	v_cndmask_b32_e32 v150, v150, v146, vcc
	v_cndmask_b32_e64 v151, v151, v147, s[8:9]
	v_pk_add_f32 v[138:139], v[138:139], v[230:231]
	v_bfi_b32 v150, s37, v150, v142
	v_bfi_b32 v151, s37, v151, v143
	v_pk_add_f32 v[150:151], v[150:151], v[230:231]
	v_pk_mul_f32 v[138:139], v[140:141], v[138:139]
	v_lshl_add_u64 v[32:33], s[6:7], 0, v[36:37]
	v_pk_mul_f32 v[150:151], v[152:153], v[150:151]
	v_lshl_add_u64 v[32:33], v[182:183], 1, v[32:33]
	v_cvt_pk_bf16_f32 v34, v138, v139
	v_cvt_pk_bf16_f32 v35, v150, v151
	global_store_dwordx2 v[32:33], v[34:35], off offset:-2016

; DI void st_bf4(u16* p, float a, float b, float c, float d) { *(uint2*)p = make_uint2(pk2(a, b), pk2(c, d)); }
; DI float gelu_f(float x) { return 0.5f * x * (1.f + erff(x * 0.70710678118654752f)); }
;   template <int NT, int MT> DI void run(f32x4 (&acc)[NT][MT], int mb, int nb) const {
;     ...
;         } else if (n < 3072) {
;           st_bf4(uvbuf + (size_t)m * 2048 + (n - 1024), gelu_f(v[0]), gelu_f(v[1]), gelu_f(v[2]), gelu_f(v[3]));
.LBB0_1534:
	s_andn2_saveexec_b64 s[48:49], s[48:49]
	s_cbranch_execz .LBB0_1552
	v_pk_mul_f32 v[130:131], v[28:29], v[170:171]
	v_pk_mul_f32 v[142:143], v[30:31], v[170:171]
	v_and_b32_e32 v132, 0x7fffffff, v130
	v_and_b32_e32 v144, 0x7fffffff, v142
	v_and_b32_e32 v133, 0x7fffffff, v131
	v_and_b32_e32 v145, 0x7fffffff, v143
	v_pk_fma_f32 v[134:135], v[132:133], v[174:175], v[176:177]
	v_pk_fma_f32 v[146:147], v[144:145], v[174:175], v[176:177]
	v_pk_fma_f32 v[134:135], v[132:133], v[134:135], v[178:179]
	v_pk_fma_f32 v[146:147], v[144:145], v[146:147], v[178:179]
	v_pk_fma_f32 v[134:135], v[132:133], v[134:135], v[180:181]
	v_pk_fma_f32 v[146:147], v[144:145], v[146:147], v[180:181]
	v_pk_fma_f32 v[134:135], v[132:133], v[134:135], v[186:187]
	v_pk_fma_f32 v[146:147], v[144:145], v[146:147], v[186:187]
	v_pk_fma_f32 v[134:135], v[132:133], v[134:135], v[188:189]
	v_pk_fma_f32 v[146:147], v[144:145], v[146:147], v[188:189]
	v_pk_fma_f32 v[134:135], v[132:133], v[134:135], v[190:191]
	v_pk_fma_f32 v[146:147], v[144:145], v[146:147], v[190:191]
	v_pk_fma_f32 v[134:135], v[132:133], v[134:135], v[132:133]
	v_pk_fma_f32 v[146:147], v[144:145], v[146:147], v[144:145]
	v_pk_mul_f32 v[134:135], v[134:135], v[172:173]
	v_pk_mul_f32 v[146:147], v[146:147], v[172:173]
	v_pk_mul_f32 v[136:137], v[130:131], v[130:131]
	v_pk_mul_f32 v[148:149], v[142:143], v[142:143]
	v_exp_f32_e32 v134, v134
	v_exp_f32_e32 v146, v146
	v_exp_f32_e32 v135, v135
	v_exp_f32_e32 v147, v147
	v_pk_fma_f32 v[138:139], v[136:137], v[192:193], v[194:195]
	v_pk_fma_f32 v[150:151], v[148:149], v[192:193], v[194:195]
	v_pk_fma_f32 v[138:139], v[136:137], v[138:139], v[196:197]
	v_pk_fma_f32 v[150:151], v[148:149], v[150:151], v[196:197]
	v_pk_fma_f32 v[138:139], v[136:137], v[138:139], v[224:225]
	v_pk_fma_f32 v[150:151], v[148:149], v[150:151], v[224:225]
	v_pk_fma_f32 v[138:139], v[136:137], v[138:139], v[226:227]
	v_pk_fma_f32 v[150:151], v[148:149], v[150:151], v[226:227]
	v_pk_fma_f32 v[138:139], v[136:137], v[138:139], v[228:229]
	v_pk_fma_f32 v[150:151], v[148:149], v[150:151], v[228:229]
	v_pk_fma_f32 v[134:135], v[134:135], v[234:235], v[230:231]
	v_pk_fma_f32 v[146:147], v[146:147], v[234:235], v[230:231]
	v_pk_fma_f32 v[138:139], v[132:133], v[138:139], v[132:133]
	v_pk_fma_f32 v[150:151], v[144:145], v[150:151], v[144:145]
	v_pk_mul_f32 v[140:141], v[28:29], v[232:233]
	v_pk_mul_f32 v[152:153], v[30:31], v[232:233]
	v_cmp_ngt_f32_e32 vcc, 1.0, v132
	v_cmp_ngt_f32_e64 s[8:9], 1.0, v133
	v_readlane_b32 s6, v252, 33
	v_readlane_b32 s7, v252, 34
	v_cndmask_b32_e32 v138, v138, v134, vcc
	v_cndmask_b32_e64 v139, v139, v135, s[8:9]
	v_cmp_ngt_f32_e32 vcc, 1.0, v144
	v_cmp_ngt_f32_e64 s[8:9], 1.0, v145
	v_bfi_b32 v138, s37, v138, v130
	v_bfi_b32 v139, s37, v139, v131
	v_cndmask_b32_e32 v150, v150, v146, vcc
	v_cndmask_b32_e64 v151, v151, v147, s[8:9]
	v_pk_add_f32 v[138:139], v[138:139], v[230:231]
	v_bfi_b32 v150, s37, v150, v142
	v_bfi_b32 v151, s37, v151, v143
	v_pk_add_f32 v[150:151], v[150:151], v[230:231]
	v_pk_mul_f32 v[138:139], v[140:141], v[138:139]
	v_lshl_add_u64 v[28:29], s[6:7], 0, v[32:33]
	v_pk_mul_f32 v[150:151], v[152:153], v[150:151]
	v_lshl_add_u64 v[28:29], v[182:183], 1, v[28:29]
	v_cvt_pk_bf16_f32 v30, v138, v139
	v_cvt_pk_bf16_f32 v31, v150, v151
	global_store_dwordx2 v[28:29], v[30:31], off offset:-1984

; DI void st_bf4(u16* p, float a, float b, float c, float d) { *(uint2*)p = make_uint2(pk2(a, b), pk2(c, d)); }
; DI float gelu_f(float x) { return 0.5f * x * (1.f + erff(x * 0.70710678118654752f)); }
;   template <int NT, int MT> DI void run(f32x4 (&acc)[NT][MT], int mb, int nb) const {
;     ...
;         } else if (n < 3072) {
;           st_bf4(uvbuf + (size_t)m * 2048 + (n - 1024), gelu_f(v[0]), gelu_f(v[1]), gelu_f(v[2]), gelu_f(v[3]));
.LBB0_1558:
	s_andn2_saveexec_b64 s[48:49], s[48:49]
	s_cbranch_execz .LBB0_1576
	v_pk_mul_f32 v[130:131], v[24:25], v[170:171]
	v_pk_mul_f32 v[142:143], v[26:27], v[170:171]
	v_and_b32_e32 v132, 0x7fffffff, v130
	v_and_b32_e32 v144, 0x7fffffff, v142
	v_and_b32_e32 v133, 0x7fffffff, v131
	v_and_b32_e32 v145, 0x7fffffff, v143
	v_pk_fma_f32 v[134:135], v[132:133], v[174:175], v[176:177]
	v_pk_fma_f32 v[146:147], v[144:145], v[174:175], v[176:177]
	v_pk_fma_f32 v[134:135], v[132:133], v[134:135], v[178:179]
	v_pk_fma_f32 v[146:147], v[144:145], v[146:147], v[178:179]
	v_pk_fma_f32 v[134:135], v[132:133], v[134:135], v[180:181]
	v_pk_fma_f32 v[146:147], v[144:145], v[146:147], v[180:181]
	v_pk_fma_f32 v[134:135], v[132:133], v[134:135], v[186:187]
	v_pk_fma_f32 v[146:147], v[144:145], v[146:147], v[186:187]
	v_pk_fma_f32 v[134:135], v[132:133], v[134:135], v[188:189]
	v_pk_fma_f32 v[146:147], v[144:145], v[146:147], v[188:189]
	v_pk_fma_f32 v[134:135], v[132:133], v[134:135], v[190:191]
	v_pk_fma_f32 v[146:147], v[144:145], v[146:147], v[190:191]
	v_pk_fma_f32 v[134:135], v[132:133], v[134:135], v[132:133]
	v_pk_fma_f32 v[146:147], v[144:145], v[146:147], v[144:145]
	v_pk_mul_f32 v[134:135], v[134:135], v[172:173]
	v_pk_mul_f32 v[146:147], v[146:147], v[172:173]
	v_pk_mul_f32 v[136:137], v[130:131], v[130:131]
	v_pk_mul_f32 v[148:149], v[142:143], v[142:143]
	v_exp_f32_e32 v134, v134
	v_exp_f32_e32 v146, v146
	v_exp_f32_e32 v135, v135
	v_exp_f32_e32 v147, v147
	v_pk_fma_f32 v[138:139], v[136:137], v[192:193], v[194:195]
	v_pk_fma_f32 v[150:151], v[148:149], v[192:193], v[194:195]
	v_pk_fma_f32 v[138:139], v[136:137], v[138:139], v[196:197]
	v_pk_fma_f32 v[150:151], v[148:149], v[150:151], v[196:197]
	v_pk_fma_f32 v[138:139], v[136:137], v[138:139], v[224:225]
	v_pk_fma_f32 v[150:151], v[148:149], v[150:151], v[224:225]
	v_pk_fma_f32 v[138:139], v[136:137], v[138:139], v[226:227]
	v_pk_fma_f32 v[150:151], v[148:149], v[150:151], v[226:227]
	v_pk_fma_f32 v[138:139], v[136:137], v[138:139], v[228:229]
	v_pk_fma_f32 v[150:151], v[148:149], v[150:151], v[228:229]
	v_pk_fma_f32 v[134:135], v[134:135], v[234:235], v[230:231]
	v_pk_fma_f32 v[146:147], v[146:147], v[234:235], v[230:231]
	v_pk_fma_f32 v[138:139], v[132:133], v[138:139], v[132:133]
	v_pk_fma_f32 v[150:151], v[144:145], v[150:151], v[144:145]
	v_pk_mul_f32 v[140:141], v[24:25], v[232:233]
	v_pk_mul_f32 v[152:153], v[26:27], v[232:233]
	v_cmp_ngt_f32_e32 vcc, 1.0, v132
	v_cmp_ngt_f32_e64 s[8:9], 1.0, v133
	v_readlane_b32 s6, v252, 33
	v_readlane_b32 s7, v252, 34
	v_cndmask_b32_e32 v138, v138, v134, vcc
	v_cndmask_b32_e64 v139, v139, v135, s[8:9]
	v_cmp_ngt_f32_e32 vcc, 1.0, v144
	v_cmp_ngt_f32_e64 s[8:9], 1.0, v145
	v_bfi_b32 v138, s37, v138, v130
	v_bfi_b32 v139, s37, v139, v131
	v_cndmask_b32_e32 v150, v150, v146, vcc
	v_cndmask_b32_e64 v151, v151, v147, s[8:9]
	v_pk_add_f32 v[138:139], v[138:139], v[230:231]
	v_bfi_b32 v150, s37, v150, v142
	v_bfi_b32 v151, s37, v151, v143
	v_pk_add_f32 v[150:151], v[150:151], v[230:231]
	v_pk_mul_f32 v[138:139], v[140:141], v[138:139]
	v_lshl_add_u64 v[24:25], s[6:7], 0, v[28:29]
	v_pk_mul_f32 v[150:151], v[152:153], v[150:151]
	v_lshl_add_u64 v[24:25], v[182:183], 1, v[24:25]
	v_cvt_pk_bf16_f32 v26, v138, v139
	v_cvt_pk_bf16_f32 v27, v150, v151
	global_store_dwordx2 v[24:25], v[26:27], off offset:-1984

; DI void st_bf4(u16* p, float a, float b, float c, float d) { *(uint2*)p = make_uint2(pk2(a, b), pk2(c, d)); }
; DI float gelu_f(float x) { return 0.5f * x * (1.f + erff(x * 0.70710678118654752f)); }
;   template <int NT, int MT> DI void run(f32x4 (&acc)[NT][MT], int mb, int nb) const {
;     ...
;         } else if (n < 3072) {
;           st_bf4(uvbuf + (size_t)m * 2048 + (n - 1024), gelu_f(v[0]), gelu_f(v[1]), gelu_f(v[2]), gelu_f(v[3]));
.LBB0_1588:
	s_andn2_saveexec_b64 s[48:49], s[48:49]
	s_cbranch_execz .LBB0_1606
	v_pk_mul_f32 v[130:131], v[20:21], v[170:171]
	v_pk_mul_f32 v[142:143], v[22:23], v[170:171]
	v_and_b32_e32 v132, 0x7fffffff, v130
	v_and_b32_e32 v144, 0x7fffffff, v142
	v_and_b32_e32 v133, 0x7fffffff, v131
	v_and_b32_e32 v145, 0x7fffffff, v143
	v_pk_fma_f32 v[134:135], v[132:133], v[174:175], v[176:177]
	v_pk_fma_f32 v[146:147], v[144:145], v[174:175], v[176:177]
	v_pk_fma_f32 v[134:135], v[132:133], v[134:135], v[178:179]
	v_pk_fma_f32 v[146:147], v[144:145], v[146:147], v[178:179]
	v_pk_fma_f32 v[134:135], v[132:133], v[134:135], v[180:181]
	v_pk_fma_f32 v[146:147], v[144:145], v[146:147], v[180:181]
	v_pk_fma_f32 v[134:135], v[132:133], v[134:135], v[186:187]
	v_pk_fma_f32 v[146:147], v[144:145], v[146:147], v[186:187]
	v_pk_fma_f32 v[134:135], v[132:133], v[134:135], v[188:189]
	v_pk_fma_f32 v[146:147], v[144:145], v[146:147], v[188:189]
	v_pk_fma_f32 v[134:135], v[132:133], v[134:135], v[190:191]
	v_pk_fma_f32 v[146:147], v[144:145], v[146:147], v[190:191]
	v_pk_fma_f32 v[134:135], v[132:133], v[134:135], v[132:133]
	v_pk_fma_f32 v[146:147], v[144:145], v[146:147], v[144:145]
	v_pk_mul_f32 v[134:135], v[134:135], v[172:173]
	v_pk_mul_f32 v[146:147], v[146:147], v[172:173]
	v_pk_mul_f32 v[136:137], v[130:131], v[130:131]
	v_pk_mul_f32 v[148:149], v[142:143], v[142:143]
	v_exp_f32_e32 v134, v134
	v_exp_f32_e32 v146, v146
	v_exp_f32_e32 v135, v135
	v_exp_f32_e32 v147, v147
	v_pk_fma_f32 v[138:139], v[136:137], v[192:193], v[194:195]
	v_pk_fma_f32 v[150:151], v[148:149], v[192:193], v[194:195]
	v_pk_fma_f32 v[138:139], v[136:137], v[138:139], v[196:197]
	v_pk_fma_f32 v[150:151], v[148:149], v[150:151], v[196:197]
	v_pk_fma_f32 v[138:139], v[136:137], v[138:139], v[224:225]
	v_pk_fma_f32 v[150:151], v[148:149], v[150:151], v[224:225]
	v_pk_fma_f32 v[138:139], v[136:137], v[138:139], v[226:227]
	v_pk_fma_f32 v[150:151], v[148:149], v[150:151], v[226:227]
	v_pk_fma_f32 v[138:139], v[136:137], v[138:139], v[228:229]
	v_pk_fma_f32 v[150:151], v[148:149], v[150:151], v[228:229]
	v_pk_fma_f32 v[134:135], v[134:135], v[234:235], v[230:231]
	v_pk_fma_f32 v[146:147], v[146:147], v[234:235], v[230:231]
	v_pk_fma_f32 v[138:139], v[132:133], v[138:139], v[132:133]
	v_pk_fma_f32 v[150:151], v[144:145], v[150:151], v[144:145]
	v_pk_mul_f32 v[140:141], v[20:21], v[232:233]
	v_pk_mul_f32 v[152:153], v[22:23], v[232:233]
	v_cmp_ngt_f32_e32 vcc, 1.0, v132
	v_cmp_ngt_f32_e64 s[8:9], 1.0, v133
	v_readlane_b32 s6, v252, 33
	v_readlane_b32 s7, v252, 34
	v_cndmask_b32_e32 v138, v138, v134, vcc
	v_cndmask_b32_e64 v139, v139, v135, s[8:9]
	v_cmp_ngt_f32_e32 vcc, 1.0, v144
	v_cmp_ngt_f32_e64 s[8:9], 1.0, v145
	v_bfi_b32 v138, s37, v138, v130
	v_bfi_b32 v139, s37, v139, v131
	v_cndmask_b32_e32 v150, v150, v146, vcc
	v_cndmask_b32_e64 v151, v151, v147, s[8:9]
	v_pk_add_f32 v[138:139], v[138:139], v[230:231]
	v_bfi_b32 v150, s37, v150, v142
	v_bfi_b32 v151, s37, v151, v143
	v_pk_add_f32 v[150:151], v[150:151], v[230:231]
	v_pk_mul_f32 v[138:139], v[140:141], v[138:139]
	v_lshl_add_u64 v[20:21], s[6:7], 0, v[24:25]
	v_pk_mul_f32 v[150:151], v[152:153], v[150:151]
	v_lshl_add_u64 v[20:21], v[182:183], 1, v[20:21]
	v_cvt_pk_bf16_f32 v22, v138, v139
	v_cvt_pk_bf16_f32 v23, v150, v151
	global_store_dwordx2 v[20:21], v[22:23], off offset:-1984

; DI void st_bf4(u16* p, float a, float b, float c, float d) { *(uint2*)p = make_uint2(pk2(a, b), pk2(c, d)); }
; DI float gelu_f(float x) { return 0.5f * x * (1.f + erff(x * 0.70710678118654752f)); }
;   template <int NT, int MT> DI void run(f32x4 (&acc)[NT][MT], int mb, int nb) const {
;     ...
;         } else if (n < 3072) {
;           st_bf4(uvbuf + (size_t)m * 2048 + (n - 1024), gelu_f(v[0]), gelu_f(v[1]), gelu_f(v[2]), gelu_f(v[3]));
.LBB0_1612:
	s_andn2_saveexec_b64 s[46:47], s[46:47]
	s_cbranch_execz .LBB0_1630
	v_pk_mul_f32 v[130:131], v[16:17], v[170:171]
	v_pk_mul_f32 v[142:143], v[18:19], v[170:171]
	v_and_b32_e32 v132, 0x7fffffff, v130
	v_and_b32_e32 v144, 0x7fffffff, v142
	v_and_b32_e32 v133, 0x7fffffff, v131
	v_and_b32_e32 v145, 0x7fffffff, v143
	v_pk_fma_f32 v[134:135], v[132:133], v[174:175], v[176:177]
	v_pk_fma_f32 v[146:147], v[144:145], v[174:175], v[176:177]
	v_pk_fma_f32 v[134:135], v[132:133], v[134:135], v[178:179]
	v_pk_fma_f32 v[146:147], v[144:145], v[146:147], v[178:179]
	v_pk_fma_f32 v[134:135], v[132:133], v[134:135], v[180:181]
	v_pk_fma_f32 v[146:147], v[144:145], v[146:147], v[180:181]
	v_pk_fma_f32 v[134:135], v[132:133], v[134:135], v[186:187]
	v_pk_fma_f32 v[146:147], v[144:145], v[146:147], v[186:187]
	v_pk_fma_f32 v[134:135], v[132:133], v[134:135], v[188:189]
	v_pk_fma_f32 v[146:147], v[144:145], v[146:147], v[188:189]
	v_pk_fma_f32 v[134:135], v[132:133], v[134:135], v[190:191]
	v_pk_fma_f32 v[146:147], v[144:145], v[146:147], v[190:191]
	v_pk_fma_f32 v[134:135], v[132:133], v[134:135], v[132:133]
	v_pk_fma_f32 v[146:147], v[144:145], v[146:147], v[144:145]
	v_pk_mul_f32 v[134:135], v[134:135], v[172:173]
	v_pk_mul_f32 v[146:147], v[146:147], v[172:173]
	v_pk_mul_f32 v[136:137], v[130:131], v[130:131]
	v_pk_mul_f32 v[148:149], v[142:143], v[142:143]
	v_exp_f32_e32 v134, v134
	v_exp_f32_e32 v146, v146
	v_exp_f32_e32 v135, v135
	v_exp_f32_e32 v147, v147
	v_pk_fma_f32 v[138:139], v[136:137], v[192:193], v[194:195]
	v_pk_fma_f32 v[150:151], v[148:149], v[192:193], v[194:195]
	v_pk_fma_f32 v[138:139], v[136:137], v[138:139], v[196:197]
	v_pk_fma_f32 v[150:151], v[148:149], v[150:151], v[196:197]
	v_pk_fma_f32 v[138:139], v[136:137], v[138:139], v[224:225]
	v_pk_fma_f32 v[150:151], v[148:149], v[150:151], v[224:225]
	v_pk_fma_f32 v[138:139], v[136:137], v[138:139], v[226:227]
	v_pk_fma_f32 v[150:151], v[148:149], v[150:151], v[226:227]
	v_pk_fma_f32 v[138:139], v[136:137], v[138:139], v[228:229]
	v_pk_fma_f32 v[150:151], v[148:149], v[150:151], v[228:229]
	v_pk_fma_f32 v[134:135], v[134:135], v[234:235], v[230:231]
	v_pk_fma_f32 v[146:147], v[146:147], v[234:235], v[230:231]
	v_pk_fma_f32 v[138:139], v[132:133], v[138:139], v[132:133]
	v_pk_fma_f32 v[150:151], v[144:145], v[150:151], v[144:145]
	v_pk_mul_f32 v[140:141], v[16:17], v[232:233]
	v_pk_mul_f32 v[152:153], v[18:19], v[232:233]
	v_cmp_ngt_f32_e32 vcc, 1.0, v132
	v_cmp_ngt_f32_e64 s[8:9], 1.0, v133
	v_readlane_b32 s6, v252, 33
	v_readlane_b32 s7, v252, 34
	v_cndmask_b32_e32 v138, v138, v134, vcc
	v_cndmask_b32_e64 v139, v139, v135, s[8:9]
	v_cmp_ngt_f32_e32 vcc, 1.0, v144
	v_cmp_ngt_f32_e64 s[8:9], 1.0, v145
	v_bfi_b32 v138, s37, v138, v130
	v_bfi_b32 v139, s37, v139, v131
	v_cndmask_b32_e32 v150, v150, v146, vcc
	v_cndmask_b32_e64 v151, v151, v147, s[8:9]
	v_pk_add_f32 v[138:139], v[138:139], v[230:231]
	v_bfi_b32 v150, s37, v150, v142
	v_bfi_b32 v151, s37, v151, v143
	v_pk_add_f32 v[150:151], v[150:151], v[230:231]
	v_pk_mul_f32 v[138:139], v[140:141], v[138:139]
	v_lshl_add_u64 v[16:17], s[6:7], 0, v[20:21]
	v_pk_mul_f32 v[150:151], v[152:153], v[150:151]
	v_lshl_add_u64 v[16:17], v[182:183], 1, v[16:17]
	v_cvt_pk_bf16_f32 v18, v138, v139
	v_cvt_pk_bf16_f32 v19, v150, v151
	global_store_dwordx2 v[16:17], v[18:19], off offset:-1984

; DI void st_bf4(u16* p, float a, float b, float c, float d) { *(uint2*)p = make_uint2(pk2(a, b), pk2(c, d)); }
; DI float gelu_f(float x) { return 0.5f * x * (1.f + erff(x * 0.70710678118654752f)); }
;   template <int NT, int MT> DI void run(f32x4 (&acc)[NT][MT], int mb, int nb) const {
;     ...
;         } else if (n < 3072) {
;           st_bf4(uvbuf + (size_t)m * 2048 + (n - 1024), gelu_f(v[0]), gelu_f(v[1]), gelu_f(v[2]), gelu_f(v[3]));
.LBB0_1642:
	s_andn2_saveexec_b64 s[48:49], s[48:49]
	s_cbranch_execz .LBB0_1660
	v_pk_mul_f32 v[130:131], v[12:13], v[170:171]
	v_pk_mul_f32 v[142:143], v[14:15], v[170:171]
	v_and_b32_e32 v132, 0x7fffffff, v130
	v_and_b32_e32 v144, 0x7fffffff, v142
	v_and_b32_e32 v133, 0x7fffffff, v131
	v_and_b32_e32 v145, 0x7fffffff, v143
	v_pk_fma_f32 v[134:135], v[132:133], v[174:175], v[176:177]
	v_pk_fma_f32 v[146:147], v[144:145], v[174:175], v[176:177]
	v_pk_fma_f32 v[134:135], v[132:133], v[134:135], v[178:179]
	v_pk_fma_f32 v[146:147], v[144:145], v[146:147], v[178:179]
	v_pk_fma_f32 v[134:135], v[132:133], v[134:135], v[180:181]
	v_pk_fma_f32 v[146:147], v[144:145], v[146:147], v[180:181]
	v_pk_fma_f32 v[134:135], v[132:133], v[134:135], v[186:187]
	v_pk_fma_f32 v[146:147], v[144:145], v[146:147], v[186:187]
	v_pk_fma_f32 v[134:135], v[132:133], v[134:135], v[188:189]
	v_pk_fma_f32 v[146:147], v[144:145], v[146:147], v[188:189]
	v_pk_fma_f32 v[134:135], v[132:133], v[134:135], v[190:191]
	v_pk_fma_f32 v[146:147], v[144:145], v[146:147], v[190:191]
	v_pk_fma_f32 v[134:135], v[132:133], v[134:135], v[132:133]
	v_pk_fma_f32 v[146:147], v[144:145], v[146:147], v[144:145]
	v_pk_mul_f32 v[134:135], v[134:135], v[172:173]
	v_pk_mul_f32 v[146:147], v[146:147], v[172:173]
	v_pk_mul_f32 v[136:137], v[130:131], v[130:131]
	v_pk_mul_f32 v[148:149], v[142:143], v[142:143]
	v_exp_f32_e32 v134, v134
	v_exp_f32_e32 v146, v146
	v_exp_f32_e32 v135, v135
	v_exp_f32_e32 v147, v147
	v_pk_fma_f32 v[138:139], v[136:137], v[192:193], v[194:195]
	v_pk_fma_f32 v[150:151], v[148:149], v[192:193], v[194:195]
	v_pk_fma_f32 v[138:139], v[136:137], v[138:139], v[196:197]
	v_pk_fma_f32 v[150:151], v[148:149], v[150:151], v[196:197]
	v_pk_fma_f32 v[138:139], v[136:137], v[138:139], v[224:225]
	v_pk_fma_f32 v[150:151], v[148:149], v[150:151], v[224:225]
	v_pk_fma_f32 v[138:139], v[136:137], v[138:139], v[226:227]
	v_pk_fma_f32 v[150:151], v[148:149], v[150:151], v[226:227]
	v_pk_fma_f32 v[138:139], v[136:137], v[138:139], v[228:229]
	v_pk_fma_f32 v[150:151], v[148:149], v[150:151], v[228:229]
	v_pk_fma_f32 v[134:135], v[134:135], v[234:235], v[230:231]
	v_pk_fma_f32 v[146:147], v[146:147], v[234:235], v[230:231]
	v_pk_fma_f32 v[138:139], v[132:133], v[138:139], v[132:133]
	v_pk_fma_f32 v[150:151], v[144:145], v[150:151], v[144:145]
	v_pk_mul_f32 v[140:141], v[12:13], v[232:233]
	v_pk_mul_f32 v[152:153], v[14:15], v[232:233]
	v_cmp_ngt_f32_e32 vcc, 1.0, v132
	v_cmp_ngt_f32_e64 s[8:9], 1.0, v133
	v_readlane_b32 s6, v252, 33
	v_readlane_b32 s7, v252, 34
	v_cndmask_b32_e32 v138, v138, v134, vcc
	v_cndmask_b32_e64 v139, v139, v135, s[8:9]
	v_cmp_ngt_f32_e32 vcc, 1.0, v144
	v_cmp_ngt_f32_e64 s[8:9], 1.0, v145
	v_bfi_b32 v138, s37, v138, v130
	v_bfi_b32 v139, s37, v139, v131
	v_cndmask_b32_e32 v150, v150, v146, vcc
	v_cndmask_b32_e64 v151, v151, v147, s[8:9]
	v_pk_add_f32 v[138:139], v[138:139], v[230:231]
	v_bfi_b32 v150, s37, v150, v142
	v_bfi_b32 v151, s37, v151, v143
	v_pk_add_f32 v[150:151], v[150:151], v[230:231]
	v_pk_mul_f32 v[138:139], v[140:141], v[138:139]
	v_lshl_add_u64 v[12:13], s[6:7], 0, v[16:17]
	v_pk_mul_f32 v[150:151], v[152:153], v[150:151]
	v_lshl_add_u64 v[12:13], v[182:183], 1, v[12:13]
	v_cvt_pk_bf16_f32 v14, v138, v139
	v_cvt_pk_bf16_f32 v15, v150, v151
	global_store_dwordx2 v[12:13], v[14:15], off offset:-1952

; DI void st_bf4(u16* p, float a, float b, float c, float d) { *(uint2*)p = make_uint2(pk2(a, b), pk2(c, d)); }
; DI float gelu_f(float x) { return 0.5f * x * (1.f + erff(x * 0.70710678118654752f)); }
;   template <int NT, int MT> DI void run(f32x4 (&acc)[NT][MT], int mb, int nb) const {
;     ...
;         } else if (n < 3072) {
;           st_bf4(uvbuf + (size_t)m * 2048 + (n - 1024), gelu_f(v[0]), gelu_f(v[1]), gelu_f(v[2]), gelu_f(v[3]));
.LBB0_1666:
	s_andn2_saveexec_b64 s[48:49], s[48:49]
	s_cbranch_execz .LBB0_1684
	v_pk_mul_f32 v[130:131], v[8:9], v[170:171]
	v_pk_mul_f32 v[142:143], v[10:11], v[170:171]
	v_and_b32_e32 v132, 0x7fffffff, v130
	v_and_b32_e32 v144, 0x7fffffff, v142
	v_and_b32_e32 v133, 0x7fffffff, v131
	v_and_b32_e32 v145, 0x7fffffff, v143
	v_pk_fma_f32 v[134:135], v[132:133], v[174:175], v[176:177]
	v_pk_fma_f32 v[146:147], v[144:145], v[174:175], v[176:177]
	v_pk_fma_f32 v[134:135], v[132:133], v[134:135], v[178:179]
	v_pk_fma_f32 v[146:147], v[144:145], v[146:147], v[178:179]
	v_pk_fma_f32 v[134:135], v[132:133], v[134:135], v[180:181]
	v_pk_fma_f32 v[146:147], v[144:145], v[146:147], v[180:181]
	v_pk_fma_f32 v[134:135], v[132:133], v[134:135], v[186:187]
	v_pk_fma_f32 v[146:147], v[144:145], v[146:147], v[186:187]
	v_pk_fma_f32 v[134:135], v[132:133], v[134:135], v[188:189]
	v_pk_fma_f32 v[146:147], v[144:145], v[146:147], v[188:189]
	v_pk_fma_f32 v[134:135], v[132:133], v[134:135], v[190:191]
	v_pk_fma_f32 v[146:147], v[144:145], v[146:147], v[190:191]
	v_pk_fma_f32 v[134:135], v[132:133], v[134:135], v[132:133]
	v_pk_fma_f32 v[146:147], v[144:145], v[146:147], v[144:145]
	v_pk_mul_f32 v[134:135], v[134:135], v[172:173]
	v_pk_mul_f32 v[146:147], v[146:147], v[172:173]
	v_pk_mul_f32 v[136:137], v[130:131], v[130:131]
	v_pk_mul_f32 v[148:149], v[142:143], v[142:143]
	v_exp_f32_e32 v134, v134
	v_exp_f32_e32 v146, v146
	v_exp_f32_e32 v135, v135
	v_exp_f32_e32 v147, v147
	v_pk_fma_f32 v[138:139], v[136:137], v[192:193], v[194:195]
	v_pk_fma_f32 v[150:151], v[148:149], v[192:193], v[194:195]
	v_pk_fma_f32 v[138:139], v[136:137], v[138:139], v[196:197]
	v_pk_fma_f32 v[150:151], v[148:149], v[150:151], v[196:197]
	v_pk_fma_f32 v[138:139], v[136:137], v[138:139], v[224:225]
	v_pk_fma_f32 v[150:151], v[148:149], v[150:151], v[224:225]
	v_pk_fma_f32 v[138:139], v[136:137], v[138:139], v[226:227]
	v_pk_fma_f32 v[150:151], v[148:149], v[150:151], v[226:227]
	v_pk_fma_f32 v[138:139], v[136:137], v[138:139], v[228:229]
	v_pk_fma_f32 v[150:151], v[148:149], v[150:151], v[228:229]
	v_pk_fma_f32 v[134:135], v[134:135], v[234:235], v[230:231]
	v_pk_fma_f32 v[146:147], v[146:147], v[234:235], v[230:231]
	v_pk_fma_f32 v[138:139], v[132:133], v[138:139], v[132:133]
	v_pk_fma_f32 v[150:151], v[144:145], v[150:151], v[144:145]
	v_pk_mul_f32 v[140:141], v[8:9], v[232:233]
	v_pk_mul_f32 v[152:153], v[10:11], v[232:233]
	v_cmp_ngt_f32_e32 vcc, 1.0, v132
	v_cmp_ngt_f32_e64 s[8:9], 1.0, v133
	v_readlane_b32 s6, v252, 33
	v_readlane_b32 s7, v252, 34
	v_cndmask_b32_e32 v138, v138, v134, vcc
	v_cndmask_b32_e64 v139, v139, v135, s[8:9]
	v_cmp_ngt_f32_e32 vcc, 1.0, v144
	v_cmp_ngt_f32_e64 s[8:9], 1.0, v145
	v_bfi_b32 v138, s37, v138, v130
	v_bfi_b32 v139, s37, v139, v131
	v_cndmask_b32_e32 v150, v150, v146, vcc
	v_cndmask_b32_e64 v151, v151, v147, s[8:9]
	v_pk_add_f32 v[138:139], v[138:139], v[230:231]
	v_bfi_b32 v150, s37, v150, v142
	v_bfi_b32 v151, s37, v151, v143
	v_pk_add_f32 v[150:151], v[150:151], v[230:231]
	v_pk_mul_f32 v[138:139], v[140:141], v[138:139]
	v_lshl_add_u64 v[8:9], s[6:7], 0, v[12:13]
	v_pk_mul_f32 v[150:151], v[152:153], v[150:151]
	v_lshl_add_u64 v[8:9], v[182:183], 1, v[8:9]
	v_cvt_pk_bf16_f32 v10, v138, v139
	v_cvt_pk_bf16_f32 v11, v150, v151
	global_store_dwordx2 v[8:9], v[10:11], off offset:-1952

; DI void st_bf4(u16* p, float a, float b, float c, float d) { *(uint2*)p = make_uint2(pk2(a, b), pk2(c, d)); }
; DI float gelu_f(float x) { return 0.5f * x * (1.f + erff(x * 0.70710678118654752f)); }
;   template <int NT, int MT> DI void run(f32x4 (&acc)[NT][MT], int mb, int nb) const {
;     ...
;         } else if (n < 3072) {
;           st_bf4(uvbuf + (size_t)m * 2048 + (n - 1024), gelu_f(v[0]), gelu_f(v[1]), gelu_f(v[2]), gelu_f(v[3]));
.LBB0_1696:
	s_andn2_saveexec_b64 s[48:49], s[48:49]
	s_cbranch_execz .LBB0_1714
	v_pk_mul_f32 v[130:131], v[4:5], v[170:171]
	v_pk_mul_f32 v[142:143], v[6:7], v[170:171]
	v_and_b32_e32 v132, 0x7fffffff, v130
	v_and_b32_e32 v144, 0x7fffffff, v142
	v_and_b32_e32 v133, 0x7fffffff, v131
	v_and_b32_e32 v145, 0x7fffffff, v143
	v_pk_fma_f32 v[134:135], v[132:133], v[174:175], v[176:177]
	v_pk_fma_f32 v[146:147], v[144:145], v[174:175], v[176:177]
	v_pk_fma_f32 v[134:135], v[132:133], v[134:135], v[178:179]
	v_pk_fma_f32 v[146:147], v[144:145], v[146:147], v[178:179]
	v_pk_fma_f32 v[134:135], v[132:133], v[134:135], v[180:181]
	v_pk_fma_f32 v[146:147], v[144:145], v[146:147], v[180:181]
	v_pk_fma_f32 v[134:135], v[132:133], v[134:135], v[186:187]
	v_pk_fma_f32 v[146:147], v[144:145], v[146:147], v[186:187]
	v_pk_fma_f32 v[134:135], v[132:133], v[134:135], v[188:189]
	v_pk_fma_f32 v[146:147], v[144:145], v[146:147], v[188:189]
	v_pk_fma_f32 v[134:135], v[132:133], v[134:135], v[190:191]
	v_pk_fma_f32 v[146:147], v[144:145], v[146:147], v[190:191]
	v_pk_fma_f32 v[134:135], v[132:133], v[134:135], v[132:133]
	v_pk_fma_f32 v[146:147], v[144:145], v[146:147], v[144:145]
	v_pk_mul_f32 v[134:135], v[134:135], v[172:173]
	v_pk_mul_f32 v[146:147], v[146:147], v[172:173]
	v_pk_mul_f32 v[136:137], v[130:131], v[130:131]
	v_pk_mul_f32 v[148:149], v[142:143], v[142:143]
	v_exp_f32_e32 v134, v134
	v_exp_f32_e32 v146, v146
	v_exp_f32_e32 v135, v135
	v_exp_f32_e32 v147, v147
	v_pk_fma_f32 v[138:139], v[136:137], v[192:193], v[194:195]
	v_pk_fma_f32 v[150:151], v[148:149], v[192:193], v[194:195]
	v_pk_fma_f32 v[138:139], v[136:137], v[138:139], v[196:197]
	v_pk_fma_f32 v[150:151], v[148:149], v[150:151], v[196:197]
	v_pk_fma_f32 v[138:139], v[136:137], v[138:139], v[224:225]
	v_pk_fma_f32 v[150:151], v[148:149], v[150:151], v[224:225]
	v_pk_fma_f32 v[138:139], v[136:137], v[138:139], v[226:227]
	v_pk_fma_f32 v[150:151], v[148:149], v[150:151], v[226:227]
	v_pk_fma_f32 v[138:139], v[136:137], v[138:139], v[228:229]
	v_pk_fma_f32 v[150:151], v[148:149], v[150:151], v[228:229]
	v_pk_fma_f32 v[134:135], v[134:135], v[234:235], v[230:231]
	v_pk_fma_f32 v[146:147], v[146:147], v[234:235], v[230:231]
	v_pk_fma_f32 v[138:139], v[132:133], v[138:139], v[132:133]
	v_pk_fma_f32 v[150:151], v[144:145], v[150:151], v[144:145]
	v_pk_mul_f32 v[140:141], v[4:5], v[232:233]
	v_pk_mul_f32 v[152:153], v[6:7], v[232:233]
	v_cmp_ngt_f32_e32 vcc, 1.0, v132
	v_cmp_ngt_f32_e64 s[8:9], 1.0, v133
	v_readlane_b32 s6, v252, 33
	v_readlane_b32 s7, v252, 34
	v_cndmask_b32_e32 v138, v138, v134, vcc
	v_cndmask_b32_e64 v139, v139, v135, s[8:9]
	v_cmp_ngt_f32_e32 vcc, 1.0, v144
	v_cmp_ngt_f32_e64 s[8:9], 1.0, v145
	v_bfi_b32 v138, s37, v138, v130
	v_bfi_b32 v139, s37, v139, v131
	v_cndmask_b32_e32 v150, v150, v146, vcc
	v_cndmask_b32_e64 v151, v151, v147, s[8:9]
	v_pk_add_f32 v[138:139], v[138:139], v[230:231]
	v_bfi_b32 v150, s37, v150, v142
	v_bfi_b32 v151, s37, v151, v143
	v_pk_add_f32 v[150:151], v[150:151], v[230:231]
	v_pk_mul_f32 v[138:139], v[140:141], v[138:139]
	v_lshl_add_u64 v[4:5], s[6:7], 0, v[8:9]
	v_pk_mul_f32 v[150:151], v[152:153], v[150:151]
	v_lshl_add_u64 v[4:5], v[182:183], 1, v[4:5]
	v_cvt_pk_bf16_f32 v6, v138, v139
	v_cvt_pk_bf16_f32 v7, v150, v151
	global_store_dwordx2 v[4:5], v[6:7], off offset:-1952

; DI void st_bf4(u16* p, float a, float b, float c, float d) { *(uint2*)p = make_uint2(pk2(a, b), pk2(c, d)); }
; DI float gelu_f(float x) { return 0.5f * x * (1.f + erff(x * 0.70710678118654752f)); }
;   template <int NT, int MT> DI void run(f32x4 (&acc)[NT][MT], int mb, int nb) const {
;     ...
;         } else if (n < 3072) {
;           st_bf4(uvbuf + (size_t)m * 2048 + (n - 1024), gelu_f(v[0]), gelu_f(v[1]), gelu_f(v[2]), gelu_f(v[3]));
.LBB0_1720:
	s_andn2_saveexec_b64 s[38:39], s[38:39]
	s_cbranch_execz .LBB0_1738
	v_pk_mul_f32 v[130:131], v[0:1], v[170:171]
	v_pk_mul_f32 v[142:143], v[2:3], v[170:171]
	v_and_b32_e32 v132, 0x7fffffff, v130
	v_and_b32_e32 v144, 0x7fffffff, v142
	v_and_b32_e32 v133, 0x7fffffff, v131
	v_and_b32_e32 v145, 0x7fffffff, v143
	v_pk_fma_f32 v[134:135], v[132:133], v[174:175], v[176:177]
	v_pk_fma_f32 v[146:147], v[144:145], v[174:175], v[176:177]
	v_pk_fma_f32 v[134:135], v[132:133], v[134:135], v[178:179]
	v_pk_fma_f32 v[146:147], v[144:145], v[146:147], v[178:179]
	v_pk_fma_f32 v[134:135], v[132:133], v[134:135], v[180:181]
	v_pk_fma_f32 v[146:147], v[144:145], v[146:147], v[180:181]
	v_pk_fma_f32 v[134:135], v[132:133], v[134:135], v[186:187]
	v_pk_fma_f32 v[146:147], v[144:145], v[146:147], v[186:187]
	v_pk_fma_f32 v[134:135], v[132:133], v[134:135], v[188:189]
	v_pk_fma_f32 v[146:147], v[144:145], v[146:147], v[188:189]
	v_pk_fma_f32 v[134:135], v[132:133], v[134:135], v[190:191]
	v_pk_fma_f32 v[146:147], v[144:145], v[146:147], v[190:191]
	v_pk_fma_f32 v[134:135], v[132:133], v[134:135], v[132:133]
	v_pk_fma_f32 v[146:147], v[144:145], v[146:147], v[144:145]
	v_pk_mul_f32 v[134:135], v[134:135], v[172:173]
	v_pk_mul_f32 v[146:147], v[146:147], v[172:173]
	v_pk_mul_f32 v[136:137], v[130:131], v[130:131]
	v_pk_mul_f32 v[148:149], v[142:143], v[142:143]
	v_exp_f32_e32 v134, v134
	v_exp_f32_e32 v146, v146
	v_exp_f32_e32 v135, v135
	v_exp_f32_e32 v147, v147
	v_pk_fma_f32 v[138:139], v[136:137], v[192:193], v[194:195]
	v_pk_fma_f32 v[150:151], v[148:149], v[192:193], v[194:195]
	v_pk_fma_f32 v[138:139], v[136:137], v[138:139], v[196:197]
	v_pk_fma_f32 v[150:151], v[148:149], v[150:151], v[196:197]
	v_pk_fma_f32 v[138:139], v[136:137], v[138:139], v[224:225]
	v_pk_fma_f32 v[150:151], v[148:149], v[150:151], v[224:225]
	v_pk_fma_f32 v[138:139], v[136:137], v[138:139], v[226:227]
	v_pk_fma_f32 v[150:151], v[148:149], v[150:151], v[226:227]
	v_pk_fma_f32 v[138:139], v[136:137], v[138:139], v[228:229]
	v_pk_fma_f32 v[150:151], v[148:149], v[150:151], v[228:229]
	v_pk_fma_f32 v[134:135], v[134:135], v[234:235], v[230:231]
	v_pk_fma_f32 v[146:147], v[146:147], v[234:235], v[230:231]
	v_pk_fma_f32 v[138:139], v[132:133], v[138:139], v[132:133]
	v_pk_fma_f32 v[150:151], v[144:145], v[150:151], v[144:145]
	v_pk_mul_f32 v[140:141], v[0:1], v[232:233]
	v_pk_mul_f32 v[152:153], v[2:3], v[232:233]
	v_cmp_ngt_f32_e32 vcc, 1.0, v132
	v_cmp_ngt_f32_e64 s[8:9], 1.0, v133
	v_readlane_b32 s6, v252, 33
	v_readlane_b32 s7, v252, 34
	v_cndmask_b32_e32 v138, v138, v134, vcc
	v_cndmask_b32_e64 v139, v139, v135, s[8:9]
	v_cmp_ngt_f32_e32 vcc, 1.0, v144
	v_cmp_ngt_f32_e64 s[8:9], 1.0, v145
	v_bfi_b32 v138, s37, v138, v130
	v_bfi_b32 v139, s37, v139, v131
	v_cndmask_b32_e32 v150, v150, v146, vcc
	v_cndmask_b32_e64 v151, v151, v147, s[8:9]
	v_pk_add_f32 v[138:139], v[138:139], v[230:231]
	v_bfi_b32 v150, s37, v150, v142
	v_bfi_b32 v151, s37, v151, v143
	v_pk_add_f32 v[150:151], v[150:151], v[230:231]
	v_pk_mul_f32 v[138:139], v[140:141], v[138:139]
	v_lshl_add_u64 v[0:1], s[6:7], 0, v[4:5]
	v_pk_mul_f32 v[150:151], v[152:153], v[150:151]
	v_lshl_add_u64 v[0:1], v[182:183], 1, v[0:1]
	v_cvt_pk_bf16_f32 v2, v138, v139
	v_cvt_pk_bf16_f32 v3, v150, v151
	global_store_dwordx2 v[0:1], v[2:3], off offset:-1952

; DI unsigned xb_ld(unsigned* p) { return __hip_atomic_load(p, __ATOMIC_RELAXED, __HIP_MEMORY_SCOPE_AGENT); }
; DI unsigned xb_add(unsigned* p, unsigned v) { return __hip_atomic_fetch_add(p, v, __ATOMIC_RELAXED, __HIP_MEMORY_SCOPE_AGENT); }
; #define XB_SPIN(cond, bar) do { unsigned _sp = 0; while (cond) { __builtin_amdgcn_s_sleep(1); \
;     if ((++_sp & 255u) == 0u) { if (xb_ld(&(bar)[XB_TMO])) break; if (_sp > XB_SPIN_CAP) { atomicAdd(&(bar)[XB_TMO], 1u); break; } } } } while (0)
; DI void xcd_barrier(const XcdBarrier& b) {
;     ...
;     const unsigned old = xb_add(&bar[XB_XSUB(b.x)], 1u);
;     const unsigned gen = old / nloc;
;     if (old + 1u == (gen + 1u) * nloc) {
;       __builtin_amdgcn_fence(__ATOMIC_RELEASE, "agent");
;       asm volatile("s_waitcnt vmcnt(0)" ::: "memory");
;       const unsigned og = xb_add(&bar[XB_TOP], 1u);
;       const unsigned tg = og / nx;
;       if (og + 1u == (tg + 1u) * nx) xb_add(&bar[XB_TOPGEN], 1u);
;       else XB_SPIN(xb_ld(&bar[XB_TOPGEN]) == tg, bar);
;       __builtin_amdgcn_fence(__ATOMIC_ACQUIRE, "agent");
;       xb_add(&bar[XB_XGEN(b.x)], 1u);
;       asm volatile("s_waitcnt vmcnt(0)" ::: "memory");
;     } else {
;       XB_SPIN(xb_ld(&bar[XB_XGEN(b.x)]) == gen, bar);
.LBB0_1806:
	s_or_b64 exec, exec, s[40:41]
	v_cvt_f32_u32_e32 v4, v2
	s_waitcnt vmcnt(0)
	v_readfirstlane_b32 s4, v3
	v_sub_u32_e32 v3, 0, v2
	v_rcp_iflag_f32_e32 v4, v4
	v_add_u32_e32 v5, s4, v1
	v_mul_f32_e32 v4, 0x4f7ffffe, v4
	v_cvt_u32_f32_e32 v4, v4
	v_mul_lo_u32 v1, v3, v4
	v_mul_hi_u32 v1, v4, v1
	v_add_u32_e32 v1, v4, v1
	v_mul_hi_u32 v1, v5, v1
	v_mul_lo_u32 v3, v1, v2
	v_sub_u32_e32 v3, v5, v3
	v_add_u32_e32 v4, 1, v1
	v_cmp_ge_u32_e32 vcc, v3, v2
	s_nop 1
	v_cndmask_b32_e32 v1, v1, v4, vcc
	v_sub_u32_e32 v4, v3, v2
	v_cndmask_b32_e32 v3, v3, v4, vcc
	v_add_u32_e32 v4, 1, v1
	v_cmp_ge_u32_e32 vcc, v3, v2
	v_add_u32_e32 v3, 1, v5
	s_nop 0
	v_cndmask_b32_e32 v1, v1, v4, vcc
	v_mul_lo_u32 v4, v2, v1
	v_add_u32_e32 v2, v4, v2
	v_cmp_ne_u32_e32 vcc, v3, v2
	s_and_saveexec_b64 s[4:5], vcc
	s_xor_b64 s[40:41], exec, s[4:5]
	s_cbranch_execz .LBB0_1820
	v_readlane_b32 s4, v254, 48
	v_readlane_b32 s5, v254, 49
	s_waitcnt lgkmcnt(0)
	s_nop 3
	global_load_dword v0, v183, s[4:5] sc1
	s_waitcnt vmcnt(0)
	v_cmp_eq_u32_e32 vcc, v0, v1
	s_and_saveexec_b64 s[42:43], vcc
	s_cbranch_execz .LBB0_1819
	s_mov_b32 s4, 1
	s_mov_b64 s[44:45], 0
	s_branch .LBB0_1810

; DI unsigned xb_ld(unsigned* p) { return __hip_atomic_load(p, __ATOMIC_RELAXED, __HIP_MEMORY_SCOPE_AGENT); }
; DI unsigned xb_add(unsigned* p, unsigned v) { return __hip_atomic_fetch_add(p, v, __ATOMIC_RELAXED, __HIP_MEMORY_SCOPE_AGENT); }
; #define XB_SPIN(cond, bar) do { unsigned _sp = 0; while (cond) { __builtin_amdgcn_s_sleep(1); \
;     if ((++_sp & 255u) == 0u) { if (xb_ld(&(bar)[XB_TMO])) break; if (_sp > XB_SPIN_CAP) { atomicAdd(&(bar)[XB_TMO], 1u); break; } } } } while (0)
; DI void xcd_barrier(const XcdBarrier& b) {
;     ...
;       else XB_SPIN(xb_ld(&bar[XB_TOPGEN]) == tg, bar);
;       __builtin_amdgcn_fence(__ATOMIC_ACQUIRE, "agent");
;       xb_add(&bar[XB_XGEN(b.x)], 1u);
;       asm volatile("s_waitcnt vmcnt(0)" ::: "memory");
;     } else {
;       XB_SPIN(xb_ld(&bar[XB_XGEN(b.x)]) == gen, bar);
.LBB0_1812:
	v_readlane_b32 s6, v254, 48
	v_readlane_b32 s7, v254, 49
	s_add_i32 s4, s4, 1
	s_mov_b64 s[50:51], -1
	s_nop 2
	global_load_dword v0, v183, s[6:7] sc1
	s_waitcnt vmcnt(0)
	v_cmp_ne_u32_e32 vcc, v0, v1
	s_orn2_b64 s[48:49], vcc, exec
	s_branch .LBB0_1809
